# on top of v32: compute intervals C2/C4/C6 made pure MFMA runs, their gap SALU (m0 / address setup) moved behind the ds_reads of the following load interval
# speedup vs baseline: 1.0158x; 1.0158x over previous
; #define PG8_STAGE(bufoff, gbase) do { _Pragma("unroll") for (int _i = 0; _i < 2; ++_i) \
;         __builtin_amdgcn_global_load_lds((const unsigned*)((const char*)(gbase) + voff[_i]), (LAS unsigned*)(lds + (bufoff) + ldsw + _i * 8192), 16, 0, 0); } while (0)
; #define PG8_LDA(dst, b, h) do { _Pragma("unroll") for (int m = 0; m < 4; ++m) _Pragma("unroll") for (int k = 0; k < 2; ++k) dst[m][k] = *(const LAS bf16x8*)(lds + PG8_SA(b, h) + aoff + m * 2048 + k * 1024); } while (0)
; #define PG8_LDB(dst, b, h) do { _Pragma("unroll") for (int n = 0; n < 2; ++n) _Pragma("unroll") for (int k = 0; k < 2; ++k) dst[n][k] = *(const LAS bf16x8*)(lds + PG8_SB(b, h) + boff + n * 2048 + k * 1024); } while (0)
; #define PG8_MMA(ai, bj, At, Bt) do { __builtin_amdgcn_s_setprio(1); _Pragma("unroll") for (int m = 0; m < 4; ++m) _Pragma("unroll") for (int n = 0; n < 2; ++n) _Pragma("unroll") for (int k = 0; k < 2; ++k) \
;         acc[ai][bj][m][n] = __builtin_amdgcn_mfma_f32_16x16x32_bf16(Bt[n][k], At[m][k], acc[ai][bj][m][n], 0, 0, 0); __builtin_amdgcn_s_setprio(0); } while (0)
; #define PG8_WAIT_V(n) asm volatile("s_waitcnt vmcnt(" #n ")" ::: "memory")
; #define PG8_WAIT_L(n) asm volatile("s_waitcnt lgkmcnt(" #n ")" ::: "memory")
; #define PG8_BAR __builtin_amdgcn_s_barrier()
; #define PG8_SCHED __builtin_amdgcn_sched_barrier(0)
; template <class Epi>
; DI void gemm_phase(LAS unsigned char* lds, const Gemm g, const StaticOrder& S, const Epi& E) {
;     ...
;         for (int t = 0; t < nt; t += 2) {
;             const bool last = (t == nt - 2);
;             const char* a1 = cA + (size_t)(t + 1) * kstep;
;             const char* a2 = last ? nA : cA + (size_t)(t + 2) * kstep; const char* b2 = last ? nB : cB + (size_t)(t + 2) * kstep;
;             const char* a3 = a2 + kstep; const char* b3 = b2 + kstep;
;             PG8_LDB(B0, 0, 0); PG8_SCHED; PG8_LDA(At, 0, 0); PG8_STAGE(PG8_SA(1, 1), a1 + hstep);
;             PG8_WAIT_L(8); PG8_BAR; PG8_WAIT_L(0); PG8_MMA(0, 0, At, B0); PG8_BAR; PG8_SCHED;
;             PG8_LDB(B1, 0, 1); PG8_STAGE(PG8_SB(0, 0), b2);
;             PG8_BAR; PG8_WAIT_L(0); PG8_MMA(0, 1, At, B1); PG8_BAR;
;             PG8_LDA(At, 0, 1); PG8_STAGE(PG8_SA(0, 0), a2);
;             PG8_BAR; PG8_WAIT_L(0); PG8_MMA(1, 0, At, B0); PG8_BAR; PG8_SCHED;
;             PG8_STAGE(PG8_SB(0, 1), b2 + hstep);
;             PG8_WAIT_V(6); PG8_BAR; PG8_MMA(1, 1, At, B1); PG8_BAR;
.LBB0_37:
	ds_read_b128 v[138:141], v135
	ds_read_b128 v[142:145], v135 offset:1024
	ds_read_b128 v[146:149], v135 offset:2048
	ds_read_b128 v[150:153], v135 offset:3072
	ds_read_b128 v[186:189], v137
	ds_read_b128 v[190:193], v137 offset:1024
	ds_read_b128 v[194:197], v137 offset:2048
	ds_read_b128 v[198:201], v137 offset:3072
	ds_read_b128 v[202:205], v137 offset:4096
	ds_read_b128 v[206:209], v137 offset:5120
	ds_read_b128 v[210:213], v137 offset:6144
	ds_read_b128 v[214:217], v137 offset:7168
	s_add_u32 s20, s18, 0xfff80080
	s_addc_u32 s21, s19, -1
	s_add_i32 s39, 0, 0x10000
	s_cmp_eq_u32 s38, 28
	s_cselect_b32 s23, s4, s21
	s_cselect_b32 s22, s5, s20
	s_cselect_b32 s21, s9, s37
	s_cselect_b32 s20, s11, s33
	s_add_i32 m0, s28, 0xc000
	s_nop 0
	global_load_lds_dwordx4 v130, s[18:19]
	s_add_i32 m0, s28, 0xe000
	s_nop 0
	global_load_lds_dwordx4 v132, s[18:19]
	s_waitcnt lgkmcnt(8)
	s_setprio 1
	s_barrier
	s_waitcnt lgkmcnt(0)
	v_mfma_f32_16x16x32_bf16 v[124:127], v[138:141], v[186:189], v[124:127]
	v_mfma_f32_16x16x32_bf16 v[120:123], v[146:149], v[186:189], v[120:123]
	v_mfma_f32_16x16x32_bf16 v[108:111], v[138:141], v[194:197], v[108:111]
	v_mfma_f32_16x16x32_bf16 v[104:107], v[146:149], v[194:197], v[104:107]
	v_mfma_f32_16x16x32_bf16 v[92:95], v[138:141], v[202:205], v[92:95]
	v_mfma_f32_16x16x32_bf16 v[88:91], v[146:149], v[202:205], v[88:91]
	v_mfma_f32_16x16x32_bf16 v[76:79], v[138:141], v[210:213], v[76:79]
	v_mfma_f32_16x16x32_bf16 v[72:75], v[146:149], v[210:213], v[72:75]
	v_mfma_f32_16x16x32_bf16 v[124:127], v[142:145], v[190:193], v[124:127]
	v_mfma_f32_16x16x32_bf16 v[120:123], v[150:153], v[190:193], v[120:123]
	v_mfma_f32_16x16x32_bf16 v[108:111], v[142:145], v[198:201], v[108:111]
	v_mfma_f32_16x16x32_bf16 v[104:107], v[150:153], v[198:201], v[104:107]
	v_mfma_f32_16x16x32_bf16 v[92:95], v[142:145], v[206:209], v[92:95]
	v_mfma_f32_16x16x32_bf16 v[88:91], v[150:153], v[206:209], v[88:91]
	v_mfma_f32_16x16x32_bf16 v[76:79], v[142:145], v[214:217], v[76:79]
	s_setprio 0
	v_mfma_f32_16x16x32_bf16 v[72:75], v[150:153], v[214:217], v[72:75]
	s_barrier
	ds_read_b128 v[226:229], v135 offset:16384
	ds_read_b128 v[230:233], v135 offset:17408
	ds_read_b128 v[234:237], v135 offset:18432
	ds_read_b128 v[238:241], v135 offset:19456
	s_add_i32 s42, 0, 0x14000
	s_add_i32 s39, s39, s27
	s_mov_b32 m0, s39
	s_nop 0
	global_load_lds_dwordx4 v158, s[20:21]
	s_add_i32 m0, s39, 0x2000
	s_nop 0
	global_load_lds_dwordx4 v128, s[20:21]
	s_waitcnt lgkmcnt(0)
	s_setprio 1
	s_barrier
	v_mfma_f32_16x16x32_bf16 v[116:119], v[226:229], v[186:189], v[116:119]
	v_mfma_f32_16x16x32_bf16 v[112:115], v[234:237], v[186:189], v[112:115]
	v_mfma_f32_16x16x32_bf16 v[100:103], v[226:229], v[194:197], v[100:103]
	v_mfma_f32_16x16x32_bf16 v[96:99], v[234:237], v[194:197], v[96:99]
	v_mfma_f32_16x16x32_bf16 v[84:87], v[226:229], v[202:205], v[84:87]
	v_mfma_f32_16x16x32_bf16 v[80:83], v[234:237], v[202:205], v[80:83]
	v_mfma_f32_16x16x32_bf16 v[68:71], v[226:229], v[210:213], v[68:71]
	v_mfma_f32_16x16x32_bf16 v[64:67], v[234:237], v[210:213], v[64:67]
	v_mfma_f32_16x16x32_bf16 v[116:119], v[230:233], v[190:193], v[116:119]
	v_mfma_f32_16x16x32_bf16 v[112:115], v[238:241], v[190:193], v[112:115]
	v_mfma_f32_16x16x32_bf16 v[100:103], v[230:233], v[198:201], v[100:103]
	v_mfma_f32_16x16x32_bf16 v[96:99], v[238:241], v[198:201], v[96:99]
	v_mfma_f32_16x16x32_bf16 v[84:87], v[230:233], v[206:209], v[84:87]
	v_mfma_f32_16x16x32_bf16 v[80:83], v[238:241], v[206:209], v[80:83]
	v_mfma_f32_16x16x32_bf16 v[68:71], v[230:233], v[214:217], v[68:71]
	s_setprio 0
	v_mfma_f32_16x16x32_bf16 v[64:67], v[238:241], v[214:217], v[64:67]
	s_barrier
	ds_read_b128 v[186:189], v137 offset:16384
	ds_read_b128 v[190:193], v137 offset:17408
	ds_read_b128 v[194:197], v137 offset:18432
	ds_read_b128 v[198:201], v137 offset:19456
	ds_read_b128 v[202:205], v137 offset:20480
	ds_read_b128 v[206:209], v137 offset:21504
	ds_read_b128 v[210:213], v137 offset:22528
	ds_read_b128 v[214:217], v137 offset:23552
	s_mov_b32 m0, s28
	s_nop 0
	global_load_lds_dwordx4 v158, s[22:23]
	s_mov_b64 s[100:101], s[22:23]
	s_mov_b32 m0, s29
	s_nop 0
	global_load_lds_dwordx4 v128, s[22:23]
	s_waitcnt lgkmcnt(0)
	s_setprio 1
	s_barrier
	v_mfma_f32_16x16x32_bf16 v[60:63], v[138:141], v[186:189], v[60:63]
	v_mfma_f32_16x16x32_bf16 v[56:59], v[146:149], v[186:189], v[56:59]
	v_mfma_f32_16x16x32_bf16 v[44:47], v[138:141], v[194:197], v[44:47]
	v_mfma_f32_16x16x32_bf16 v[40:43], v[146:149], v[194:197], v[40:43]
	v_mfma_f32_16x16x32_bf16 v[28:31], v[138:141], v[202:205], v[28:31]
	v_mfma_f32_16x16x32_bf16 v[24:27], v[146:149], v[202:205], v[24:27]
	v_mfma_f32_16x16x32_bf16 v[12:15], v[138:141], v[210:213], v[12:15]
	v_mfma_f32_16x16x32_bf16 v[8:11], v[146:149], v[210:213], v[8:11]
	v_mfma_f32_16x16x32_bf16 v[60:63], v[142:145], v[190:193], v[60:63]
	v_mfma_f32_16x16x32_bf16 v[56:59], v[150:153], v[190:193], v[56:59]
	v_mfma_f32_16x16x32_bf16 v[44:47], v[142:145], v[198:201], v[44:47]
	v_mfma_f32_16x16x32_bf16 v[40:43], v[150:153], v[198:201], v[40:43]
	v_mfma_f32_16x16x32_bf16 v[28:31], v[142:145], v[206:209], v[28:31]
	v_mfma_f32_16x16x32_bf16 v[24:27], v[150:153], v[206:209], v[24:27]
	v_mfma_f32_16x16x32_bf16 v[12:15], v[142:145], v[214:217], v[12:15]
	s_setprio 0
	v_mfma_f32_16x16x32_bf16 v[8:11], v[150:153], v[214:217], v[8:11]
	s_barrier
	s_add_u32 s40, s20, 0x80000
	s_addc_u32 s41, s21, 0
	s_add_i32 s39, s42, s27
	s_mov_b32 m0, s39
	s_nop 0
	global_load_lds_dwordx4 v158, s[40:41]
	s_add_i32 m0, s39, 0x2000
	s_nop 0
	global_load_lds_dwordx4 v128, s[40:41]
	s_waitcnt vmcnt(6)
	s_setprio 1
	s_barrier
; #define PG8_STAGE(bufoff, gbase) do { _Pragma("unroll") for (int _i = 0; _i < 2; ++_i) \
;         __builtin_amdgcn_global_load_lds((const unsigned*)((const char*)(gbase) + voff[_i]), (LAS unsigned*)(lds + (bufoff) + ldsw + _i * 8192), 16, 0, 0); } while (0)
; #define PG8_LDA(dst, b, h) do { _Pragma("unroll") for (int m = 0; m < 4; ++m) _Pragma("unroll") for (int k = 0; k < 2; ++k) dst[m][k] = *(const LAS bf16x8*)(lds + PG8_SA(b, h) + aoff + m * 2048 + k * 1024); } while (0)
; #define PG8_LDB(dst, b, h) do { _Pragma("unroll") for (int n = 0; n < 2; ++n) _Pragma("unroll") for (int k = 0; k < 2; ++k) dst[n][k] = *(const LAS bf16x8*)(lds + PG8_SB(b, h) + boff + n * 2048 + k * 1024); } while (0)
; #define PG8_MMA(ai, bj, At, Bt) do { __builtin_amdgcn_s_setprio(1); _Pragma("unroll") for (int m = 0; m < 4; ++m) _Pragma("unroll") for (int n = 0; n < 2; ++n) _Pragma("unroll") for (int k = 0; k < 2; ++k) \
;         acc[ai][bj][m][n] = __builtin_amdgcn_mfma_f32_16x16x32_bf16(Bt[n][k], At[m][k], acc[ai][bj][m][n], 0, 0, 0); __builtin_amdgcn_s_setprio(0); } while (0)
; #define PG8_WAIT_V(n) asm volatile("s_waitcnt vmcnt(" #n ")" ::: "memory")
; #define PG8_WAIT_L(n) asm volatile("s_waitcnt lgkmcnt(" #n ")" ::: "memory")
; #define PG8_BAR __builtin_amdgcn_s_barrier()
; #define PG8_SCHED __builtin_amdgcn_sched_barrier(0)
; template <class Epi>
; DI void gemm_phase(LAS unsigned char* lds, const Gemm g, const StaticOrder& S, const Epi& E) {
;     ...
;             PG8_STAGE(PG8_SB(0, 1), b2 + hstep);
;             PG8_WAIT_V(6); PG8_BAR; PG8_MMA(1, 1, At, B1); PG8_BAR;
;             PG8_LDB(B0, 1, 0); PG8_SCHED; PG8_LDA(At, 1, 0); PG8_STAGE(PG8_SA(0, 1), a2 + hstep);
;             PG8_WAIT_L(8); PG8_BAR; PG8_WAIT_L(0); PG8_MMA(0, 0, At, B0); PG8_BAR; PG8_SCHED;
;             PG8_LDB(B1, 1, 1); PG8_STAGE(PG8_SB(1, 0), b3);
;             PG8_BAR; PG8_WAIT_L(0); PG8_MMA(0, 1, At, B1); PG8_BAR;
;             PG8_LDA(At, 1, 1); PG8_STAGE(PG8_SA(1, 0), a3);
	v_mfma_f32_16x16x32_bf16 v[52:55], v[226:229], v[186:189], v[52:55]
	v_mfma_f32_16x16x32_bf16 v[48:51], v[234:237], v[186:189], v[48:51]
	v_mfma_f32_16x16x32_bf16 v[36:39], v[226:229], v[194:197], v[36:39]
	v_mfma_f32_16x16x32_bf16 v[32:35], v[234:237], v[194:197], v[32:35]
	v_mfma_f32_16x16x32_bf16 v[20:23], v[226:229], v[202:205], v[20:23]
	v_mfma_f32_16x16x32_bf16 v[16:19], v[234:237], v[202:205], v[16:19]
	v_mfma_f32_16x16x32_bf16 v[4:7], v[226:229], v[210:213], v[4:7]
	v_mfma_f32_16x16x32_bf16 v[0:3], v[234:237], v[210:213], v[0:3]
	v_mfma_f32_16x16x32_bf16 v[52:55], v[230:233], v[190:193], v[52:55]
	v_mfma_f32_16x16x32_bf16 v[48:51], v[238:241], v[190:193], v[48:51]
	v_mfma_f32_16x16x32_bf16 v[36:39], v[230:233], v[198:201], v[36:39]
	v_mfma_f32_16x16x32_bf16 v[32:35], v[238:241], v[198:201], v[32:35]
	v_mfma_f32_16x16x32_bf16 v[20:23], v[230:233], v[206:209], v[20:23]
	v_mfma_f32_16x16x32_bf16 v[16:19], v[238:241], v[206:209], v[16:19]
	v_mfma_f32_16x16x32_bf16 v[4:7], v[230:233], v[214:217], v[4:7]
	s_setprio 0
	v_mfma_f32_16x16x32_bf16 v[0:3], v[238:241], v[214:217], v[0:3]
	s_barrier
	ds_read_b128 v[138:141], v135 offset:32768
	ds_read_b128 v[142:145], v135 offset:33792
	ds_read_b128 v[146:149], v135 offset:34816
	ds_read_b128 v[150:153], v135 offset:35840
	ds_read_b128 v[186:189], v137 offset:32768
	ds_read_b128 v[190:193], v137 offset:33792
	ds_read_b128 v[194:197], v137 offset:34816
	ds_read_b128 v[198:201], v137 offset:35840
	ds_read_b128 v[202:205], v137 offset:36864
	ds_read_b128 v[206:209], v137 offset:37888
	ds_read_b128 v[210:213], v137 offset:38912
	ds_read_b128 v[214:217], v137 offset:39936
	s_add_i32 s39, 0, 0x18000
	s_add_u32 s22, s22, 0x80000
	s_addc_u32 s23, s23, 0
	s_mov_b32 m0, s30
	s_nop 0
	global_load_lds_dwordx4 v158, s[22:23]
	s_mov_b32 m0, s31
	s_nop 0
	global_load_lds_dwordx4 v128, s[22:23]
	s_waitcnt lgkmcnt(8)
	s_setprio 1
	s_barrier
	s_waitcnt lgkmcnt(0)
	v_mfma_f32_16x16x32_bf16 v[124:127], v[138:141], v[186:189], v[124:127]
	v_mfma_f32_16x16x32_bf16 v[120:123], v[146:149], v[186:189], v[120:123]
	v_mfma_f32_16x16x32_bf16 v[108:111], v[138:141], v[194:197], v[108:111]
	v_mfma_f32_16x16x32_bf16 v[104:107], v[146:149], v[194:197], v[104:107]
	v_mfma_f32_16x16x32_bf16 v[92:95], v[138:141], v[202:205], v[92:95]
	v_mfma_f32_16x16x32_bf16 v[88:91], v[146:149], v[202:205], v[88:91]
	v_mfma_f32_16x16x32_bf16 v[76:79], v[138:141], v[210:213], v[76:79]
	v_mfma_f32_16x16x32_bf16 v[72:75], v[146:149], v[210:213], v[72:75]
	v_mfma_f32_16x16x32_bf16 v[124:127], v[142:145], v[190:193], v[124:127]
	v_mfma_f32_16x16x32_bf16 v[120:123], v[150:153], v[190:193], v[120:123]
	v_mfma_f32_16x16x32_bf16 v[108:111], v[142:145], v[198:201], v[108:111]
	v_mfma_f32_16x16x32_bf16 v[104:107], v[150:153], v[198:201], v[104:107]
	v_mfma_f32_16x16x32_bf16 v[92:95], v[142:145], v[206:209], v[92:95]
	v_mfma_f32_16x16x32_bf16 v[88:91], v[150:153], v[206:209], v[88:91]
	v_mfma_f32_16x16x32_bf16 v[76:79], v[142:145], v[214:217], v[76:79]
	s_setprio 0
	v_mfma_f32_16x16x32_bf16 v[72:75], v[150:153], v[214:217], v[72:75]
	s_barrier
	ds_read_b128 v[226:229], v135 offset:49152
	ds_read_b128 v[230:233], v135 offset:50176
	ds_read_b128 v[234:237], v135 offset:51200
	ds_read_b128 v[238:241], v135 offset:52224
	s_add_i32 s22, 0, 0x1c000
	s_add_i32 s23, s39, s27
	s_add_i32 m0, s23, 0xffffff80
	s_nop 0
	global_load_lds_dwordx4 v158, s[20:21] offset:128
	s_add_i32 m0, s23, 0x1f80
	s_nop 0
	global_load_lds_dwordx4 v128, s[20:21] offset:128
	s_waitcnt lgkmcnt(0)
	s_setprio 1
	s_barrier
	v_mfma_f32_16x16x32_bf16 v[116:119], v[226:229], v[186:189], v[116:119]
	v_mfma_f32_16x16x32_bf16 v[112:115], v[234:237], v[186:189], v[112:115]
	v_mfma_f32_16x16x32_bf16 v[100:103], v[226:229], v[194:197], v[100:103]
	v_mfma_f32_16x16x32_bf16 v[96:99], v[234:237], v[194:197], v[96:99]
	v_mfma_f32_16x16x32_bf16 v[84:87], v[226:229], v[202:205], v[84:87]
	v_mfma_f32_16x16x32_bf16 v[80:83], v[234:237], v[202:205], v[80:83]
	v_mfma_f32_16x16x32_bf16 v[68:71], v[226:229], v[210:213], v[68:71]
	v_mfma_f32_16x16x32_bf16 v[64:67], v[234:237], v[210:213], v[64:67]
	v_mfma_f32_16x16x32_bf16 v[116:119], v[230:233], v[190:193], v[116:119]
	v_mfma_f32_16x16x32_bf16 v[112:115], v[238:241], v[190:193], v[112:115]
	v_mfma_f32_16x16x32_bf16 v[100:103], v[230:233], v[198:201], v[100:103]
	v_mfma_f32_16x16x32_bf16 v[96:99], v[238:241], v[198:201], v[96:99]
	v_mfma_f32_16x16x32_bf16 v[84:87], v[230:233], v[206:209], v[84:87]
	v_mfma_f32_16x16x32_bf16 v[80:83], v[238:241], v[206:209], v[80:83]
	v_mfma_f32_16x16x32_bf16 v[68:71], v[230:233], v[214:217], v[68:71]
	s_setprio 0
	v_mfma_f32_16x16x32_bf16 v[64:67], v[238:241], v[214:217], v[64:67]
	s_barrier
	ds_read_b128 v[186:189], v137 offset:49152
	ds_read_b128 v[190:193], v137 offset:50176
	ds_read_b128 v[194:197], v137 offset:51200
	ds_read_b128 v[198:201], v137 offset:52224
	ds_read_b128 v[202:205], v137 offset:53248
	ds_read_b128 v[206:209], v137 offset:54272
	ds_read_b128 v[210:213], v137 offset:55296
	ds_read_b128 v[214:217], v137 offset:56320
	s_add_i32 m0, s34, 0xffffff80
	s_nop 0
	global_load_lds_dwordx4 v158, s[100:101] offset:128
	s_add_i32 m0, s35, 0xffffff80
	s_nop 0
	global_load_lds_dwordx4 v128, s[100:101] offset:128
	s_waitcnt lgkmcnt(0)
	s_setprio 1
	s_barrier
; #define PG8_STAGE(bufoff, gbase) do { _Pragma("unroll") for (int _i = 0; _i < 2; ++_i) \
;         __builtin_amdgcn_global_load_lds((const unsigned*)((const char*)(gbase) + voff[_i]), (LAS unsigned*)(lds + (bufoff) + ldsw + _i * 8192), 16, 0, 0); } while (0)
; #define PG8_MMA(ai, bj, At, Bt) do { __builtin_amdgcn_s_setprio(1); _Pragma("unroll") for (int m = 0; m < 4; ++m) _Pragma("unroll") for (int n = 0; n < 2; ++n) _Pragma("unroll") for (int k = 0; k < 2; ++k) \
;         acc[ai][bj][m][n] = __builtin_amdgcn_mfma_f32_16x16x32_bf16(Bt[n][k], At[m][k], acc[ai][bj][m][n], 0, 0, 0); __builtin_amdgcn_s_setprio(0); } while (0)
; #define PG8_WAIT_V(n) asm volatile("s_waitcnt vmcnt(" #n ")" ::: "memory")
; #define PG8_WAIT_L(n) asm volatile("s_waitcnt lgkmcnt(" #n ")" ::: "memory")
; #define PG8_BAR __builtin_amdgcn_s_barrier()
; #define PG8_SCHED __builtin_amdgcn_sched_barrier(0)
; template <class Epi>
; DI void gemm_phase(LAS unsigned char* lds, const Gemm g, const StaticOrder& S, const Epi& E) {
;     ...
;             PG8_BAR; PG8_WAIT_L(0); PG8_MMA(1, 0, At, B0); PG8_BAR; PG8_SCHED;
;             PG8_STAGE(PG8_SB(1, 1), b3 + hstep);
;             PG8_WAIT_V(6); PG8_BAR; PG8_MMA(1, 1, At, B1); PG8_BAR;
;     DI void operator()(const f32x4 (&acc)[2][2][4][2], const Unit& u, int wr, int wc, int fr, int fq) const {
;         const int row0 = u.pm * BM + wr * 64 + fr, col0 = u.pn * HALF + wc * 32 + 8 * fq;
; #pragma unroll
;         for (int ai = 0; ai < 2; ++ai)
; #pragma unroll
;             for (int m = 0; m < 4; ++m) { float hv[8];
; #pragma unroll
;                 for (int n = 0; n < 2; ++n)
; #pragma unroll
;                     for (int e = 0; e < 4; ++e) { const float gt = acc[ai][0][m][n][e], up = acc[ai][1][m][n][e];
;                         hv[n * 4 + e] = gt * __builtin_amdgcn_rcpf(1.f + __builtin_amdgcn_exp2f(-1.4426950408889634f * gt)) * up; }
;                 *(u32x4*)(H + (size_t)(row0 + ai * HALF + m * 16) * DFF + col0) = (u32x4){pk(hv[0], hv[1]), pk(hv[2], hv[3]), pk(hv[4], hv[5]), pk(hv[6], hv[7])}; }
	v_mfma_f32_16x16x32_bf16 v[60:63], v[138:141], v[186:189], v[60:63]
	v_mfma_f32_16x16x32_bf16 v[56:59], v[146:149], v[186:189], v[56:59]
	v_mfma_f32_16x16x32_bf16 v[44:47], v[138:141], v[194:197], v[44:47]
	v_mfma_f32_16x16x32_bf16 v[40:43], v[146:149], v[194:197], v[40:43]
	v_mfma_f32_16x16x32_bf16 v[28:31], v[138:141], v[202:205], v[28:31]
	v_mfma_f32_16x16x32_bf16 v[24:27], v[146:149], v[202:205], v[24:27]
	v_mfma_f32_16x16x32_bf16 v[12:15], v[138:141], v[210:213], v[12:15]
	v_mfma_f32_16x16x32_bf16 v[8:11], v[146:149], v[210:213], v[8:11]
	v_mfma_f32_16x16x32_bf16 v[60:63], v[142:145], v[190:193], v[60:63]
	v_mfma_f32_16x16x32_bf16 v[56:59], v[150:153], v[190:193], v[56:59]
	v_mfma_f32_16x16x32_bf16 v[44:47], v[142:145], v[198:201], v[44:47]
	v_mfma_f32_16x16x32_bf16 v[40:43], v[150:153], v[198:201], v[40:43]
	v_mfma_f32_16x16x32_bf16 v[28:31], v[142:145], v[206:209], v[28:31]
	v_mfma_f32_16x16x32_bf16 v[24:27], v[150:153], v[206:209], v[24:27]
	v_mfma_f32_16x16x32_bf16 v[12:15], v[142:145], v[214:217], v[12:15]
	s_setprio 0
	v_mfma_f32_16x16x32_bf16 v[8:11], v[150:153], v[214:217], v[8:11]
	s_barrier
	s_add_u32 s20, s20, 0x80080
	s_addc_u32 s21, s21, 0
	s_add_i32 s22, s22, s27
	s_mov_b32 m0, s22
	s_nop 0
	global_load_lds_dwordx4 v158, s[20:21]
	s_add_i32 m0, s22, 0x2000
	s_nop 0
	global_load_lds_dwordx4 v128, s[20:21]
	s_waitcnt vmcnt(6)
	s_setprio 1
	s_barrier
	v_mfma_f32_16x16x32_bf16 v[52:55], v[226:229], v[186:189], v[52:55]
	v_mfma_f32_16x16x32_bf16 v[48:51], v[234:237], v[186:189], v[48:51]
	v_mfma_f32_16x16x32_bf16 v[36:39], v[226:229], v[194:197], v[36:39]
	v_mfma_f32_16x16x32_bf16 v[32:35], v[234:237], v[194:197], v[32:35]
	v_mfma_f32_16x16x32_bf16 v[20:23], v[226:229], v[202:205], v[20:23]
	v_mfma_f32_16x16x32_bf16 v[16:19], v[234:237], v[202:205], v[16:19]
	v_mfma_f32_16x16x32_bf16 v[4:7], v[226:229], v[210:213], v[4:7]
	v_mfma_f32_16x16x32_bf16 v[0:3], v[234:237], v[210:213], v[0:3]
	v_mfma_f32_16x16x32_bf16 v[52:55], v[230:233], v[190:193], v[52:55]
	s_add_i32 s38, s38, 2
	v_mfma_f32_16x16x32_bf16 v[48:51], v[238:241], v[190:193], v[48:51]
	s_add_u32 s18, s18, 0x100
	v_mfma_f32_16x16x32_bf16 v[36:39], v[230:233], v[198:201], v[36:39]
	s_addc_u32 s19, s19, 0
	v_mfma_f32_16x16x32_bf16 v[32:35], v[238:241], v[198:201], v[32:35]
	s_add_u32 s33, s33, 0x100
	v_mfma_f32_16x16x32_bf16 v[20:23], v[230:233], v[206:209], v[20:23]
	s_addc_u32 s37, s37, 0
	v_mfma_f32_16x16x32_bf16 v[16:19], v[238:241], v[206:209], v[16:19]
	s_cmp_gt_u32 s38, 29
	v_mfma_f32_16x16x32_bf16 v[4:7], v[230:233], v[214:217], v[4:7]
	s_setprio 0
	v_mfma_f32_16x16x32_bf16 v[0:3], v[238:241], v[214:217], v[0:3]
	s_barrier
	s_cbranch_scc0 .LBB0_37
	v_mul_f32_e32 v139, 0xbfb8aa3b, v124
	v_exp_f32_e32 v139, v139
	v_lshl_or_b32 v140, s2, 7, v136
	v_lshl_add_u32 v138, s3, 8, v134
	v_ashrrev_i32_e32 v141, 31, v140
	v_add_f32_e32 v139, 1.0, v139
	v_rcp_f32_e32 v142, v139
	v_mul_f32_e32 v139, 0xbfb8aa3b, v125
	v_exp_f32_e32 v139, v139
	s_movk_i32 s4, 0x2c00
	s_and_b64 vcc, exec, s[6:7]
	s_mov_b64 s[20:21], s[16:17]
	v_add_f32_e32 v139, 1.0, v139
	v_rcp_f32_e32 v143, v139
	v_mul_f32_e32 v139, 0xbfb8aa3b, v126
	v_exp_f32_e32 v139, v139
	s_mov_b64 s[18:19], s[14:15]
	v_pk_mul_f32 v[124:125], v[124:125], v[142:143]
	v_add_f32_e32 v139, 1.0, v139
	v_rcp_f32_e32 v144, v139
	v_mul_f32_e32 v139, 0xbfb8aa3b, v127
	v_exp_f32_e32 v139, v139
	v_pk_mul_f32 v[116:117], v[124:125], v[116:117]
	v_add_f32_e32 v139, 1.0, v139
	v_rcp_f32_e32 v145, v139
	v_mul_f32_e32 v139, 0xbfb8aa3b, v120
	v_exp_f32_e32 v139, v139
	v_cvt_pk_bf16_f32 v116, v116, v117
	v_pk_mul_f32 v[124:125], v[126:127], v[144:145]
	v_add_f32_e32 v139, 1.0, v139
	v_rcp_f32_e32 v146, v139
	v_mul_f32_e32 v139, 0xbfb8aa3b, v121
	v_exp_f32_e32 v139, v139
	v_pk_mul_f32 v[118:119], v[124:125], v[118:119]
	v_add_f32_e32 v139, 1.0, v139
	v_rcp_f32_e32 v147, v139
	v_mul_f32_e32 v139, 0xbfb8aa3b, v122
	v_exp_f32_e32 v139, v139
	v_cvt_pk_bf16_f32 v117, v118, v119
	v_pk_mul_f32 v[118:119], v[120:121], v[146:147]
	v_add_f32_e32 v139, 1.0, v139
	v_rcp_f32_e32 v148, v139
	v_mul_f32_e32 v139, 0xbfb8aa3b, v123
	v_exp_f32_e32 v139, v139
	v_pk_mul_f32 v[112:113], v[118:119], v[112:113]
	v_add_f32_e32 v139, 1.0, v139
	v_rcp_f32_e32 v149, v139
	v_cvt_pk_bf16_f32 v118, v112, v113
	v_pk_mul_f32 v[112:113], v[122:123], v[148:149]
	s_nop 0
	v_pk_mul_f32 v[112:113], v[112:113], v[114:115]
	v_lshlrev_b64 v[114:115], 1, v[140:141]
	v_cvt_pk_bf16_f32 v119, v112, v113
	v_mov_b64_e32 v[112:113], s[54:55]
	v_mad_i64_i32 v[120:121], s[2:3], v138, s4, v[112:113]
	v_lshl_add_u64 v[120:121], v[120:121], 0, v[114:115]
	global_store_dwordx4 v[120:121], v[116:119], off
	v_mul_f32_e32 v120, 0xbfb8aa3b, v104
	v_mul_f32_e32 v121, 0xbfb8aa3b, v105
	v_mul_f32_e32 v116, 0xbfb8aa3b, v108
	v_mul_f32_e32 v117, 0xbfb8aa3b, v109
	v_exp_f32_e32 v116, v116
	v_exp_f32_e32 v117, v117
	v_mul_f32_e32 v118, 0xbfb8aa3b, v110
	v_mul_f32_e32 v119, 0xbfb8aa3b, v111
	v_exp_f32_e32 v118, v118
	v_exp_f32_e32 v119, v119
	v_exp_f32_e32 v120, v120
	v_exp_f32_e32 v121, v121
	v_add_f32_e32 v116, 1.0, v116
	v_add_f32_e32 v117, 1.0, v117
	v_mul_f32_e32 v122, 0xbfb8aa3b, v106
	v_mul_f32_e32 v123, 0xbfb8aa3b, v107
	v_rcp_f32_e32 v116, v116
	v_rcp_f32_e32 v117, v117
	v_add_f32_e32 v118, 1.0, v118
	v_add_f32_e32 v119, 1.0, v119
	v_exp_f32_e32 v122, v122
	v_exp_f32_e32 v123, v123
	v_rcp_f32_e32 v118, v118
	v_rcp_f32_e32 v119, v119
	v_add_f32_e32 v120, 1.0, v120
	v_add_f32_e32 v121, 1.0, v121
	v_rcp_f32_e32 v120, v120
	v_rcp_f32_e32 v121, v121
	v_add_f32_e32 v122, 1.0, v122
	v_add_f32_e32 v123, 1.0, v123
	v_pk_mul_f32 v[108:109], v[108:109], v[116:117]
	v_rcp_f32_e32 v122, v122
;     DI void operator()(const f32x4 (&acc)[2][2][4][2], const Unit& u, int wr, int wc, int fr, int fq) const {
;     ...
;             for (int m = 0; m < 4; ++m) { float hv[8];
; #pragma unroll
;                 for (int n = 0; n < 2; ++n)
; #pragma unroll
;                     for (int e = 0; e < 4; ++e) { const float gt = acc[ai][0][m][n][e], up = acc[ai][1][m][n][e];
;                         hv[n * 4 + e] = gt * __builtin_amdgcn_rcpf(1.f + __builtin_amdgcn_exp2f(-1.4426950408889634f * gt)) * up; }
;                 *(u32x4*)(H + (size_t)(row0 + ai * HALF + m * 16) * DFF + col0) = (u32x4){pk(hv[0], hv[1]), pk(hv[2], hv[3]), pk(hv[4], hv[5]), pk(hv[6], hv[7])}; }
	v_rcp_f32_e32 v123, v123
	v_pk_mul_f32 v[100:101], v[108:109], v[100:101]
	v_pk_mul_f32 v[108:109], v[110:111], v[118:119]
	v_cvt_pk_bf16_f32 v100, v100, v101
	v_pk_mul_f32 v[102:103], v[108:109], v[102:103]
	s_nop 0
	v_cvt_pk_bf16_f32 v101, v102, v103
	v_pk_mul_f32 v[102:103], v[104:105], v[120:121]
	s_nop 0
	v_pk_mul_f32 v[96:97], v[102:103], v[96:97]
	s_nop 0
	v_cvt_pk_bf16_f32 v102, v96, v97
	v_pk_mul_f32 v[96:97], v[106:107], v[122:123]
	s_nop 0
	v_pk_mul_f32 v[96:97], v[96:97], v[98:99]
	v_mul_f32_e32 v98, 0xbfb8aa3b, v94
	v_cvt_pk_bf16_f32 v103, v96, v97
	v_or_b32_e32 v96, 16, v138
	v_mad_i64_i32 v[96:97], s[2:3], v96, s4, v[112:113]
	v_lshl_add_u64 v[96:97], v[96:97], 0, v[114:115]
	global_store_dwordx4 v[96:97], v[100:103], off
	v_mul_f32_e32 v96, 0xbfb8aa3b, v92
	v_mul_f32_e32 v97, 0xbfb8aa3b, v93
	v_exp_f32_e32 v96, v96
	v_exp_f32_e32 v97, v97
	v_mul_f32_e32 v99, 0xbfb8aa3b, v95
	v_exp_f32_e32 v98, v98
	v_exp_f32_e32 v99, v99
	v_mul_f32_e32 v100, 0xbfb8aa3b, v88
	v_mul_f32_e32 v101, 0xbfb8aa3b, v89
	v_exp_f32_e32 v100, v100
	v_exp_f32_e32 v101, v101
	v_add_f32_e32 v96, 1.0, v96
	v_add_f32_e32 v97, 1.0, v97
	v_mul_f32_e32 v102, 0xbfb8aa3b, v90
	v_mul_f32_e32 v103, 0xbfb8aa3b, v91
	v_rcp_f32_e32 v96, v96
	v_rcp_f32_e32 v97, v97
	v_add_f32_e32 v98, 1.0, v98
	v_add_f32_e32 v99, 1.0, v99
	v_exp_f32_e32 v102, v102
	v_exp_f32_e32 v103, v103
	v_rcp_f32_e32 v98, v98
	v_rcp_f32_e32 v99, v99
	v_add_f32_e32 v100, 1.0, v100
	v_add_f32_e32 v101, 1.0, v101
	v_rcp_f32_e32 v100, v100
	v_rcp_f32_e32 v101, v101
	v_add_f32_e32 v102, 1.0, v102
	v_add_f32_e32 v103, 1.0, v103
	v_pk_mul_f32 v[92:93], v[92:93], v[96:97]
	v_rcp_f32_e32 v102, v102
	v_rcp_f32_e32 v103, v103
	v_pk_mul_f32 v[84:85], v[92:93], v[84:85]
	v_pk_mul_f32 v[92:93], v[94:95], v[98:99]
	v_cvt_pk_bf16_f32 v84, v84, v85
	v_pk_mul_f32 v[86:87], v[92:93], v[86:87]
	s_nop 0
	v_cvt_pk_bf16_f32 v85, v86, v87
	v_pk_mul_f32 v[86:87], v[88:89], v[100:101]
	s_nop 0
	v_pk_mul_f32 v[80:81], v[86:87], v[80:81]
	s_nop 0
	v_cvt_pk_bf16_f32 v86, v80, v81
	v_pk_mul_f32 v[80:81], v[90:91], v[102:103]
	s_nop 0
	v_pk_mul_f32 v[80:81], v[80:81], v[82:83]
	v_mul_f32_e32 v82, 0xbfb8aa3b, v78
	v_cvt_pk_bf16_f32 v87, v80, v81
	v_or_b32_e32 v80, 32, v138
	v_mad_i64_i32 v[80:81], s[2:3], v80, s4, v[112:113]
	v_lshl_add_u64 v[80:81], v[80:81], 0, v[114:115]
	global_store_dwordx4 v[80:81], v[84:87], off
	v_mul_f32_e32 v80, 0xbfb8aa3b, v76
	v_mul_f32_e32 v81, 0xbfb8aa3b, v77
	v_exp_f32_e32 v80, v80
	v_exp_f32_e32 v81, v81
	v_mul_f32_e32 v83, 0xbfb8aa3b, v79
	v_exp_f32_e32 v82, v82
	v_exp_f32_e32 v83, v83
	v_mul_f32_e32 v84, 0xbfb8aa3b, v72
	v_mul_f32_e32 v85, 0xbfb8aa3b, v73
	v_exp_f32_e32 v84, v84
	v_exp_f32_e32 v85, v85
	v_add_f32_e32 v80, 1.0, v80
	v_add_f32_e32 v81, 1.0, v81
	v_mul_f32_e32 v86, 0xbfb8aa3b, v74
	v_mul_f32_e32 v87, 0xbfb8aa3b, v75
	v_rcp_f32_e32 v80, v80
	v_rcp_f32_e32 v81, v81
	v_add_f32_e32 v82, 1.0, v82
	v_add_f32_e32 v83, 1.0, v83
	v_exp_f32_e32 v86, v86
	v_exp_f32_e32 v87, v87
	v_rcp_f32_e32 v82, v82
	v_rcp_f32_e32 v83, v83
	v_add_f32_e32 v84, 1.0, v84
	v_add_f32_e32 v85, 1.0, v85
	v_rcp_f32_e32 v84, v84
	v_rcp_f32_e32 v85, v85
	v_add_f32_e32 v86, 1.0, v86
	v_add_f32_e32 v87, 1.0, v87
	v_pk_mul_f32 v[76:77], v[76:77], v[80:81]
	v_rcp_f32_e32 v86, v86
	v_rcp_f32_e32 v87, v87
	v_pk_mul_f32 v[68:69], v[76:77], v[68:69]
	v_pk_mul_f32 v[76:77], v[78:79], v[82:83]
	v_cvt_pk_bf16_f32 v68, v68, v69
	v_pk_mul_f32 v[70:71], v[76:77], v[70:71]
	s_nop 0
	v_cvt_pk_bf16_f32 v69, v70, v71
	v_pk_mul_f32 v[70:71], v[72:73], v[84:85]
	v_add_u32_e32 v72, 0x80, v138
	v_pk_mul_f32 v[64:65], v[70:71], v[64:65]
	s_nop 0
	v_cvt_pk_bf16_f32 v70, v64, v65
	v_pk_mul_f32 v[64:65], v[74:75], v[86:87]
	s_nop 0
	v_pk_mul_f32 v[64:65], v[64:65], v[66:67]
	v_mul_f32_e32 v66, 0xbfb8aa3b, v62
	v_cvt_pk_bf16_f32 v71, v64, v65
	v_or_b32_e32 v64, 48, v138
	v_mad_i64_i32 v[64:65], s[2:3], v64, s4, v[112:113]
	v_lshl_add_u64 v[64:65], v[64:65], 0, v[114:115]
	global_store_dwordx4 v[64:65], v[68:71], off
	v_mul_f32_e32 v64, 0xbfb8aa3b, v60
	v_mul_f32_e32 v65, 0xbfb8aa3b, v61
	v_exp_f32_e32 v64, v64
	v_exp_f32_e32 v65, v65
	v_mul_f32_e32 v67, 0xbfb8aa3b, v63
	v_exp_f32_e32 v66, v66
	v_exp_f32_e32 v67, v67
	v_mul_f32_e32 v68, 0xbfb8aa3b, v56
	v_mul_f32_e32 v69, 0xbfb8aa3b, v57
	v_exp_f32_e32 v68, v68
	v_exp_f32_e32 v69, v69
	v_add_f32_e32 v64, 1.0, v64
	v_add_f32_e32 v65, 1.0, v65
	v_mul_f32_e32 v70, 0xbfb8aa3b, v58
	v_mul_f32_e32 v71, 0xbfb8aa3b, v59
	v_rcp_f32_e32 v64, v64
	v_rcp_f32_e32 v65, v65
	v_add_f32_e32 v66, 1.0, v66
	v_add_f32_e32 v67, 1.0, v67
	v_exp_f32_e32 v70, v70
	v_exp_f32_e32 v71, v71
	v_rcp_f32_e32 v66, v66
	v_rcp_f32_e32 v67, v67
	v_add_f32_e32 v68, 1.0, v68
	v_add_f32_e32 v69, 1.0, v69
	v_rcp_f32_e32 v68, v68
	v_rcp_f32_e32 v69, v69
	v_add_f32_e32 v70, 1.0, v70
	v_add_f32_e32 v71, 1.0, v71
	v_pk_mul_f32 v[60:61], v[60:61], v[64:65]
	v_rcp_f32_e32 v70, v70
	v_rcp_f32_e32 v71, v71
	v_pk_mul_f32 v[52:53], v[60:61], v[52:53]
	v_pk_mul_f32 v[60:61], v[62:63], v[66:67]
	v_cvt_pk_bf16_f32 v52, v52, v53
	v_pk_mul_f32 v[54:55], v[60:61], v[54:55]
	s_nop 0
	v_cvt_pk_bf16_f32 v53, v54, v55
	v_pk_mul_f32 v[54:55], v[56:57], v[68:69]
	s_nop 0
	v_pk_mul_f32 v[48:49], v[54:55], v[48:49]
; #define PG8_WAIT_V(n) asm volatile("s_waitcnt vmcnt(" #n ")" ::: "memory")
; #define PG8_BAR __builtin_amdgcn_s_barrier()
; template <class Epi>
; DI void gemm_phase(LAS unsigned char* lds, const Gemm g, const StaticOrder& S, const Epi& E) {
;     ...
;         cur = nxt; cA = nA; cB = nB; ++ui;
;     }
;     PG8_WAIT_V(0);
;     if (wr == 0) PG8_BAR;
;     PG8_BAR;
;     DI void operator()(const f32x4 (&acc)[2][2][4][2], const Unit& u, int wr, int wc, int fr, int fq) const {
;     ...
;             for (int m = 0; m < 4; ++m) { float hv[8];
; #pragma unroll
;                 for (int n = 0; n < 2; ++n)
; #pragma unroll
;                     for (int e = 0; e < 4; ++e) { const float gt = acc[ai][0][m][n][e], up = acc[ai][1][m][n][e];
;                         hv[n * 4 + e] = gt * __builtin_amdgcn_rcpf(1.f + __builtin_amdgcn_exp2f(-1.4426950408889634f * gt)) * up; }
;                 *(u32x4*)(H + (size_t)(row0 + ai * HALF + m * 16) * DFF + col0) = (u32x4){pk(hv[0], hv[1]), pk(hv[2], hv[3]), pk(hv[4], hv[5]), pk(hv[6], hv[7])}; }
	s_nop 0
	v_cvt_pk_bf16_f32 v54, v48, v49
	v_pk_mul_f32 v[48:49], v[58:59], v[70:71]
	s_nop 0
	v_pk_mul_f32 v[48:49], v[48:49], v[50:51]
	v_mul_f32_e32 v50, 0xbfb8aa3b, v46
	v_cvt_pk_bf16_f32 v55, v48, v49
	v_mad_i64_i32 v[48:49], s[2:3], v72, s4, v[112:113]
	v_lshl_add_u64 v[48:49], v[48:49], 0, v[114:115]
	global_store_dwordx4 v[48:49], v[52:55], off
	v_mul_f32_e32 v48, 0xbfb8aa3b, v44
	v_mul_f32_e32 v49, 0xbfb8aa3b, v45
	v_exp_f32_e32 v48, v48
	v_exp_f32_e32 v49, v49
	v_mul_f32_e32 v51, 0xbfb8aa3b, v47
	v_exp_f32_e32 v50, v50
	v_exp_f32_e32 v51, v51
	v_mul_f32_e32 v52, 0xbfb8aa3b, v40
	v_mul_f32_e32 v53, 0xbfb8aa3b, v41
	v_exp_f32_e32 v52, v52
	v_exp_f32_e32 v53, v53
	v_add_f32_e32 v48, 1.0, v48
	v_add_f32_e32 v49, 1.0, v49
	v_mul_f32_e32 v54, 0xbfb8aa3b, v42
	v_mul_f32_e32 v55, 0xbfb8aa3b, v43
	v_rcp_f32_e32 v48, v48
	v_rcp_f32_e32 v49, v49
	v_add_f32_e32 v50, 1.0, v50
	v_add_f32_e32 v51, 1.0, v51
	v_exp_f32_e32 v54, v54
	v_exp_f32_e32 v55, v55
	v_rcp_f32_e32 v50, v50
	v_rcp_f32_e32 v51, v51
	v_add_f32_e32 v52, 1.0, v52
	v_add_f32_e32 v53, 1.0, v53
	v_rcp_f32_e32 v52, v52
	v_rcp_f32_e32 v53, v53
	v_add_f32_e32 v54, 1.0, v54
	v_add_f32_e32 v55, 1.0, v55
	v_pk_mul_f32 v[44:45], v[44:45], v[48:49]
	v_rcp_f32_e32 v54, v54
	v_rcp_f32_e32 v55, v55
	v_pk_mul_f32 v[36:37], v[44:45], v[36:37]
	v_pk_mul_f32 v[44:45], v[46:47], v[50:51]
	v_cvt_pk_bf16_f32 v36, v36, v37
	v_pk_mul_f32 v[38:39], v[44:45], v[38:39]
	s_nop 0
	v_cvt_pk_bf16_f32 v37, v38, v39
	v_pk_mul_f32 v[38:39], v[40:41], v[52:53]
	s_nop 0
	v_pk_mul_f32 v[32:33], v[38:39], v[32:33]
	s_nop 0
	v_cvt_pk_bf16_f32 v38, v32, v33
	v_pk_mul_f32 v[32:33], v[42:43], v[54:55]
	s_nop 0
	v_pk_mul_f32 v[32:33], v[32:33], v[34:35]
	v_mul_f32_e32 v34, 0xbfb8aa3b, v30
	v_cvt_pk_bf16_f32 v39, v32, v33
	v_add_u32_e32 v32, 0x90, v138
	v_mad_i64_i32 v[32:33], s[2:3], v32, s4, v[112:113]
	v_lshl_add_u64 v[32:33], v[32:33], 0, v[114:115]
	global_store_dwordx4 v[32:33], v[36:39], off
	v_mul_f32_e32 v32, 0xbfb8aa3b, v28
	v_mul_f32_e32 v33, 0xbfb8aa3b, v29
	v_exp_f32_e32 v32, v32
	v_exp_f32_e32 v33, v33
	v_mul_f32_e32 v35, 0xbfb8aa3b, v31
	v_exp_f32_e32 v34, v34
	v_exp_f32_e32 v35, v35
	v_mul_f32_e32 v36, 0xbfb8aa3b, v24
	v_mul_f32_e32 v37, 0xbfb8aa3b, v25
	v_exp_f32_e32 v36, v36
	v_exp_f32_e32 v37, v37
	v_add_f32_e32 v32, 1.0, v32
	v_add_f32_e32 v33, 1.0, v33
	v_mul_f32_e32 v38, 0xbfb8aa3b, v26
	v_mul_f32_e32 v39, 0xbfb8aa3b, v27
	v_rcp_f32_e32 v32, v32
	v_rcp_f32_e32 v33, v33
	v_add_f32_e32 v34, 1.0, v34
	v_add_f32_e32 v35, 1.0, v35
	v_exp_f32_e32 v38, v38
	v_exp_f32_e32 v39, v39
	v_rcp_f32_e32 v34, v34
	v_rcp_f32_e32 v35, v35
	v_add_f32_e32 v36, 1.0, v36
	v_add_f32_e32 v37, 1.0, v37
	v_rcp_f32_e32 v36, v36
	v_rcp_f32_e32 v37, v37
	v_add_f32_e32 v38, 1.0, v38
	v_add_f32_e32 v39, 1.0, v39
	v_pk_mul_f32 v[28:29], v[28:29], v[32:33]
	v_rcp_f32_e32 v38, v38
	v_rcp_f32_e32 v39, v39
	v_pk_mul_f32 v[20:21], v[28:29], v[20:21]
	v_pk_mul_f32 v[28:29], v[30:31], v[34:35]
	v_cvt_pk_bf16_f32 v20, v20, v21
	v_pk_mul_f32 v[22:23], v[28:29], v[22:23]
	s_nop 0
	v_cvt_pk_bf16_f32 v21, v22, v23
	v_pk_mul_f32 v[22:23], v[24:25], v[36:37]
	s_nop 0
	v_pk_mul_f32 v[16:17], v[22:23], v[16:17]
	s_nop 0
	v_cvt_pk_bf16_f32 v22, v16, v17
	v_pk_mul_f32 v[16:17], v[26:27], v[38:39]
	s_nop 0
	v_pk_mul_f32 v[16:17], v[16:17], v[18:19]
	v_mul_f32_e32 v18, 0xbfb8aa3b, v14
	v_cvt_pk_bf16_f32 v23, v16, v17
	v_add_u32_e32 v16, 0xa0, v138
	v_mad_i64_i32 v[16:17], s[2:3], v16, s4, v[112:113]
	v_lshl_add_u64 v[16:17], v[16:17], 0, v[114:115]
	global_store_dwordx4 v[16:17], v[20:23], off
	v_mul_f32_e32 v16, 0xbfb8aa3b, v12
	v_mul_f32_e32 v17, 0xbfb8aa3b, v13
	v_exp_f32_e32 v16, v16
	v_exp_f32_e32 v17, v17
	v_mul_f32_e32 v19, 0xbfb8aa3b, v15
	v_exp_f32_e32 v18, v18
	v_exp_f32_e32 v19, v19
	v_mul_f32_e32 v20, 0xbfb8aa3b, v8
	v_mul_f32_e32 v21, 0xbfb8aa3b, v9
	v_exp_f32_e32 v20, v20
	v_exp_f32_e32 v21, v21
	v_add_f32_e32 v16, 1.0, v16
	v_add_f32_e32 v17, 1.0, v17
	v_mul_f32_e32 v22, 0xbfb8aa3b, v10
	v_mul_f32_e32 v23, 0xbfb8aa3b, v11
	v_rcp_f32_e32 v16, v16
	v_rcp_f32_e32 v17, v17
	v_add_f32_e32 v18, 1.0, v18
	v_add_f32_e32 v19, 1.0, v19
	v_exp_f32_e32 v22, v22
	v_exp_f32_e32 v23, v23
	v_rcp_f32_e32 v18, v18
	v_rcp_f32_e32 v19, v19
	v_add_f32_e32 v20, 1.0, v20
	v_add_f32_e32 v21, 1.0, v21
	v_rcp_f32_e32 v20, v20
	v_rcp_f32_e32 v21, v21
	v_add_f32_e32 v22, 1.0, v22
	v_add_f32_e32 v23, 1.0, v23
	v_pk_mul_f32 v[12:13], v[12:13], v[16:17]
	v_rcp_f32_e32 v22, v22
	v_rcp_f32_e32 v23, v23
	v_pk_mul_f32 v[4:5], v[12:13], v[4:5]
	v_pk_mul_f32 v[12:13], v[14:15], v[18:19]
	v_cvt_pk_bf16_f32 v4, v4, v5
	v_pk_mul_f32 v[6:7], v[12:13], v[6:7]
	s_nop 0
	v_cvt_pk_bf16_f32 v5, v6, v7
	v_pk_mul_f32 v[6:7], v[8:9], v[20:21]
	s_nop 0
	v_pk_mul_f32 v[0:1], v[6:7], v[0:1]
	s_nop 0
	v_cvt_pk_bf16_f32 v6, v0, v1
	v_pk_mul_f32 v[0:1], v[10:11], v[22:23]
	s_nop 0
	v_pk_mul_f32 v[0:1], v[0:1], v[2:3]
	s_nop 0
	v_cvt_pk_bf16_f32 v7, v0, v1
	v_add_u32_e32 v0, 0xb0, v138
	v_mad_i64_i32 v[0:1], s[2:3], v0, s4, v[112:113]
	v_lshl_add_u64 v[0:1], v[0:1], 0, v[114:115]
	s_mov_b32 s2, s8
	s_mov_b32 s3, s10
	global_store_dwordx4 v[0:1], v[4:7], off
	s_cbranch_vccz .LBB0_34
	s_waitcnt vmcnt(0)
	s_cmpk_gt_u32 s24, 0xff
	s_cbranch_scc1 .LBB0_41
	s_barrier

; #define PG8_STAGE(bufoff, gbase) do { _Pragma("unroll") for (int _i = 0; _i < 2; ++_i) \
;         __builtin_amdgcn_global_load_lds((const unsigned*)((const char*)(gbase) + voff[_i]), (LAS unsigned*)(lds + (bufoff) + ldsw + _i * 8192), 16, 0, 0); } while (0)
; #define PG8_LDA(dst, b, h) do { _Pragma("unroll") for (int m = 0; m < 4; ++m) _Pragma("unroll") for (int k = 0; k < 2; ++k) dst[m][k] = *(const LAS bf16x8*)(lds + PG8_SA(b, h) + aoff + m * 2048 + k * 1024); } while (0)
; #define PG8_LDB(dst, b, h) do { _Pragma("unroll") for (int n = 0; n < 2; ++n) _Pragma("unroll") for (int k = 0; k < 2; ++k) dst[n][k] = *(const LAS bf16x8*)(lds + PG8_SB(b, h) + boff + n * 2048 + k * 1024); } while (0)
; #define PG8_MMA(ai, bj, At, Bt) do { __builtin_amdgcn_s_setprio(1); _Pragma("unroll") for (int m = 0; m < 4; ++m) _Pragma("unroll") for (int n = 0; n < 2; ++n) _Pragma("unroll") for (int k = 0; k < 2; ++k) \
;         acc[ai][bj][m][n] = __builtin_amdgcn_mfma_f32_16x16x32_bf16(Bt[n][k], At[m][k], acc[ai][bj][m][n], 0, 0, 0); __builtin_amdgcn_s_setprio(0); } while (0)
; #define PG8_WAIT_V(n) asm volatile("s_waitcnt vmcnt(" #n ")" ::: "memory")
; #define PG8_WAIT_L(n) asm volatile("s_waitcnt lgkmcnt(" #n ")" ::: "memory")
; #define PG8_BAR __builtin_amdgcn_s_barrier()
; #define PG8_SCHED __builtin_amdgcn_sched_barrier(0)
; template <class Epi>
; DI void gemm_phase(LAS unsigned char* lds, const Gemm g, const StaticOrder& S, const Epi& E) {
;     ...
;         for (int t = 0; t < nt; t += 2) {
;             const bool last = (t == nt - 2);
;             const char* a1 = cA + (size_t)(t + 1) * kstep;
;             const char* a2 = last ? nA : cA + (size_t)(t + 2) * kstep; const char* b2 = last ? nB : cB + (size_t)(t + 2) * kstep;
;             const char* a3 = a2 + kstep; const char* b3 = b2 + kstep;
;             PG8_LDB(B0, 0, 0); PG8_SCHED; PG8_LDA(At, 0, 0); PG8_STAGE(PG8_SA(1, 1), a1 + hstep);
;             PG8_WAIT_L(8); PG8_BAR; PG8_WAIT_L(0); PG8_MMA(0, 0, At, B0); PG8_BAR; PG8_SCHED;
;             PG8_LDB(B1, 0, 1); PG8_STAGE(PG8_SB(0, 0), b2);
;             PG8_BAR; PG8_WAIT_L(0); PG8_MMA(0, 1, At, B1); PG8_BAR;
;             PG8_LDA(At, 0, 1); PG8_STAGE(PG8_SA(0, 0), a2);
;             PG8_BAR; PG8_WAIT_L(0); PG8_MMA(1, 0, At, B0); PG8_BAR; PG8_SCHED;
;             PG8_STAGE(PG8_SB(0, 1), b2 + hstep);
;             PG8_WAIT_V(6); PG8_BAR; PG8_MMA(1, 1, At, B1); PG8_BAR;
.LBB0_77:
	ds_read_b128 v[128:131], v226
	ds_read_b128 v[132:135], v226 offset:1024
	ds_read_b128 v[136:139], v226 offset:2048
	ds_read_b128 v[140:143], v226 offset:3072
	ds_read_b128 v[144:147], v228
	ds_read_b128 v[148:151], v228 offset:1024
	ds_read_b128 v[152:155], v228 offset:2048
	ds_read_b128 v[194:197], v228 offset:3072
	ds_read_b128 v[198:201], v228 offset:4096
	ds_read_b128 v[202:205], v228 offset:5120
	ds_read_b128 v[206:209], v228 offset:6144
	ds_read_b128 v[210:213], v228 offset:7168
	s_add_u32 s22, s20, 0x100
	s_addc_u32 s23, s21, 0
	s_add_i32 s43, 0, 0x10000
	s_cmp_eq_u32 s33, 32
	s_cselect_b32 s27, s9, s23
	s_cselect_b32 s26, s8, s22
	s_cselect_b32 s25, s11, s5
	s_cselect_b32 s24, s10, s4
	s_add_i32 m0, s34, 0xc000
	s_nop 0
	global_load_lds_dwordx4 v190, s[20:21]
	s_add_i32 m0, s34, 0xe000
	s_nop 0
	global_load_lds_dwordx4 v192, s[20:21]
	s_waitcnt lgkmcnt(8)
	s_setprio 1
	s_barrier
	s_waitcnt lgkmcnt(0)
	v_mfma_f32_16x16x32_bf16 v[124:127], v[128:131], v[144:147], v[124:127]
	v_mfma_f32_16x16x32_bf16 v[120:123], v[136:139], v[144:147], v[120:123]
	v_mfma_f32_16x16x32_bf16 v[116:119], v[128:131], v[152:155], v[116:119]
	v_mfma_f32_16x16x32_bf16 v[112:115], v[136:139], v[152:155], v[112:115]
	v_mfma_f32_16x16x32_bf16 v[108:111], v[128:131], v[198:201], v[108:111]
	v_mfma_f32_16x16x32_bf16 v[104:107], v[136:139], v[198:201], v[104:107]
	v_mfma_f32_16x16x32_bf16 v[100:103], v[128:131], v[206:209], v[100:103]
	v_mfma_f32_16x16x32_bf16 v[96:99], v[136:139], v[206:209], v[96:99]
	v_mfma_f32_16x16x32_bf16 v[124:127], v[132:135], v[148:151], v[124:127]
	v_mfma_f32_16x16x32_bf16 v[120:123], v[140:143], v[148:151], v[120:123]
	v_mfma_f32_16x16x32_bf16 v[116:119], v[132:135], v[194:197], v[116:119]
	v_mfma_f32_16x16x32_bf16 v[112:115], v[140:143], v[194:197], v[112:115]
	v_mfma_f32_16x16x32_bf16 v[108:111], v[132:135], v[202:205], v[108:111]
	v_mfma_f32_16x16x32_bf16 v[104:107], v[140:143], v[202:205], v[104:107]
	v_mfma_f32_16x16x32_bf16 v[100:103], v[132:135], v[210:213], v[100:103]
	s_setprio 0
	v_mfma_f32_16x16x32_bf16 v[96:99], v[140:143], v[210:213], v[96:99]
	s_barrier
	ds_read_b128 v[214:217], v226 offset:16384
	ds_read_b128 v[230:233], v226 offset:17408
	ds_read_b128 v[234:237], v226 offset:18432
	ds_read_b128 v[238:241], v226 offset:19456
	s_add_i32 s44, 0, 0x14000
	s_add_i32 s20, s43, s31
	s_mov_b32 m0, s20
	s_nop 0
	global_load_lds_dwordx4 v188, s[24:25]
	s_add_i32 m0, s20, 0x2000
	s_nop 0
	global_load_lds_dwordx4 v186, s[24:25]
	s_waitcnt lgkmcnt(0)
	s_setprio 1
	s_barrier
	v_mfma_f32_16x16x32_bf16 v[60:63], v[214:217], v[144:147], v[60:63]
	v_mfma_f32_16x16x32_bf16 v[56:59], v[234:237], v[144:147], v[56:59]
	v_mfma_f32_16x16x32_bf16 v[52:55], v[214:217], v[152:155], v[52:55]
	v_mfma_f32_16x16x32_bf16 v[48:51], v[234:237], v[152:155], v[48:51]
	v_mfma_f32_16x16x32_bf16 v[44:47], v[214:217], v[198:201], v[44:47]
	v_mfma_f32_16x16x32_bf16 v[40:43], v[234:237], v[198:201], v[40:43]
	v_mfma_f32_16x16x32_bf16 v[36:39], v[214:217], v[206:209], v[36:39]
	v_mfma_f32_16x16x32_bf16 v[32:35], v[234:237], v[206:209], v[32:35]
	v_mfma_f32_16x16x32_bf16 v[60:63], v[230:233], v[148:151], v[60:63]
	v_mfma_f32_16x16x32_bf16 v[56:59], v[238:241], v[148:151], v[56:59]
	v_mfma_f32_16x16x32_bf16 v[52:55], v[230:233], v[194:197], v[52:55]
	v_mfma_f32_16x16x32_bf16 v[48:51], v[238:241], v[194:197], v[48:51]
	v_mfma_f32_16x16x32_bf16 v[44:47], v[230:233], v[202:205], v[44:47]
	v_mfma_f32_16x16x32_bf16 v[40:43], v[238:241], v[202:205], v[40:43]
	v_mfma_f32_16x16x32_bf16 v[36:39], v[230:233], v[210:213], v[36:39]
	s_setprio 0
	v_mfma_f32_16x16x32_bf16 v[32:35], v[238:241], v[210:213], v[32:35]
	s_barrier
	ds_read_b128 v[144:147], v228 offset:16384
	ds_read_b128 v[148:151], v228 offset:17408
	ds_read_b128 v[152:155], v228 offset:18432
	ds_read_b128 v[194:197], v228 offset:19456
	ds_read_b128 v[198:201], v228 offset:20480
	ds_read_b128 v[202:205], v228 offset:21504
	ds_read_b128 v[206:209], v228 offset:22528
	ds_read_b128 v[210:213], v228 offset:23552
	s_mov_b32 m0, s34
	s_nop 0
	global_load_lds_dwordx4 v188, s[26:27]
	s_mov_b64 s[100:101], s[26:27]
	s_mov_b32 m0, s35
	s_nop 0
	global_load_lds_dwordx4 v186, s[26:27]
	s_waitcnt lgkmcnt(0)
	s_setprio 1
	s_barrier
	v_mfma_f32_16x16x32_bf16 v[92:95], v[128:131], v[144:147], v[92:95]
	v_mfma_f32_16x16x32_bf16 v[88:91], v[136:139], v[144:147], v[88:91]
	v_mfma_f32_16x16x32_bf16 v[84:87], v[128:131], v[152:155], v[84:87]
	v_mfma_f32_16x16x32_bf16 v[80:83], v[136:139], v[152:155], v[80:83]
	v_mfma_f32_16x16x32_bf16 v[76:79], v[128:131], v[198:201], v[76:79]
	v_mfma_f32_16x16x32_bf16 v[72:75], v[136:139], v[198:201], v[72:75]
	v_mfma_f32_16x16x32_bf16 v[68:71], v[128:131], v[206:209], v[68:71]
	v_mfma_f32_16x16x32_bf16 v[64:67], v[136:139], v[206:209], v[64:67]
	v_mfma_f32_16x16x32_bf16 v[92:95], v[132:135], v[148:151], v[92:95]
	v_mfma_f32_16x16x32_bf16 v[88:91], v[140:143], v[148:151], v[88:91]
	v_mfma_f32_16x16x32_bf16 v[84:87], v[132:135], v[194:197], v[84:87]
	v_mfma_f32_16x16x32_bf16 v[80:83], v[140:143], v[194:197], v[80:83]
	v_mfma_f32_16x16x32_bf16 v[76:79], v[132:135], v[202:205], v[76:79]
	v_mfma_f32_16x16x32_bf16 v[72:75], v[140:143], v[202:205], v[72:75]
	v_mfma_f32_16x16x32_bf16 v[68:71], v[132:135], v[210:213], v[68:71]
	s_setprio 0
	v_mfma_f32_16x16x32_bf16 v[64:67], v[140:143], v[210:213], v[64:67]
	s_barrier
	s_add_u32 s20, s24, 0x90000
	s_addc_u32 s21, s25, 0
	s_add_i32 s43, s44, s31
	s_mov_b32 m0, s43
	s_nop 0
	global_load_lds_dwordx4 v188, s[20:21]
	s_add_i32 m0, s43, 0x2000
	s_nop 0
	global_load_lds_dwordx4 v186, s[20:21]
	s_waitcnt vmcnt(6)
	s_setprio 1
	s_barrier
; #define PG8_STAGE(bufoff, gbase) do { _Pragma("unroll") for (int _i = 0; _i < 2; ++_i) \
;         __builtin_amdgcn_global_load_lds((const unsigned*)((const char*)(gbase) + voff[_i]), (LAS unsigned*)(lds + (bufoff) + ldsw + _i * 8192), 16, 0, 0); } while (0)
; #define PG8_LDA(dst, b, h) do { _Pragma("unroll") for (int m = 0; m < 4; ++m) _Pragma("unroll") for (int k = 0; k < 2; ++k) dst[m][k] = *(const LAS bf16x8*)(lds + PG8_SA(b, h) + aoff + m * 2048 + k * 1024); } while (0)
; #define PG8_LDB(dst, b, h) do { _Pragma("unroll") for (int n = 0; n < 2; ++n) _Pragma("unroll") for (int k = 0; k < 2; ++k) dst[n][k] = *(const LAS bf16x8*)(lds + PG8_SB(b, h) + boff + n * 2048 + k * 1024); } while (0)
; #define PG8_MMA(ai, bj, At, Bt) do { __builtin_amdgcn_s_setprio(1); _Pragma("unroll") for (int m = 0; m < 4; ++m) _Pragma("unroll") for (int n = 0; n < 2; ++n) _Pragma("unroll") for (int k = 0; k < 2; ++k) \
;         acc[ai][bj][m][n] = __builtin_amdgcn_mfma_f32_16x16x32_bf16(Bt[n][k], At[m][k], acc[ai][bj][m][n], 0, 0, 0); __builtin_amdgcn_s_setprio(0); } while (0)
; #define PG8_WAIT_V(n) asm volatile("s_waitcnt vmcnt(" #n ")" ::: "memory")
; #define PG8_WAIT_L(n) asm volatile("s_waitcnt lgkmcnt(" #n ")" ::: "memory")
; #define PG8_BAR __builtin_amdgcn_s_barrier()
; #define PG8_SCHED __builtin_amdgcn_sched_barrier(0)
; template <class Epi>
; DI void gemm_phase(LAS unsigned char* lds, const Gemm g, const StaticOrder& S, const Epi& E) {
;     ...
;             PG8_WAIT_V(6); PG8_BAR; PG8_MMA(1, 1, At, B1); PG8_BAR;
;             PG8_LDB(B0, 1, 0); PG8_SCHED; PG8_LDA(At, 1, 0); PG8_STAGE(PG8_SA(0, 1), a2 + hstep);
;             PG8_WAIT_L(8); PG8_BAR; PG8_WAIT_L(0); PG8_MMA(0, 0, At, B0); PG8_BAR; PG8_SCHED;
;             PG8_LDB(B1, 1, 1); PG8_STAGE(PG8_SB(1, 0), b3);
;             PG8_BAR; PG8_WAIT_L(0); PG8_MMA(0, 1, At, B1); PG8_BAR;
;             PG8_LDA(At, 1, 1); PG8_STAGE(PG8_SA(1, 0), a3);
;             PG8_BAR; PG8_WAIT_L(0); PG8_MMA(1, 0, At, B0); PG8_BAR; PG8_SCHED;
	v_mfma_f32_16x16x32_bf16 v[28:31], v[214:217], v[144:147], v[28:31]
	v_mfma_f32_16x16x32_bf16 v[24:27], v[234:237], v[144:147], v[24:27]
	v_mfma_f32_16x16x32_bf16 v[20:23], v[214:217], v[152:155], v[20:23]
	v_mfma_f32_16x16x32_bf16 v[16:19], v[234:237], v[152:155], v[16:19]
	v_mfma_f32_16x16x32_bf16 v[12:15], v[214:217], v[198:201], v[12:15]
	v_mfma_f32_16x16x32_bf16 v[8:11], v[234:237], v[198:201], v[8:11]
	v_mfma_f32_16x16x32_bf16 v[4:7], v[214:217], v[206:209], v[4:7]
	v_mfma_f32_16x16x32_bf16 v[0:3], v[234:237], v[206:209], v[0:3]
	v_mfma_f32_16x16x32_bf16 v[28:31], v[230:233], v[148:151], v[28:31]
	v_mfma_f32_16x16x32_bf16 v[24:27], v[238:241], v[148:151], v[24:27]
	v_mfma_f32_16x16x32_bf16 v[20:23], v[230:233], v[194:197], v[20:23]
	v_mfma_f32_16x16x32_bf16 v[16:19], v[238:241], v[194:197], v[16:19]
	v_mfma_f32_16x16x32_bf16 v[12:15], v[230:233], v[202:205], v[12:15]
	v_mfma_f32_16x16x32_bf16 v[8:11], v[238:241], v[202:205], v[8:11]
	v_mfma_f32_16x16x32_bf16 v[4:7], v[230:233], v[210:213], v[4:7]
	s_setprio 0
	v_mfma_f32_16x16x32_bf16 v[0:3], v[238:241], v[210:213], v[0:3]
	s_barrier
	ds_read_b128 v[128:131], v226 offset:32768
	ds_read_b128 v[132:135], v226 offset:33792
	ds_read_b128 v[136:139], v226 offset:34816
	ds_read_b128 v[140:143], v226 offset:35840
	ds_read_b128 v[144:147], v228 offset:32768
	ds_read_b128 v[148:151], v228 offset:33792
	ds_read_b128 v[152:155], v228 offset:34816
	ds_read_b128 v[194:197], v228 offset:35840
	ds_read_b128 v[198:201], v228 offset:36864
	ds_read_b128 v[202:205], v228 offset:37888
	ds_read_b128 v[206:209], v228 offset:38912
	ds_read_b128 v[210:213], v228 offset:39936
	s_add_i32 s43, 0, 0x18000
	s_add_u32 s20, s26, 0x90000
	s_addc_u32 s21, s27, 0
	s_mov_b32 m0, s36
	s_nop 0
	global_load_lds_dwordx4 v188, s[20:21]
	s_mov_b32 m0, s37
	s_nop 0
	global_load_lds_dwordx4 v186, s[20:21]
	s_waitcnt lgkmcnt(8)
	s_setprio 1
	s_barrier
	s_waitcnt lgkmcnt(0)
	v_mfma_f32_16x16x32_bf16 v[124:127], v[128:131], v[144:147], v[124:127]
	v_mfma_f32_16x16x32_bf16 v[120:123], v[136:139], v[144:147], v[120:123]
	v_mfma_f32_16x16x32_bf16 v[116:119], v[128:131], v[152:155], v[116:119]
	v_mfma_f32_16x16x32_bf16 v[112:115], v[136:139], v[152:155], v[112:115]
	v_mfma_f32_16x16x32_bf16 v[108:111], v[128:131], v[198:201], v[108:111]
	v_mfma_f32_16x16x32_bf16 v[104:107], v[136:139], v[198:201], v[104:107]
	v_mfma_f32_16x16x32_bf16 v[100:103], v[128:131], v[206:209], v[100:103]
	v_mfma_f32_16x16x32_bf16 v[96:99], v[136:139], v[206:209], v[96:99]
	v_mfma_f32_16x16x32_bf16 v[124:127], v[132:135], v[148:151], v[124:127]
	v_mfma_f32_16x16x32_bf16 v[120:123], v[140:143], v[148:151], v[120:123]
	v_mfma_f32_16x16x32_bf16 v[116:119], v[132:135], v[194:197], v[116:119]
	v_mfma_f32_16x16x32_bf16 v[112:115], v[140:143], v[194:197], v[112:115]
	v_mfma_f32_16x16x32_bf16 v[108:111], v[132:135], v[202:205], v[108:111]
	v_mfma_f32_16x16x32_bf16 v[104:107], v[140:143], v[202:205], v[104:107]
	v_mfma_f32_16x16x32_bf16 v[100:103], v[132:135], v[210:213], v[100:103]
	s_setprio 0
	v_mfma_f32_16x16x32_bf16 v[96:99], v[140:143], v[210:213], v[96:99]
	s_barrier
	ds_read_b128 v[214:217], v226 offset:49152
	ds_read_b128 v[230:233], v226 offset:50176
	ds_read_b128 v[234:237], v226 offset:51200
	ds_read_b128 v[238:241], v226 offset:52224
	s_add_i32 s26, 0, 0x1c000
	s_add_i32 s20, s43, s31
	s_add_i32 m0, s20, 0xffffff80
	s_nop 0
	global_load_lds_dwordx4 v188, s[24:25] offset:128
	s_add_i32 m0, s20, 0x1f80
	s_nop 0
	global_load_lds_dwordx4 v186, s[24:25] offset:128
	s_waitcnt lgkmcnt(0)
	s_setprio 1
	s_barrier
	v_mfma_f32_16x16x32_bf16 v[60:63], v[214:217], v[144:147], v[60:63]
	v_mfma_f32_16x16x32_bf16 v[56:59], v[234:237], v[144:147], v[56:59]
	v_mfma_f32_16x16x32_bf16 v[52:55], v[214:217], v[152:155], v[52:55]
	v_mfma_f32_16x16x32_bf16 v[48:51], v[234:237], v[152:155], v[48:51]
	v_mfma_f32_16x16x32_bf16 v[44:47], v[214:217], v[198:201], v[44:47]
	v_mfma_f32_16x16x32_bf16 v[40:43], v[234:237], v[198:201], v[40:43]
	v_mfma_f32_16x16x32_bf16 v[36:39], v[214:217], v[206:209], v[36:39]
	v_mfma_f32_16x16x32_bf16 v[32:35], v[234:237], v[206:209], v[32:35]
	v_mfma_f32_16x16x32_bf16 v[60:63], v[230:233], v[148:151], v[60:63]
	v_mfma_f32_16x16x32_bf16 v[56:59], v[238:241], v[148:151], v[56:59]
	v_mfma_f32_16x16x32_bf16 v[52:55], v[230:233], v[194:197], v[52:55]
	v_mfma_f32_16x16x32_bf16 v[48:51], v[238:241], v[194:197], v[48:51]
	v_mfma_f32_16x16x32_bf16 v[44:47], v[230:233], v[202:205], v[44:47]
	v_mfma_f32_16x16x32_bf16 v[40:43], v[238:241], v[202:205], v[40:43]
	v_mfma_f32_16x16x32_bf16 v[36:39], v[230:233], v[210:213], v[36:39]
	s_setprio 0
	v_mfma_f32_16x16x32_bf16 v[32:35], v[238:241], v[210:213], v[32:35]
	s_barrier
	ds_read_b128 v[144:147], v228 offset:49152
	ds_read_b128 v[148:151], v228 offset:50176
	ds_read_b128 v[152:155], v228 offset:51200
	ds_read_b128 v[194:197], v228 offset:52224
	ds_read_b128 v[198:201], v228 offset:53248
	ds_read_b128 v[202:205], v228 offset:54272
	ds_read_b128 v[206:209], v228 offset:55296
	ds_read_b128 v[210:213], v228 offset:56320
	s_add_i32 m0, s38, 0xffffff80
	s_nop 0
	global_load_lds_dwordx4 v188, s[100:101] offset:128
	s_add_i32 m0, s39, 0xffffff80
	s_nop 0
	global_load_lds_dwordx4 v186, s[100:101] offset:128
	s_waitcnt lgkmcnt(0)
	s_setprio 1
	s_barrier
; #define PG8_WAIT_V(n) asm volatile("s_waitcnt vmcnt(" #n ")" ::: "memory")
; #define PG8_WAIT_L(n) asm volatile("s_waitcnt lgkmcnt(" #n ")" ::: "memory")
; template <class Epi>
; DI void gemm_phase(LAS unsigned char* lds, const Gemm g, const StaticOrder& S, const Epi& E) {
;     ...
;             PG8_BAR; PG8_WAIT_L(0); PG8_MMA(1, 0, At, B0); PG8_BAR; PG8_SCHED;
;             PG8_STAGE(PG8_SB(1, 1), b3 + hstep);
;             PG8_WAIT_V(6); PG8_BAR; PG8_MMA(1, 1, At, B1); PG8_BAR;
;     template <bool LN, int BJ, int LO, int HI> DI void batch(const f32x4 (&acc)[2][2][4][2], unsigned row0, unsigned col0, const f32x4 (&gv)[2], const f32x4 (&bv)[2]) const {
;         f32x4 r[HI - LO]; float mean[(HI - LO) / 2], rstd[(HI - LO) / 2];
; #pragma unroll
;         for (int i = LO; i < HI; ++i) { const int ai = i >> 3, m = (i >> 1) & 3, n = i & 1; const unsigned row = row0 + ai * HALF + m * 16;
;             if (n == 0) { mean[(i - LO) >> 1] = 0.f; rstd[(i - LO) >> 1] = 1.f;
;                 if (LN) { const float2 st = *(const float2*)(stats + row * 2u); mean[(i - LO) >> 1] = st.x; rstd[(i - LO) >> 1] = st.y; } }
;             r[i - LO] = *(const f32x4*)(src + (row * (unsigned)DM + col0 + BJ * HALF + n * 16)); }
; #pragma unroll
;         for (int i = LO; i < HI; ++i) { const int ai = i >> 3, m = (i >> 1) & 3, n = i & 1; const unsigned row = row0 + ai * HALF + m * 16;
;             *(f32x4*)(Y + (row * (unsigned)DM + col0 + BJ * HALF + n * 16)) = acc[ai][BJ][m][n] + ((r[i - LO] - mean[(i - LO) >> 1]) * rstd[(i - LO) >> 1]) * gv[n] + bv[n]; }
;         __builtin_amdgcn_sched_barrier(0);
;     }
;     template <bool LN, int BJ> DI void load_gb(unsigned col0, f32x4 (&gv)[2], f32x4 (&bv)[2]) const {
; #pragma unroll
;         for (int n = 0; n < 2; ++n) {
;             if (LN) { gv[n] = *(const f32x4*)(gam + col0 + BJ * HALF + n * 16) * ALPHA; bv[n] = *(const f32x4*)(bet + col0 + BJ * HALF + n * 16) * ALPHA; }
;             else { gv[n] = (f32x4){ALPHA, ALPHA, ALPHA, ALPHA}; bv[n] = (f32x4){0.f, 0.f, 0.f, 0.f}; }
;         }
;     }
;     template <bool LN> DI void run(const f32x4 (&acc)[2][2][4][2], const Unit& u, int wr, int wc, int fr, int fq) const {
;         const unsigned row0 = u.pm * BM + wr * 64 + fr, col0 = u.pn * BM + wc * 32 + 4 * fq;
;         f32x4 gv[2], bv[2];
;         load_gb<LN, 0>(col0, gv, bv);
;         batch<LN, 0, 0, 4>(acc, row0, col0, gv, bv);
	v_mfma_f32_16x16x32_bf16 v[92:95], v[128:131], v[144:147], v[92:95]
	v_mfma_f32_16x16x32_bf16 v[88:91], v[136:139], v[144:147], v[88:91]
	v_mfma_f32_16x16x32_bf16 v[84:87], v[128:131], v[152:155], v[84:87]
	v_mfma_f32_16x16x32_bf16 v[80:83], v[136:139], v[152:155], v[80:83]
	v_mfma_f32_16x16x32_bf16 v[76:79], v[128:131], v[198:201], v[76:79]
	v_mfma_f32_16x16x32_bf16 v[72:75], v[136:139], v[198:201], v[72:75]
	v_mfma_f32_16x16x32_bf16 v[68:71], v[128:131], v[206:209], v[68:71]
	v_mfma_f32_16x16x32_bf16 v[64:67], v[136:139], v[206:209], v[64:67]
	v_mfma_f32_16x16x32_bf16 v[92:95], v[132:135], v[148:151], v[92:95]
	v_mfma_f32_16x16x32_bf16 v[88:91], v[140:143], v[148:151], v[88:91]
	v_mfma_f32_16x16x32_bf16 v[84:87], v[132:135], v[194:197], v[84:87]
	v_mfma_f32_16x16x32_bf16 v[80:83], v[140:143], v[194:197], v[80:83]
	v_mfma_f32_16x16x32_bf16 v[76:79], v[132:135], v[202:205], v[76:79]
	v_mfma_f32_16x16x32_bf16 v[72:75], v[140:143], v[202:205], v[72:75]
	v_mfma_f32_16x16x32_bf16 v[68:71], v[132:135], v[210:213], v[68:71]
	s_setprio 0
	v_mfma_f32_16x16x32_bf16 v[64:67], v[140:143], v[210:213], v[64:67]
	s_barrier
	s_add_u32 s20, s24, 0x90080
	s_addc_u32 s21, s25, 0
	s_add_i32 s24, s26, s31
	s_mov_b32 m0, s24
	s_nop 0
	global_load_lds_dwordx4 v188, s[20:21]
	s_add_i32 m0, s24, 0x2000
	s_nop 0
	global_load_lds_dwordx4 v186, s[20:21]
	s_waitcnt vmcnt(6)
	s_setprio 1
	s_barrier
	v_mfma_f32_16x16x32_bf16 v[28:31], v[214:217], v[144:147], v[28:31]
	v_mfma_f32_16x16x32_bf16 v[24:27], v[234:237], v[144:147], v[24:27]
	v_mfma_f32_16x16x32_bf16 v[20:23], v[214:217], v[152:155], v[20:23]
	v_mfma_f32_16x16x32_bf16 v[16:19], v[234:237], v[152:155], v[16:19]
	v_mfma_f32_16x16x32_bf16 v[12:15], v[214:217], v[198:201], v[12:15]
	v_mfma_f32_16x16x32_bf16 v[8:11], v[234:237], v[198:201], v[8:11]
	v_mfma_f32_16x16x32_bf16 v[4:7], v[214:217], v[206:209], v[4:7]
	v_mfma_f32_16x16x32_bf16 v[0:3], v[234:237], v[206:209], v[0:3]
	v_mfma_f32_16x16x32_bf16 v[28:31], v[230:233], v[148:151], v[28:31]
	s_add_i32 s33, s33, 2
	v_mfma_f32_16x16x32_bf16 v[24:27], v[238:241], v[148:151], v[24:27]
	s_add_u32 s4, s4, 0x100
	v_mfma_f32_16x16x32_bf16 v[20:23], v[230:233], v[194:197], v[20:23]
	s_addc_u32 s5, s5, 0
	v_mfma_f32_16x16x32_bf16 v[16:19], v[238:241], v[194:197], v[16:19]
	s_cmp_gt_u32 s33, 33
	v_mfma_f32_16x16x32_bf16 v[12:15], v[230:233], v[202:205], v[12:15]
	s_mov_b64 s[20:21], s[22:23]
	v_mfma_f32_16x16x32_bf16 v[8:11], v[238:241], v[202:205], v[8:11]
	v_mfma_f32_16x16x32_bf16 v[4:7], v[230:233], v[210:213], v[4:7]
	s_setprio 0
	v_mfma_f32_16x16x32_bf16 v[0:3], v[238:241], v[210:213], v[0:3]
	s_barrier
	s_cbranch_scc0 .LBB0_77
	v_lshl_add_u32 v206, s3, 8, v225
	v_lshl_or_b32 v158, s2, 8, v227
	v_lshlrev_b32_e32 v232, 11, v206
	s_andn2_b64 vcc, exec, s[14:15]
	v_or_b32_e32 v231, 16, v158
	v_add_u32_e32 v194, v232, v158
	v_or_b32_e32 v230, 0x80, v158
	v_or_b32_e32 v229, 0x90, v158
	s_cbranch_vccnz .LBB0_80
	v_lshlrev_b64 v[132:133], 2, v[158:159]
	v_lshl_add_u64 v[140:141], s[16:17], 0, v[132:133]
	global_load_dwordx4 v[128:131], v[140:141], off
	v_lshl_add_u64 v[142:143], s[18:19], 0, v[132:133]
	v_readlane_b32 s2, v253, 8
	v_mov_b32_e32 v195, v159
	v_lshlrev_b32_e32 v136, 1, v206
	v_mov_b32_e32 v137, v159
	v_readlane_b32 s3, v253, 9
	v_lshlrev_b64 v[212:213], 2, v[194:195]
	v_add_u32_e32 v146, v232, v231
	v_lshl_add_u64 v[144:145], v[136:137], 2, s[2:3]
	v_lshl_add_u64 v[136:137], s[88:89], 0, v[212:213]
	v_mov_b32_e32 v147, v159
	v_lshl_add_u64 v[146:147], v[146:147], 2, s[88:89]
	v_or_b32_e32 v195, 16, v206
	v_mov_b32_e32 v201, v159
	v_mov_b32_e32 v209, v159
	v_lshl_add_u64 v[212:213], s[90:91], 0, v[212:213]
	s_waitcnt vmcnt(0)
	v_pk_mul_f32 v[152:153], v[130:131], s[78:79] op_sel_hi:[1,0]
	v_pk_mul_f32 v[154:155], v[128:129], s[78:79] op_sel_hi:[1,0]
	global_load_dwordx4 v[132:135], v[142:143], off
	global_load_dwordx4 v[128:131], v[140:141], off offset:64
	global_load_dwordx2 v[204:205], v[144:145], off
	global_load_dwordx4 v[196:199], v[146:147], off
	v_lshlrev_b32_e32 v146, 1, v195
	global_load_dwordx4 v[136:139], v[136:137], off
	v_lshlrev_b32_e32 v195, 11, v195
	v_mov_b32_e32 v147, v159
	v_add_u32_e32 v200, v195, v158
	v_lshl_add_u64 v[146:147], v[146:147], 2, s[2:3]
	v_lshl_add_u64 v[200:201], v[200:201], 2, s[88:89]
	global_load_dwordx2 v[214:215], v[146:147], off
	v_add_u32_e32 v208, v195, v231
	global_load_dwordx4 v[200:203], v[200:201], off
	v_lshl_add_u64 v[208:209], v[208:209], 2, s[88:89]
	global_load_dwordx4 v[208:211], v[208:209], off
	s_waitcnt vmcnt(0)
	v_pk_mul_f32 v[148:149], v[130:131], s[78:79] op_sel_hi:[1,0]
	v_pk_mul_f32 v[150:151], v[128:129], s[78:79] op_sel_hi:[1,0]
	global_load_dwordx4 v[128:131], v[142:143], off offset:64
	v_sub_f32_e32 v137, v137, v204
	v_sub_f32_e32 v136, v136, v204
	v_sub_f32_e32 v139, v139, v204
	v_sub_f32_e32 v138, v138, v204
	v_pk_mul_f32 v[138:139], v[204:205], v[138:139] op_sel:[1,0]
	v_pk_mul_f32 v[136:137], v[204:205], v[136:137] op_sel:[1,0]
	v_pk_fma_f32 v[138:139], v[152:153], v[138:139], v[126:127]
	v_pk_fma_f32 v[136:137], v[154:155], v[136:137], v[124:125]
	v_pk_fma_f32 v[138:139], v[134:135], s[78:79], v[138:139] op_sel_hi:[1,0,1]
	v_pk_fma_f32 v[136:137], v[132:133], s[78:79], v[136:137] op_sel_hi:[1,0,1]
	global_store_dwordx4 v[212:213], v[136:139], off
	s_nop 1
	v_sub_f32_e32 v137, v197, v204
	v_sub_f32_e32 v136, v196, v204
	v_sub_f32_e32 v139, v199, v204
	v_sub_f32_e32 v138, v198, v204
	v_pk_mul_f32 v[138:139], v[204:205], v[138:139] op_sel:[1,0]
	v_pk_mul_f32 v[136:137], v[204:205], v[136:137] op_sel:[1,0]
	v_pk_fma_f32 v[138:139], v[148:149], v[138:139], v[122:123]
	v_pk_fma_f32 v[136:137], v[150:151], v[136:137], v[120:121]
	v_or_b32_e32 v196, 16, v194
	v_mov_b32_e32 v197, v159
	v_lshl_add_u64 v[196:197], v[196:197], 2, s[90:91]
	s_waitcnt vmcnt(0)
;     template <bool LN, int BJ, int LO, int HI> DI void batch(const f32x4 (&acc)[2][2][4][2], unsigned row0, unsigned col0, const f32x4 (&gv)[2], const f32x4 (&bv)[2]) const {
;         f32x4 r[HI - LO]; float mean[(HI - LO) / 2], rstd[(HI - LO) / 2];
; #pragma unroll
;         for (int i = LO; i < HI; ++i) { const int ai = i >> 3, m = (i >> 1) & 3, n = i & 1; const unsigned row = row0 + ai * HALF + m * 16;
;             if (n == 0) { mean[(i - LO) >> 1] = 0.f; rstd[(i - LO) >> 1] = 1.f;
;                 if (LN) { const float2 st = *(const float2*)(stats + row * 2u); mean[(i - LO) >> 1] = st.x; rstd[(i - LO) >> 1] = st.y; } }
;             r[i - LO] = *(const f32x4*)(src + (row * (unsigned)DM + col0 + BJ * HALF + n * 16)); }
; #pragma unroll
;         for (int i = LO; i < HI; ++i) { const int ai = i >> 3, m = (i >> 1) & 3, n = i & 1; const unsigned row = row0 + ai * HALF + m * 16;
;             *(f32x4*)(Y + (row * (unsigned)DM + col0 + BJ * HALF + n * 16)) = acc[ai][BJ][m][n] + ((r[i - LO] - mean[(i - LO) >> 1]) * rstd[(i - LO) >> 1]) * gv[n] + bv[n]; }
	v_pk_fma_f32 v[138:139], v[130:131], s[78:79], v[138:139] op_sel_hi:[1,0,1]
	v_pk_fma_f32 v[136:137], v[128:129], s[78:79], v[136:137] op_sel_hi:[1,0,1]
	global_store_dwordx4 v[196:197], v[136:139], off
	v_add_u32_e32 v196, 0x8000, v194
	v_mov_b32_e32 v197, v159
	v_sub_f32_e32 v137, v201, v214
	v_sub_f32_e32 v136, v200, v214
	v_sub_f32_e32 v139, v203, v214
	v_sub_f32_e32 v138, v202, v214
	v_pk_mul_f32 v[138:139], v[214:215], v[138:139] op_sel:[1,0]
	v_pk_mul_f32 v[136:137], v[214:215], v[136:137] op_sel:[1,0]
	v_pk_fma_f32 v[138:139], v[152:153], v[138:139], v[118:119]
	v_pk_fma_f32 v[136:137], v[154:155], v[136:137], v[116:117]
	v_pk_fma_f32 v[138:139], v[134:135], s[78:79], v[138:139] op_sel_hi:[1,0,1]
	v_pk_fma_f32 v[136:137], v[132:133], s[78:79], v[136:137] op_sel_hi:[1,0,1]
	v_lshl_add_u64 v[196:197], v[196:197], 2, s[90:91]
	global_store_dwordx4 v[196:197], v[136:139], off
	v_add_u32_e32 v196, 0x8010, v194
	v_mov_b32_e32 v197, v159
	v_sub_f32_e32 v137, v209, v214
	v_sub_f32_e32 v136, v208, v214
	v_sub_f32_e32 v139, v211, v214
	v_sub_f32_e32 v138, v210, v214
	v_pk_mul_f32 v[138:139], v[214:215], v[138:139] op_sel:[1,0]
	v_pk_mul_f32 v[136:137], v[214:215], v[136:137] op_sel:[1,0]
	v_pk_fma_f32 v[138:139], v[148:149], v[138:139], v[114:115]
	v_pk_fma_f32 v[136:137], v[150:151], v[136:137], v[112:113]
	v_pk_fma_f32 v[138:139], v[130:131], s[78:79], v[138:139] op_sel_hi:[1,0,1]
	v_pk_fma_f32 v[136:137], v[128:129], s[78:79], v[136:137] op_sel_hi:[1,0,1]
	v_lshl_add_u64 v[196:197], v[196:197], 2, s[90:91]
	global_store_dwordx4 v[196:197], v[136:139], off
	s_nop 1
	v_or_b32_e32 v138, 32, v206
	v_lshlrev_b32_e32 v136, 1, v138
	v_mov_b32_e32 v137, v159
	v_lshlrev_b32_e32 v236, 11, v138
	v_lshl_add_u64 v[200:201], v[136:137], 2, s[2:3]
	v_add_u32_e32 v136, v236, v158
	v_lshl_add_u64 v[136:137], v[136:137], 2, s[88:89]
	global_load_dwordx2 v[204:205], v[200:201], off
	v_add_u32_e32 v196, v236, v231
	global_load_dwordx4 v[136:139], v[136:137], off
	v_mov_b32_e32 v197, v159
	v_lshl_add_u64 v[196:197], v[196:197], 2, s[88:89]
	global_load_dwordx4 v[196:199], v[196:197], off
	v_or_b32_e32 v207, 48, v206
	v_lshlrev_b32_e32 v235, 11, v207
	v_lshlrev_b32_e32 v202, 1, v207
	v_mov_b32_e32 v203, v159
	v_add_u32_e32 v208, v235, v158
	v_mov_b32_e32 v209, v159
	v_lshl_add_u64 v[202:203], v[202:203], 2, s[2:3]
	v_lshl_add_u64 v[208:209], v[208:209], 2, s[88:89]
	global_load_dwordx2 v[216:217], v[202:203], off
	v_add_u32_e32 v212, v235, v231
	global_load_dwordx4 v[208:211], v[208:209], off
	v_mov_b32_e32 v213, v159
	v_lshl_add_u64 v[212:213], v[212:213], 2, s[88:89]
	global_load_dwordx4 v[212:215], v[212:213], off
	v_add_u32_e32 v218, 0x10000, v194
	v_mov_b32_e32 v219, v159
	v_lshl_add_u64 v[218:219], v[218:219], 2, s[90:91]
	s_waitcnt vmcnt(0)
	v_sub_f32_e32 v137, v137, v204
	v_sub_f32_e32 v136, v136, v204
	v_sub_f32_e32 v139, v139, v204
	v_sub_f32_e32 v138, v138, v204
	v_pk_mul_f32 v[138:139], v[204:205], v[138:139] op_sel:[1,0]
	v_pk_mul_f32 v[136:137], v[204:205], v[136:137] op_sel:[1,0]
	v_pk_fma_f32 v[138:139], v[152:153], v[138:139], v[110:111]
	v_pk_fma_f32 v[136:137], v[154:155], v[136:137], v[108:109]
	v_pk_fma_f32 v[138:139], v[134:135], s[78:79], v[138:139] op_sel_hi:[1,0,1]
	v_pk_fma_f32 v[136:137], v[132:133], s[78:79], v[136:137] op_sel_hi:[1,0,1]
	global_store_dwordx4 v[218:219], v[136:139], off
	s_nop 1
	v_sub_f32_e32 v137, v197, v204
	v_sub_f32_e32 v136, v196, v204
	v_sub_f32_e32 v139, v199, v204
	v_sub_f32_e32 v138, v198, v204
	v_pk_mul_f32 v[138:139], v[204:205], v[138:139] op_sel:[1,0]
	v_pk_mul_f32 v[136:137], v[204:205], v[136:137] op_sel:[1,0]
	v_pk_fma_f32 v[138:139], v[148:149], v[138:139], v[106:107]
	v_pk_fma_f32 v[136:137], v[150:151], v[136:137], v[104:105]
	v_add_u32_e32 v196, 0x10010, v194
	v_mov_b32_e32 v197, v159
	v_pk_fma_f32 v[138:139], v[130:131], s[78:79], v[138:139] op_sel_hi:[1,0,1]
	v_pk_fma_f32 v[136:137], v[128:129], s[78:79], v[136:137] op_sel_hi:[1,0,1]
	v_lshl_add_u64 v[196:197], v[196:197], 2, s[90:91]
	global_store_dwordx4 v[196:197], v[136:139], off
	v_add_u32_e32 v196, 0x18000, v194
	v_mov_b32_e32 v197, v159
	v_sub_f32_e32 v137, v209, v216
	v_sub_f32_e32 v136, v208, v216
	v_sub_f32_e32 v139, v211, v216
	v_sub_f32_e32 v138, v210, v216
	v_pk_mul_f32 v[138:139], v[216:217], v[138:139] op_sel:[1,0]
	v_pk_mul_f32 v[136:137], v[216:217], v[136:137] op_sel:[1,0]
	v_pk_fma_f32 v[138:139], v[152:153], v[138:139], v[102:103]
	v_pk_fma_f32 v[136:137], v[154:155], v[136:137], v[100:101]
	v_pk_fma_f32 v[138:139], v[134:135], s[78:79], v[138:139] op_sel_hi:[1,0,1]
	v_pk_fma_f32 v[136:137], v[132:133], s[78:79], v[136:137] op_sel_hi:[1,0,1]
	v_lshl_add_u64 v[196:197], v[196:197], 2, s[90:91]
	global_store_dwordx4 v[196:197], v[136:139], off
	v_add_u32_e32 v196, 0x18010, v194
	v_mov_b32_e32 v197, v159
	v_sub_f32_e32 v137, v213, v216
	v_sub_f32_e32 v136, v212, v216
	v_sub_f32_e32 v139, v215, v216
	v_sub_f32_e32 v138, v214, v216
	v_pk_mul_f32 v[138:139], v[216:217], v[138:139] op_sel:[1,0]
	v_pk_mul_f32 v[136:137], v[216:217], v[136:137] op_sel:[1,0]
	v_pk_fma_f32 v[138:139], v[148:149], v[138:139], v[98:99]
	v_pk_fma_f32 v[136:137], v[150:151], v[136:137], v[96:97]
	v_pk_fma_f32 v[138:139], v[130:131], s[78:79], v[138:139] op_sel_hi:[1,0,1]
	v_pk_fma_f32 v[136:137], v[128:129], s[78:79], v[136:137] op_sel_hi:[1,0,1]
	v_lshl_add_u64 v[196:197], v[196:197], 2, s[90:91]
	global_store_dwordx4 v[196:197], v[136:139], off
	s_nop 1
	v_add_u32_e32 v138, 0x80, v206
	v_lshlrev_b32_e32 v136, 1, v138
	v_mov_b32_e32 v137, v159
	v_lshlrev_b32_e32 v233, 11, v138
	v_lshl_add_u64 v[196:197], v[136:137], 2, s[2:3]
	v_add_u32_e32 v136, v233, v158
	v_lshl_add_u64 v[136:137], v[136:137], 2, s[88:89]
	global_load_dwordx2 v[204:205], v[196:197], off
	v_add_u32_e32 v198, v233, v231
	global_load_dwordx4 v[136:139], v[136:137], off
	v_mov_b32_e32 v199, v159
	v_add_u32_e32 v207, 0x90, v206
	v_lshl_add_u64 v[198:199], v[198:199], 2, s[88:89]
	v_lshlrev_b32_e32 v234, 11, v207
	global_load_dwordx4 v[208:211], v[198:199], off
	v_add_u32_e32 v212, v234, v158
	v_mov_b32_e32 v213, v159
	v_lshl_add_u64 v[212:213], v[212:213], 2, s[88:89]
	global_load_dwordx4 v[212:215], v[212:213], off
	v_lshlrev_b32_e32 v198, 1, v207
	v_mov_b32_e32 v199, v159
	v_lshl_add_u64 v[198:199], v[198:199], 2, s[2:3]
	global_load_dwordx2 v[220:221], v[198:199], off
	v_add_u32_e32 v216, v234, v231
	v_mov_b32_e32 v217, v159
	v_lshl_add_u64 v[216:217], v[216:217], 2, s[88:89]
	global_load_dwordx4 v[216:219], v[216:217], off
	v_add_u32_e32 v238, 0x40000, v194
	v_mov_b32_e32 v239, v159
	v_lshl_add_u64 v[238:239], v[238:239], 2, s[90:91]
	s_waitcnt vmcnt(0)
;     template <bool LN, int BJ, int LO, int HI> DI void batch(const f32x4 (&acc)[2][2][4][2], unsigned row0, unsigned col0, const f32x4 (&gv)[2], const f32x4 (&bv)[2]) const {
;         f32x4 r[HI - LO]; float mean[(HI - LO) / 2], rstd[(HI - LO) / 2];
; #pragma unroll
;         for (int i = LO; i < HI; ++i) { const int ai = i >> 3, m = (i >> 1) & 3, n = i & 1; const unsigned row = row0 + ai * HALF + m * 16;
;             if (n == 0) { mean[(i - LO) >> 1] = 0.f; rstd[(i - LO) >> 1] = 1.f;
;                 if (LN) { const float2 st = *(const float2*)(stats + row * 2u); mean[(i - LO) >> 1] = st.x; rstd[(i - LO) >> 1] = st.y; } }
;             r[i - LO] = *(const f32x4*)(src + (row * (unsigned)DM + col0 + BJ * HALF + n * 16)); }
; #pragma unroll
;         for (int i = LO; i < HI; ++i) { const int ai = i >> 3, m = (i >> 1) & 3, n = i & 1; const unsigned row = row0 + ai * HALF + m * 16;
;             *(f32x4*)(Y + (row * (unsigned)DM + col0 + BJ * HALF + n * 16)) = acc[ai][BJ][m][n] + ((r[i - LO] - mean[(i - LO) >> 1]) * rstd[(i - LO) >> 1]) * gv[n] + bv[n]; }
	v_sub_f32_e32 v137, v137, v204
	v_sub_f32_e32 v136, v136, v204
	v_sub_f32_e32 v139, v139, v204
	v_sub_f32_e32 v138, v138, v204
	v_pk_mul_f32 v[138:139], v[204:205], v[138:139] op_sel:[1,0]
	v_pk_mul_f32 v[136:137], v[204:205], v[136:137] op_sel:[1,0]
	v_pk_fma_f32 v[138:139], v[152:153], v[138:139], v[94:95]
	v_pk_fma_f32 v[136:137], v[154:155], v[136:137], v[92:93]
	v_pk_fma_f32 v[138:139], v[134:135], s[78:79], v[138:139] op_sel_hi:[1,0,1]
	v_pk_fma_f32 v[136:137], v[132:133], s[78:79], v[136:137] op_sel_hi:[1,0,1]
	global_store_dwordx4 v[238:239], v[136:139], off
	s_nop 1
	v_sub_f32_e32 v137, v209, v204
	v_sub_f32_e32 v136, v208, v204
	v_sub_f32_e32 v139, v211, v204
	v_sub_f32_e32 v138, v210, v204
	v_pk_mul_f32 v[138:139], v[204:205], v[138:139] op_sel:[1,0]
	v_pk_mul_f32 v[136:137], v[204:205], v[136:137] op_sel:[1,0]
	v_pk_fma_f32 v[138:139], v[148:149], v[138:139], v[90:91]
	v_pk_fma_f32 v[136:137], v[150:151], v[136:137], v[88:89]
	v_add_u32_e32 v204, 0x40010, v194
	v_mov_b32_e32 v205, v159
	v_pk_fma_f32 v[138:139], v[130:131], s[78:79], v[138:139] op_sel_hi:[1,0,1]
	v_pk_fma_f32 v[136:137], v[128:129], s[78:79], v[136:137] op_sel_hi:[1,0,1]
	v_lshl_add_u64 v[204:205], v[204:205], 2, s[90:91]
	global_store_dwordx4 v[204:205], v[136:139], off
	v_add_u32_e32 v204, 0x48000, v194
	v_mov_b32_e32 v205, v159
	v_sub_f32_e32 v137, v213, v220
	v_sub_f32_e32 v136, v212, v220
	v_sub_f32_e32 v139, v215, v220
	v_sub_f32_e32 v138, v214, v220
	v_pk_mul_f32 v[138:139], v[220:221], v[138:139] op_sel:[1,0]
	v_pk_mul_f32 v[136:137], v[220:221], v[136:137] op_sel:[1,0]
	v_pk_fma_f32 v[138:139], v[152:153], v[138:139], v[86:87]
	v_pk_fma_f32 v[136:137], v[154:155], v[136:137], v[84:85]
	v_pk_fma_f32 v[138:139], v[134:135], s[78:79], v[138:139] op_sel_hi:[1,0,1]
	v_pk_fma_f32 v[136:137], v[132:133], s[78:79], v[136:137] op_sel_hi:[1,0,1]
	v_lshl_add_u64 v[204:205], v[204:205], 2, s[90:91]
	global_store_dwordx4 v[204:205], v[136:139], off
	v_add_u32_e32 v204, 0x48010, v194
	v_mov_b32_e32 v205, v159
	v_sub_f32_e32 v137, v217, v220
	v_sub_f32_e32 v136, v216, v220
	v_sub_f32_e32 v139, v219, v220
	v_sub_f32_e32 v138, v218, v220
	v_pk_mul_f32 v[138:139], v[220:221], v[138:139] op_sel:[1,0]
	v_pk_mul_f32 v[136:137], v[220:221], v[136:137] op_sel:[1,0]
	v_pk_fma_f32 v[138:139], v[148:149], v[138:139], v[82:83]
	v_pk_fma_f32 v[136:137], v[150:151], v[136:137], v[80:81]
	v_pk_fma_f32 v[138:139], v[130:131], s[78:79], v[138:139] op_sel_hi:[1,0,1]
	v_pk_fma_f32 v[136:137], v[128:129], s[78:79], v[136:137] op_sel_hi:[1,0,1]
	v_lshl_add_u64 v[204:205], v[204:205], 2, s[90:91]
	global_store_dwordx4 v[204:205], v[136:139], off
	s_nop 1
	v_add_u32_e32 v138, 0xa0, v206
	v_lshlrev_b32_e32 v136, 1, v138
	v_mov_b32_e32 v137, v159
	v_lshlrev_b32_e32 v237, 11, v138
	v_lshl_add_u64 v[204:205], v[136:137], 2, s[2:3]
	v_add_u32_e32 v136, v237, v158
	v_lshl_add_u64 v[136:137], v[136:137], 2, s[88:89]
	global_load_dwordx2 v[220:221], v[204:205], off
	v_add_u32_e32 v208, v237, v231
	global_load_dwordx4 v[136:139], v[136:137], off
	v_mov_b32_e32 v209, v159
	v_lshl_add_u64 v[208:209], v[208:209], 2, s[88:89]
	global_load_dwordx4 v[212:215], v[208:209], off
	v_add_u32_e32 v208, 0xb0, v206
	v_lshlrev_b32_e32 v206, 1, v208
	v_mov_b32_e32 v207, v159
	v_lshlrev_b32_e32 v238, 11, v208
	v_lshl_add_u64 v[210:211], v[206:207], 2, s[2:3]
	v_add_u32_e32 v206, v238, v158
	v_lshl_add_u64 v[206:207], v[206:207], 2, s[88:89]
	global_load_dwordx2 v[240:241], v[210:211], off
	v_add_u32_e32 v216, v238, v231
	global_load_dwordx4 v[206:209], v[206:207], off
	v_mov_b32_e32 v217, v159
	v_lshl_add_u64 v[216:217], v[216:217], 2, s[88:89]
	global_load_dwordx4 v[216:219], v[216:217], off
	v_add_u32_e32 v242, 0x50000, v194
	v_mov_b32_e32 v243, v159
	v_lshl_add_u64 v[242:243], v[242:243], 2, s[90:91]
	s_waitcnt vmcnt(0)
	v_sub_f32_e32 v137, v137, v220
	v_sub_f32_e32 v136, v136, v220
	v_sub_f32_e32 v139, v139, v220
	v_sub_f32_e32 v138, v138, v220
	v_pk_mul_f32 v[138:139], v[220:221], v[138:139] op_sel:[1,0]
	v_pk_mul_f32 v[136:137], v[220:221], v[136:137] op_sel:[1,0]
	v_pk_fma_f32 v[138:139], v[152:153], v[138:139], v[78:79]
	v_pk_fma_f32 v[136:137], v[154:155], v[136:137], v[76:77]
	v_pk_fma_f32 v[138:139], v[134:135], s[78:79], v[138:139] op_sel_hi:[1,0,1]
	v_pk_fma_f32 v[136:137], v[132:133], s[78:79], v[136:137] op_sel_hi:[1,0,1]
	global_store_dwordx4 v[242:243], v[136:139], off
	s_nop 1
	v_sub_f32_e32 v137, v213, v220
	v_sub_f32_e32 v136, v212, v220
	v_sub_f32_e32 v139, v215, v220
	v_sub_f32_e32 v138, v214, v220
	v_pk_mul_f32 v[138:139], v[220:221], v[138:139] op_sel:[1,0]
	v_pk_mul_f32 v[136:137], v[220:221], v[136:137] op_sel:[1,0]
	v_pk_fma_f32 v[138:139], v[148:149], v[138:139], v[74:75]
	v_pk_fma_f32 v[136:137], v[150:151], v[136:137], v[72:73]
	v_add_u32_e32 v212, 0x50010, v194
	v_mov_b32_e32 v213, v159
	v_pk_fma_f32 v[138:139], v[130:131], s[78:79], v[138:139] op_sel_hi:[1,0,1]
	v_pk_fma_f32 v[136:137], v[128:129], s[78:79], v[136:137] op_sel_hi:[1,0,1]
	v_lshl_add_u64 v[212:213], v[212:213], 2, s[90:91]
	global_store_dwordx4 v[212:213], v[136:139], off
	s_nop 1
	v_sub_f32_e32 v137, v207, v240
	v_sub_f32_e32 v136, v206, v240
	v_sub_f32_e32 v139, v209, v240
	v_sub_f32_e32 v138, v208, v240
	v_pk_mul_f32 v[136:137], v[240:241], v[136:137] op_sel:[1,0]
	v_pk_mul_f32 v[138:139], v[240:241], v[138:139] op_sel:[1,0]
	v_pk_fma_f32 v[136:137], v[154:155], v[136:137], v[68:69]
	v_pk_fma_f32 v[138:139], v[152:153], v[138:139], v[70:71]
	v_pk_fma_f32 v[132:133], v[132:133], s[78:79], v[136:137] op_sel_hi:[1,0,1]
	v_add_u32_e32 v136, 0x58000, v194
	v_mov_b32_e32 v137, v159
	v_pk_fma_f32 v[134:135], v[134:135], s[78:79], v[138:139] op_sel_hi:[1,0,1]
	v_lshl_add_u64 v[136:137], v[136:137], 2, s[90:91]
	global_store_dwordx4 v[136:137], v[132:135], off
	s_nop 1
	v_sub_f32_e32 v133, v217, v240
	v_sub_f32_e32 v132, v216, v240
	v_sub_f32_e32 v135, v219, v240
	v_sub_f32_e32 v134, v218, v240
	v_pk_mul_f32 v[132:133], v[240:241], v[132:133] op_sel:[1,0]
	v_pk_mul_f32 v[134:135], v[240:241], v[134:135] op_sel:[1,0]
	v_pk_fma_f32 v[132:133], v[150:151], v[132:133], v[64:65]
	v_pk_fma_f32 v[134:135], v[148:149], v[134:135], v[66:67]
	v_pk_fma_f32 v[128:129], v[128:129], s[78:79], v[132:133] op_sel_hi:[1,0,1]
	v_add_u32_e32 v132, 0x58010, v194
	v_mov_b32_e32 v133, v159
	v_pk_fma_f32 v[130:131], v[130:131], s[78:79], v[134:135] op_sel_hi:[1,0,1]
	v_lshl_add_u64 v[132:133], v[132:133], 2, s[90:91]
	global_store_dwordx4 v[132:133], v[128:131], off
	global_load_dwordx4 v[128:131], v[140:141], off offset:512
	v_add_u32_e32 v136, v232, v230
	v_mov_b32_e32 v137, v159
	v_lshl_add_u64 v[136:137], v[136:137], 2, s[88:89]
	s_waitcnt vmcnt(0)
;     template <bool LN, int BJ, int LO, int HI> DI void batch(const f32x4 (&acc)[2][2][4][2], unsigned row0, unsigned col0, const f32x4 (&gv)[2], const f32x4 (&bv)[2]) const {
;         f32x4 r[HI - LO]; float mean[(HI - LO) / 2], rstd[(HI - LO) / 2];
; #pragma unroll
;         for (int i = LO; i < HI; ++i) { const int ai = i >> 3, m = (i >> 1) & 3, n = i & 1; const unsigned row = row0 + ai * HALF + m * 16;
;             if (n == 0) { mean[(i - LO) >> 1] = 0.f; rstd[(i - LO) >> 1] = 1.f;
;                 if (LN) { const float2 st = *(const float2*)(stats + row * 2u); mean[(i - LO) >> 1] = st.x; rstd[(i - LO) >> 1] = st.y; } }
;             r[i - LO] = *(const f32x4*)(src + (row * (unsigned)DM + col0 + BJ * HALF + n * 16)); }
; #pragma unroll
;         for (int i = LO; i < HI; ++i) { const int ai = i >> 3, m = (i >> 1) & 3, n = i & 1; const unsigned row = row0 + ai * HALF + m * 16;
;             *(f32x4*)(Y + (row * (unsigned)DM + col0 + BJ * HALF + n * 16)) = acc[ai][BJ][m][n] + ((r[i - LO] - mean[(i - LO) >> 1]) * rstd[(i - LO) >> 1]) * gv[n] + bv[n]; }
;         __builtin_amdgcn_sched_barrier(0);
;     }
;     template <bool LN, int BJ> DI void load_gb(unsigned col0, f32x4 (&gv)[2], f32x4 (&bv)[2]) const {
; #pragma unroll
;         for (int n = 0; n < 2; ++n) {
;             if (LN) { gv[n] = *(const f32x4*)(gam + col0 + BJ * HALF + n * 16) * ALPHA; bv[n] = *(const f32x4*)(bet + col0 + BJ * HALF + n * 16) * ALPHA; }
;             else { gv[n] = (f32x4){ALPHA, ALPHA, ALPHA, ALPHA}; bv[n] = (f32x4){0.f, 0.f, 0.f, 0.f}; }
;         }
;     }
;     template <bool LN> DI void run(const f32x4 (&acc)[2][2][4][2], const Unit& u, int wr, int wc, int fr, int fq) const {
;         const unsigned row0 = u.pm * BM + wr * 64 + fr, col0 = u.pn * BM + wc * 32 + 4 * fq;
;         f32x4 gv[2], bv[2];
;         load_gb<LN, 0>(col0, gv, bv);
;         batch<LN, 0, 0, 4>(acc, row0, col0, gv, bv);
;         batch<LN, 0, 4, 8>(acc, row0, col0, gv, bv);
;         batch<LN, 0, 8, 12>(acc, row0, col0, gv, bv);
;         batch<LN, 0, 12, 16>(acc, row0, col0, gv, bv);
;         load_gb<LN, 1>(col0, gv, bv);
;         batch<LN, 1, 0, 8>(acc, row0, col0, gv, bv);
	v_pk_mul_f32 v[212:213], v[130:131], s[78:79] op_sel_hi:[1,0]
	v_pk_mul_f32 v[214:215], v[128:129], s[78:79] op_sel_hi:[1,0]
	global_load_dwordx4 v[132:135], v[142:143], off offset:512
	global_load_dwordx4 v[128:131], v[140:141], off offset:576
	s_waitcnt vmcnt(0)
	v_pk_mul_f32 v[206:207], v[130:131], s[78:79] op_sel_hi:[1,0]
	v_pk_mul_f32 v[208:209], v[128:129], s[78:79] op_sel_hi:[1,0]
	global_load_dwordx4 v[128:131], v[142:143], off offset:576
	global_load_dwordx2 v[220:221], v[144:145], off
	global_load_dwordx4 v[240:243], v[136:137], off
	v_add_u32_e32 v136, v232, v229
	v_mov_b32_e32 v137, v159
	v_lshl_add_u64 v[136:137], v[136:137], 2, s[88:89]
	global_load_dwordx4 v[244:247], v[136:137], off
	global_load_dwordx2 v[218:219], v[146:147], off
	v_add_u32_e32 v136, v195, v230
	v_mov_b32_e32 v137, v159
	v_lshl_add_u64 v[136:137], v[136:137], 2, s[88:89]
	global_load_dwordx4 v[248:251], v[136:137], off
	v_add_u32_e32 v136, v195, v229
	v_mov_b32_e32 v137, v159
	v_lshl_add_u64 v[136:137], v[136:137], 2, s[88:89]
	global_load_dwordx4 v[152:155], v[136:137], off
	global_load_dwordx2 v[216:217], v[200:201], off
	v_add_u32_e32 v136, v236, v230
	v_mov_b32_e32 v137, v159
	v_lshl_add_u64 v[136:137], v[136:137], 2, s[88:89]
	global_load_dwordx4 v[148:151], v[136:137], off
	v_add_u32_e32 v136, v236, v229
	v_mov_b32_e32 v137, v159
	v_lshl_add_u64 v[136:137], v[136:137], 2, s[88:89]
	global_load_dwordx4 v[144:147], v[136:137], off
	global_load_dwordx2 v[200:201], v[202:203], off
	v_add_u32_e32 v136, v235, v230
	v_mov_b32_e32 v137, v159
	v_lshl_add_u64 v[136:137], v[136:137], 2, s[88:89]
	global_load_dwordx4 v[140:143], v[136:137], off
	v_add_u32_e32 v136, v235, v229
	v_mov_b32_e32 v137, v159
	v_lshl_add_u64 v[136:137], v[136:137], 2, s[88:89]
	global_load_dwordx4 v[136:139], v[136:137], off
	v_add_u32_e32 v202, 0x80, v194
	v_mov_b32_e32 v203, v159
	v_lshl_add_u64 v[202:203], v[202:203], 2, s[90:91]
	s_waitcnt vmcnt(0)
	v_sub_f32_e32 v241, v241, v220
	v_sub_f32_e32 v240, v240, v220
	v_sub_f32_e32 v243, v243, v220
	v_sub_f32_e32 v242, v242, v220
	v_pk_mul_f32 v[242:243], v[220:221], v[242:243] op_sel:[1,0]
	v_pk_mul_f32 v[240:241], v[220:221], v[240:241] op_sel:[1,0]
	v_pk_fma_f32 v[242:243], v[212:213], v[242:243], v[62:63]
	v_pk_fma_f32 v[240:241], v[214:215], v[240:241], v[60:61]
	v_pk_fma_f32 v[242:243], v[134:135], s[78:79], v[242:243] op_sel_hi:[1,0,1]
	v_pk_fma_f32 v[240:241], v[132:133], s[78:79], v[240:241] op_sel_hi:[1,0,1]
	global_store_dwordx4 v[202:203], v[240:243], off
	v_sub_f32_e32 v203, v245, v220
	v_sub_f32_e32 v202, v244, v220
	v_sub_f32_e32 v241, v247, v220
	v_sub_f32_e32 v240, v246, v220
	v_pk_mul_f32 v[202:203], v[220:221], v[202:203] op_sel:[1,0]
	v_pk_mul_f32 v[240:241], v[220:221], v[240:241] op_sel:[1,0]
	v_pk_fma_f32 v[202:203], v[208:209], v[202:203], v[56:57]
	v_pk_fma_f32 v[220:221], v[206:207], v[240:241], v[58:59]
	v_pk_fma_f32 v[240:241], v[128:129], s[78:79], v[202:203] op_sel_hi:[1,0,1]
	v_add_u32_e32 v202, 0x90, v194
	v_mov_b32_e32 v203, v159
	v_pk_fma_f32 v[242:243], v[130:131], s[78:79], v[220:221] op_sel_hi:[1,0,1]
	v_lshl_add_u64 v[202:203], v[202:203], 2, s[90:91]
	global_store_dwordx4 v[202:203], v[240:243], off
	v_sub_f32_e32 v203, v249, v218
	v_sub_f32_e32 v202, v248, v218
	v_sub_f32_e32 v221, v251, v218
	v_sub_f32_e32 v220, v250, v218
	v_pk_mul_f32 v[202:203], v[218:219], v[202:203] op_sel:[1,0]
	v_pk_mul_f32 v[220:221], v[218:219], v[220:221] op_sel:[1,0]
	v_pk_fma_f32 v[202:203], v[214:215], v[202:203], v[52:53]
	v_pk_fma_f32 v[220:221], v[212:213], v[220:221], v[54:55]
	v_pk_fma_f32 v[240:241], v[132:133], s[78:79], v[202:203] op_sel_hi:[1,0,1]
	v_add_u32_e32 v202, 0x8080, v194
	v_mov_b32_e32 v203, v159
	v_sub_f32_e32 v153, v153, v218
	v_sub_f32_e32 v152, v152, v218
	v_sub_f32_e32 v155, v155, v218
	v_sub_f32_e32 v154, v154, v218
	v_pk_fma_f32 v[242:243], v[134:135], s[78:79], v[220:221] op_sel_hi:[1,0,1]
	v_lshl_add_u64 v[202:203], v[202:203], 2, s[90:91]
	v_pk_mul_f32 v[154:155], v[218:219], v[154:155] op_sel:[1,0]
	v_pk_mul_f32 v[152:153], v[218:219], v[152:153] op_sel:[1,0]
	global_store_dwordx4 v[202:203], v[240:243], off
	v_pk_fma_f32 v[152:153], v[208:209], v[152:153], v[48:49]
	v_pk_fma_f32 v[154:155], v[206:207], v[154:155], v[50:51]
	v_add_u32_e32 v202, 0x8090, v194
	v_mov_b32_e32 v203, v159
	v_sub_f32_e32 v149, v149, v216
	v_sub_f32_e32 v148, v148, v216
	v_sub_f32_e32 v151, v151, v216
	v_sub_f32_e32 v150, v150, v216
	v_pk_fma_f32 v[154:155], v[130:131], s[78:79], v[154:155] op_sel_hi:[1,0,1]
	v_pk_fma_f32 v[152:153], v[128:129], s[78:79], v[152:153] op_sel_hi:[1,0,1]
	v_lshl_add_u64 v[202:203], v[202:203], 2, s[90:91]
	v_pk_mul_f32 v[150:151], v[216:217], v[150:151] op_sel:[1,0]
	v_pk_mul_f32 v[148:149], v[216:217], v[148:149] op_sel:[1,0]
	global_store_dwordx4 v[202:203], v[152:155], off
	v_pk_fma_f32 v[148:149], v[214:215], v[148:149], v[44:45]
	v_pk_fma_f32 v[150:151], v[212:213], v[150:151], v[46:47]
	v_add_u32_e32 v152, 0x10080, v194
	v_mov_b32_e32 v153, v159
	v_sub_f32_e32 v145, v145, v216
	v_sub_f32_e32 v144, v144, v216
	v_sub_f32_e32 v147, v147, v216
	v_sub_f32_e32 v146, v146, v216
	v_pk_fma_f32 v[150:151], v[134:135], s[78:79], v[150:151] op_sel_hi:[1,0,1]
	v_pk_fma_f32 v[148:149], v[132:133], s[78:79], v[148:149] op_sel_hi:[1,0,1]
	v_lshl_add_u64 v[152:153], v[152:153], 2, s[90:91]
	v_pk_mul_f32 v[146:147], v[216:217], v[146:147] op_sel:[1,0]
	v_pk_mul_f32 v[144:145], v[216:217], v[144:145] op_sel:[1,0]
	global_store_dwordx4 v[152:153], v[148:151], off
	v_pk_fma_f32 v[144:145], v[208:209], v[144:145], v[40:41]
	v_pk_fma_f32 v[146:147], v[206:207], v[146:147], v[42:43]
;     template <bool LN, int BJ, int LO, int HI> DI void batch(const f32x4 (&acc)[2][2][4][2], unsigned row0, unsigned col0, const f32x4 (&gv)[2], const f32x4 (&bv)[2]) const {
;         f32x4 r[HI - LO]; float mean[(HI - LO) / 2], rstd[(HI - LO) / 2];
; #pragma unroll
;         for (int i = LO; i < HI; ++i) { const int ai = i >> 3, m = (i >> 1) & 3, n = i & 1; const unsigned row = row0 + ai * HALF + m * 16;
;             if (n == 0) { mean[(i - LO) >> 1] = 0.f; rstd[(i - LO) >> 1] = 1.f;
;                 if (LN) { const float2 st = *(const float2*)(stats + row * 2u); mean[(i - LO) >> 1] = st.x; rstd[(i - LO) >> 1] = st.y; } }
;             r[i - LO] = *(const f32x4*)(src + (row * (unsigned)DM + col0 + BJ * HALF + n * 16)); }
; #pragma unroll
;         for (int i = LO; i < HI; ++i) { const int ai = i >> 3, m = (i >> 1) & 3, n = i & 1; const unsigned row = row0 + ai * HALF + m * 16;
;             *(f32x4*)(Y + (row * (unsigned)DM + col0 + BJ * HALF + n * 16)) = acc[ai][BJ][m][n] + ((r[i - LO] - mean[(i - LO) >> 1]) * rstd[(i - LO) >> 1]) * gv[n] + bv[n]; }
	v_add_u32_e32 v148, 0x10090, v194
	v_mov_b32_e32 v149, v159
	v_sub_f32_e32 v141, v141, v200
	v_sub_f32_e32 v140, v140, v200
	v_sub_f32_e32 v143, v143, v200
	v_sub_f32_e32 v142, v142, v200
	v_pk_fma_f32 v[146:147], v[130:131], s[78:79], v[146:147] op_sel_hi:[1,0,1]
	v_pk_fma_f32 v[144:145], v[128:129], s[78:79], v[144:145] op_sel_hi:[1,0,1]
	v_lshl_add_u64 v[148:149], v[148:149], 2, s[90:91]
	v_pk_mul_f32 v[142:143], v[200:201], v[142:143] op_sel:[1,0]
	v_pk_mul_f32 v[140:141], v[200:201], v[140:141] op_sel:[1,0]
	global_store_dwordx4 v[148:149], v[144:147], off
	v_pk_fma_f32 v[140:141], v[214:215], v[140:141], v[36:37]
	v_pk_fma_f32 v[142:143], v[212:213], v[142:143], v[38:39]
	v_add_u32_e32 v144, 0x18080, v194
	v_mov_b32_e32 v145, v159
	v_sub_f32_e32 v137, v137, v200
	v_sub_f32_e32 v136, v136, v200
	v_sub_f32_e32 v139, v139, v200
	v_sub_f32_e32 v138, v138, v200
	v_pk_fma_f32 v[142:143], v[134:135], s[78:79], v[142:143] op_sel_hi:[1,0,1]
	v_pk_fma_f32 v[140:141], v[132:133], s[78:79], v[140:141] op_sel_hi:[1,0,1]
	v_lshl_add_u64 v[144:145], v[144:145], 2, s[90:91]
	v_pk_mul_f32 v[138:139], v[200:201], v[138:139] op_sel:[1,0]
	v_pk_mul_f32 v[136:137], v[200:201], v[136:137] op_sel:[1,0]
	global_store_dwordx4 v[144:145], v[140:143], off
	v_pk_fma_f32 v[136:137], v[208:209], v[136:137], v[32:33]
	v_pk_fma_f32 v[138:139], v[206:207], v[138:139], v[34:35]
	v_add_u32_e32 v140, 0x18090, v194
	v_mov_b32_e32 v141, v159
	v_pk_fma_f32 v[138:139], v[130:131], s[78:79], v[138:139] op_sel_hi:[1,0,1]
	v_pk_fma_f32 v[136:137], v[128:129], s[78:79], v[136:137] op_sel_hi:[1,0,1]
	v_lshl_add_u64 v[140:141], v[140:141], 2, s[90:91]
	global_store_dwordx4 v[140:141], v[136:139], off
	s_nop 1
	v_add_u32_e32 v136, v233, v230
	v_mov_b32_e32 v137, v159
	v_lshl_add_u64 v[136:137], v[136:137], 2, s[88:89]
	global_load_dwordx2 v[220:221], v[196:197], off
	global_load_dwordx4 v[216:219], v[136:137], off
	v_add_u32_e32 v136, v233, v229
	v_mov_b32_e32 v137, v159
	v_lshl_add_u64 v[136:137], v[136:137], 2, s[88:89]
	global_load_dwordx4 v[240:243], v[136:137], off
	global_load_dwordx2 v[200:201], v[198:199], off
	v_add_u32_e32 v136, v234, v230
	v_mov_b32_e32 v137, v159
	v_lshl_add_u64 v[136:137], v[136:137], 2, s[88:89]
	global_load_dwordx4 v[244:247], v[136:137], off
	v_add_u32_e32 v136, v234, v229
	v_mov_b32_e32 v137, v159
	v_lshl_add_u64 v[136:137], v[136:137], 2, s[88:89]
	global_load_dwordx4 v[152:155], v[136:137], off
	global_load_dwordx2 v[198:199], v[204:205], off
	v_add_u32_e32 v136, v237, v230
	v_mov_b32_e32 v137, v159
	v_lshl_add_u64 v[136:137], v[136:137], 2, s[88:89]
	global_load_dwordx4 v[148:151], v[136:137], off
	v_add_u32_e32 v136, v237, v229
	v_mov_b32_e32 v137, v159
	v_lshl_add_u64 v[136:137], v[136:137], 2, s[88:89]
	global_load_dwordx4 v[144:147], v[136:137], off
	global_load_dwordx2 v[196:197], v[210:211], off
	v_add_u32_e32 v136, v238, v230
	v_mov_b32_e32 v137, v159
	v_lshl_add_u64 v[136:137], v[136:137], 2, s[88:89]
	global_load_dwordx4 v[140:143], v[136:137], off
	v_add_u32_e32 v136, v238, v229
	v_mov_b32_e32 v137, v159
	v_lshl_add_u64 v[136:137], v[136:137], 2, s[88:89]
	global_load_dwordx4 v[136:139], v[136:137], off
	v_add_u32_e32 v210, 0x40080, v194
	v_mov_b32_e32 v211, v159
	v_lshl_add_u64 v[210:211], v[210:211], 2, s[90:91]
	s_waitcnt vmcnt(0)
;     template <bool LN, int BJ, int LO, int HI> DI void batch(const f32x4 (&acc)[2][2][4][2], unsigned row0, unsigned col0, const f32x4 (&gv)[2], const f32x4 (&bv)[2]) const {
;         f32x4 r[HI - LO]; float mean[(HI - LO) / 2], rstd[(HI - LO) / 2];
; #pragma unroll
;         for (int i = LO; i < HI; ++i) { const int ai = i >> 3, m = (i >> 1) & 3, n = i & 1; const unsigned row = row0 + ai * HALF + m * 16;
;             if (n == 0) { mean[(i - LO) >> 1] = 0.f; rstd[(i - LO) >> 1] = 1.f;
;                 if (LN) { const float2 st = *(const float2*)(stats + row * 2u); mean[(i - LO) >> 1] = st.x; rstd[(i - LO) >> 1] = st.y; } }
;             r[i - LO] = *(const f32x4*)(src + (row * (unsigned)DM + col0 + BJ * HALF + n * 16)); }
; #pragma unroll
;         for (int i = LO; i < HI; ++i) { const int ai = i >> 3, m = (i >> 1) & 3, n = i & 1; const unsigned row = row0 + ai * HALF + m * 16;
;             *(f32x4*)(Y + (row * (unsigned)DM + col0 + BJ * HALF + n * 16)) = acc[ai][BJ][m][n] + ((r[i - LO] - mean[(i - LO) >> 1]) * rstd[(i - LO) >> 1]) * gv[n] + bv[n]; }
	v_sub_f32_e32 v203, v217, v220
	v_sub_f32_e32 v202, v216, v220
	v_sub_f32_e32 v205, v219, v220
	v_sub_f32_e32 v204, v218, v220
	v_pk_mul_f32 v[204:205], v[220:221], v[204:205] op_sel:[1,0]
	v_pk_mul_f32 v[202:203], v[220:221], v[202:203] op_sel:[1,0]
	v_pk_fma_f32 v[204:205], v[212:213], v[204:205], v[30:31]
	v_pk_fma_f32 v[202:203], v[214:215], v[202:203], v[28:29]
	v_pk_fma_f32 v[204:205], v[134:135], s[78:79], v[204:205] op_sel_hi:[1,0,1]
	v_pk_fma_f32 v[202:203], v[132:133], s[78:79], v[202:203] op_sel_hi:[1,0,1]
	global_store_dwordx4 v[210:211], v[202:205], off
	v_add_u32_e32 v210, 0x40090, v194
	v_mov_b32_e32 v211, v159
	v_sub_f32_e32 v203, v241, v220
	v_sub_f32_e32 v202, v240, v220
	v_sub_f32_e32 v205, v243, v220
	v_sub_f32_e32 v204, v242, v220
	v_pk_mul_f32 v[204:205], v[220:221], v[204:205] op_sel:[1,0]
	v_pk_mul_f32 v[202:203], v[220:221], v[202:203] op_sel:[1,0]
	v_pk_fma_f32 v[204:205], v[206:207], v[204:205], v[26:27]
	v_pk_fma_f32 v[202:203], v[208:209], v[202:203], v[24:25]
	v_pk_fma_f32 v[204:205], v[130:131], s[78:79], v[204:205] op_sel_hi:[1,0,1]
	v_pk_fma_f32 v[202:203], v[128:129], s[78:79], v[202:203] op_sel_hi:[1,0,1]
	v_lshl_add_u64 v[210:211], v[210:211], 2, s[90:91]
	global_store_dwordx4 v[210:211], v[202:205], off
	v_sub_f32_e32 v149, v149, v198
	v_sub_f32_e32 v148, v148, v198
	v_sub_f32_e32 v203, v245, v200
	v_sub_f32_e32 v202, v244, v200
	v_sub_f32_e32 v141, v141, v196
	v_sub_f32_e32 v140, v140, v196
	v_sub_f32_e32 v205, v247, v200
	v_sub_f32_e32 v204, v246, v200
	v_pk_mul_f32 v[202:203], v[200:201], v[202:203] op_sel:[1,0]
	v_sub_f32_e32 v151, v151, v198
	v_sub_f32_e32 v150, v150, v198
	v_pk_mul_f32 v[148:149], v[198:199], v[148:149] op_sel:[1,0]
	v_sub_f32_e32 v143, v143, v196
	v_sub_f32_e32 v142, v142, v196
	v_pk_mul_f32 v[140:141], v[196:197], v[140:141] op_sel:[1,0]
	v_pk_mul_f32 v[204:205], v[200:201], v[204:205] op_sel:[1,0]
	v_pk_fma_f32 v[202:203], v[214:215], v[202:203], v[20:21]
	v_sub_f32_e32 v153, v153, v200
	v_sub_f32_e32 v152, v152, v200
	v_sub_f32_e32 v155, v155, v200
	v_sub_f32_e32 v154, v154, v200
	v_pk_mul_f32 v[150:151], v[198:199], v[150:151] op_sel:[1,0]
	v_pk_fma_f32 v[148:149], v[214:215], v[148:149], v[12:13]
	v_pk_mul_f32 v[142:143], v[196:197], v[142:143] op_sel:[1,0]
	v_pk_fma_f32 v[140:141], v[214:215], v[140:141], v[4:5]
	v_pk_fma_f32 v[204:205], v[212:213], v[204:205], v[22:23]
	v_pk_fma_f32 v[202:203], v[132:133], s[78:79], v[202:203] op_sel_hi:[1,0,1]
	v_pk_mul_f32 v[154:155], v[200:201], v[154:155] op_sel:[1,0]
	v_pk_mul_f32 v[152:153], v[200:201], v[152:153] op_sel:[1,0]
	v_pk_fma_f32 v[150:151], v[212:213], v[150:151], v[14:15]
	v_pk_fma_f32 v[148:149], v[132:133], s[78:79], v[148:149] op_sel_hi:[1,0,1]
	v_pk_fma_f32 v[142:143], v[212:213], v[142:143], v[6:7]
	v_pk_fma_f32 v[132:133], v[132:133], s[78:79], v[140:141] op_sel_hi:[1,0,1]
	v_add_u32_e32 v140, 0x58080, v194
	v_mov_b32_e32 v141, v159
	v_pk_fma_f32 v[204:205], v[134:135], s[78:79], v[204:205] op_sel_hi:[1,0,1]
	v_pk_fma_f32 v[152:153], v[208:209], v[152:153], v[16:17]
	v_pk_fma_f32 v[154:155], v[206:207], v[154:155], v[18:19]
	v_add_u32_e32 v200, 0x48090, v194
	v_mov_b32_e32 v201, v159
	v_pk_fma_f32 v[150:151], v[134:135], s[78:79], v[150:151] op_sel_hi:[1,0,1]
	v_pk_fma_f32 v[134:135], v[134:135], s[78:79], v[142:143] op_sel_hi:[1,0,1]
	v_lshl_add_u64 v[140:141], v[140:141], 2, s[90:91]
	v_pk_fma_f32 v[154:155], v[130:131], s[78:79], v[154:155] op_sel_hi:[1,0,1]
	v_pk_fma_f32 v[152:153], v[128:129], s[78:79], v[152:153] op_sel_hi:[1,0,1]
	v_lshl_add_u64 v[200:201], v[200:201], 2, s[90:91]
	v_sub_f32_e32 v145, v145, v198
	v_sub_f32_e32 v144, v144, v198
	global_store_dwordx4 v[140:141], v[132:135], off
	global_store_dwordx4 v[200:201], v[152:155], off
	v_sub_f32_e32 v147, v147, v198
	v_sub_f32_e32 v133, v137, v196
	v_sub_f32_e32 v132, v136, v196
	v_add_u32_e32 v152, 0x50080, v194
	v_mov_b32_e32 v153, v159
	v_sub_f32_e32 v146, v146, v198
	v_pk_mul_f32 v[144:145], v[198:199], v[144:145] op_sel:[1,0]
	v_sub_f32_e32 v135, v139, v196
	v_sub_f32_e32 v134, v138, v196
	v_pk_mul_f32 v[132:133], v[196:197], v[132:133] op_sel:[1,0]
	v_lshl_add_u64 v[152:153], v[152:153], 2, s[90:91]
	v_pk_mul_f32 v[146:147], v[198:199], v[146:147] op_sel:[1,0]
	v_pk_fma_f32 v[144:145], v[208:209], v[144:145], v[8:9]
	v_pk_mul_f32 v[134:135], v[196:197], v[134:135] op_sel:[1,0]
	v_pk_fma_f32 v[132:133], v[208:209], v[132:133], v[0:1]
	v_add_u32_e32 v210, 0x48080, v194
	v_mov_b32_e32 v211, v159
	global_store_dwordx4 v[152:153], v[148:151], off
	v_pk_fma_f32 v[146:147], v[206:207], v[146:147], v[10:11]
	v_pk_fma_f32 v[144:145], v[128:129], s[78:79], v[144:145] op_sel_hi:[1,0,1]
	v_add_u32_e32 v148, 0x50090, v194
	v_mov_b32_e32 v149, v159
	v_pk_fma_f32 v[134:135], v[206:207], v[134:135], v[2:3]
	v_pk_fma_f32 v[128:129], v[128:129], s[78:79], v[132:133] op_sel_hi:[1,0,1]
	v_add_u32_e32 v132, 0x58090, v194
	v_mov_b32_e32 v133, v159
	v_lshl_add_u64 v[210:211], v[210:211], 2, s[90:91]
	v_pk_fma_f32 v[146:147], v[130:131], s[78:79], v[146:147] op_sel_hi:[1,0,1]
	v_lshl_add_u64 v[148:149], v[148:149], 2, s[90:91]
	v_pk_fma_f32 v[130:131], v[130:131], s[78:79], v[134:135] op_sel_hi:[1,0,1]
	v_lshl_add_u64 v[132:133], v[132:133], 2, s[90:91]
	global_store_dwordx4 v[210:211], v[202:205], off
	global_store_dwordx4 v[148:149], v[144:147], off
	global_store_dwordx4 v[132:133], v[128:131], off
	s_mov_b64 s[20:21], 0
	s_branch .LBB0_81

; #define PG8_STAGE(bufoff, gbase) do { _Pragma("unroll") for (int _i = 0; _i < 2; ++_i) \
;         __builtin_amdgcn_global_load_lds((const unsigned*)((const char*)(gbase) + voff[_i]), (LAS unsigned*)(lds + (bufoff) + ldsw + _i * 8192), 16, 0, 0); } while (0)
; #define PG8_LDA(dst, b, h) do { _Pragma("unroll") for (int m = 0; m < 4; ++m) _Pragma("unroll") for (int k = 0; k < 2; ++k) dst[m][k] = *(const LAS bf16x8*)(lds + PG8_SA(b, h) + aoff + m * 2048 + k * 1024); } while (0)
; #define PG8_LDB(dst, b, h) do { _Pragma("unroll") for (int n = 0; n < 2; ++n) _Pragma("unroll") for (int k = 0; k < 2; ++k) dst[n][k] = *(const LAS bf16x8*)(lds + PG8_SB(b, h) + boff + n * 2048 + k * 1024); } while (0)
; #define PG8_MMA(ai, bj, At, Bt) do { __builtin_amdgcn_s_setprio(1); _Pragma("unroll") for (int m = 0; m < 4; ++m) _Pragma("unroll") for (int n = 0; n < 2; ++n) _Pragma("unroll") for (int k = 0; k < 2; ++k) \
;         acc[ai][bj][m][n] = __builtin_amdgcn_mfma_f32_16x16x32_bf16(Bt[n][k], At[m][k], acc[ai][bj][m][n], 0, 0, 0); __builtin_amdgcn_s_setprio(0); } while (0)
; #define PG8_WAIT_V(n) asm volatile("s_waitcnt vmcnt(" #n ")" ::: "memory")
; #define PG8_WAIT_L(n) asm volatile("s_waitcnt lgkmcnt(" #n ")" ::: "memory")
; #define PG8_BAR __builtin_amdgcn_s_barrier()
; #define PG8_SCHED __builtin_amdgcn_sched_barrier(0)
; template <class Epi>
; DI void gemm_phase(LAS unsigned char* lds, const Gemm g, const StaticOrder& S, const Epi& E) {
;     ...
;         for (int t = 0; t < nt; t += 2) {
;             const bool last = (t == nt - 2);
;             const char* a1 = cA + (size_t)(t + 1) * kstep;
;             const char* a2 = last ? nA : cA + (size_t)(t + 2) * kstep; const char* b2 = last ? nB : cB + (size_t)(t + 2) * kstep;
;             const char* a3 = a2 + kstep; const char* b3 = b2 + kstep;
;             PG8_LDB(B0, 0, 0); PG8_SCHED; PG8_LDA(At, 0, 0); PG8_STAGE(PG8_SA(1, 1), a1 + hstep);
;             PG8_WAIT_L(8); PG8_BAR; PG8_WAIT_L(0); PG8_MMA(0, 0, At, B0); PG8_BAR; PG8_SCHED;
;             PG8_LDB(B1, 0, 1); PG8_STAGE(PG8_SB(0, 0), b2);
;             PG8_BAR; PG8_WAIT_L(0); PG8_MMA(0, 1, At, B1); PG8_BAR;
;             PG8_LDA(At, 0, 1); PG8_STAGE(PG8_SA(0, 0), a2);
;             PG8_BAR; PG8_WAIT_L(0); PG8_MMA(1, 0, At, B0); PG8_BAR; PG8_SCHED;
;             PG8_STAGE(PG8_SB(0, 1), b2 + hstep);
;             PG8_WAIT_V(6); PG8_BAR; PG8_MMA(1, 1, At, B1); PG8_BAR;
.LBB0_134:
	ds_read_b128 v[96:99], v199
	ds_read_b128 v[100:103], v199 offset:1024
	ds_read_b128 v[136:139], v199 offset:2048
	ds_read_b128 v[148:151], v199 offset:3072
	ds_read_b128 v[152:155], v201
	ds_read_b128 v[186:189], v201 offset:1024
	ds_read_b128 v[190:193], v201 offset:2048
	ds_read_b128 v[194:197], v201 offset:3072
	ds_read_b128 v[202:205], v201 offset:4096
	ds_read_b128 v[206:209], v201 offset:5120
	ds_read_b128 v[210:213], v201 offset:6144
	ds_read_b128 v[214:217], v201 offset:7168
	s_add_u32 s18, s16, 0x100
	s_addc_u32 s19, s17, 0
	s_add_i32 s39, 0, 0x10000
	s_cmpk_eq_i32 s33, 0x54
	s_cselect_b32 s23, s9, s19
	s_cselect_b32 s22, s8, s18
	s_cselect_b32 s21, s11, s5
	s_cselect_b32 s20, s10, s4
	s_add_i32 m0, s28, 0xc000
	s_nop 0
	global_load_lds_dwordx4 v144, s[16:17]
	s_add_i32 m0, s28, 0xe000
	s_nop 0
	global_load_lds_dwordx4 v146, s[16:17]
	s_waitcnt lgkmcnt(8)
	s_setprio 1
	s_barrier
	s_waitcnt lgkmcnt(0)
	v_mfma_f32_16x16x32_bf16 v[132:135], v[96:99], v[152:155], v[132:135]
	v_mfma_f32_16x16x32_bf16 v[128:131], v[136:139], v[152:155], v[128:131]
	v_mfma_f32_16x16x32_bf16 v[124:127], v[96:99], v[190:193], v[124:127]
	v_mfma_f32_16x16x32_bf16 v[120:123], v[136:139], v[190:193], v[120:123]
	v_mfma_f32_16x16x32_bf16 v[116:119], v[96:99], v[202:205], v[116:119]
	v_mfma_f32_16x16x32_bf16 v[112:115], v[136:139], v[202:205], v[112:115]
	v_mfma_f32_16x16x32_bf16 v[108:111], v[96:99], v[210:213], v[108:111]
	v_mfma_f32_16x16x32_bf16 v[104:107], v[136:139], v[210:213], v[104:107]
	v_mfma_f32_16x16x32_bf16 v[132:135], v[100:103], v[186:189], v[132:135]
	v_mfma_f32_16x16x32_bf16 v[128:131], v[148:151], v[186:189], v[128:131]
	v_mfma_f32_16x16x32_bf16 v[124:127], v[100:103], v[194:197], v[124:127]
	v_mfma_f32_16x16x32_bf16 v[120:123], v[148:151], v[194:197], v[120:123]
	v_mfma_f32_16x16x32_bf16 v[116:119], v[100:103], v[206:209], v[116:119]
	v_mfma_f32_16x16x32_bf16 v[112:115], v[148:151], v[206:209], v[112:115]
	v_mfma_f32_16x16x32_bf16 v[108:111], v[100:103], v[214:217], v[108:111]
	s_setprio 0
	v_mfma_f32_16x16x32_bf16 v[104:107], v[148:151], v[214:217], v[104:107]
	s_barrier
	ds_read_b128 v[226:229], v199 offset:16384
	ds_read_b128 v[230:233], v199 offset:17408
	ds_read_b128 v[234:237], v199 offset:18432
	ds_read_b128 v[238:241], v199 offset:19456
	s_add_i32 s40, 0, 0x14000
	s_add_i32 s16, s39, s27
	s_mov_b32 m0, s16
	s_nop 0
	global_load_lds_dwordx4 v142, s[20:21]
	s_add_i32 m0, s16, 0x2000
	s_nop 0
	global_load_lds_dwordx4 v140, s[20:21]
	s_waitcnt lgkmcnt(0)
	s_setprio 1
	s_barrier
	v_mfma_f32_16x16x32_bf16 v[60:63], v[226:229], v[152:155], v[60:63]
	v_mfma_f32_16x16x32_bf16 v[56:59], v[234:237], v[152:155], v[56:59]
	v_mfma_f32_16x16x32_bf16 v[52:55], v[226:229], v[190:193], v[52:55]
	v_mfma_f32_16x16x32_bf16 v[48:51], v[234:237], v[190:193], v[48:51]
	v_mfma_f32_16x16x32_bf16 v[44:47], v[226:229], v[202:205], v[44:47]
	v_mfma_f32_16x16x32_bf16 v[40:43], v[234:237], v[202:205], v[40:43]
	v_mfma_f32_16x16x32_bf16 v[36:39], v[226:229], v[210:213], v[36:39]
	v_mfma_f32_16x16x32_bf16 v[32:35], v[234:237], v[210:213], v[32:35]
	v_mfma_f32_16x16x32_bf16 v[60:63], v[230:233], v[186:189], v[60:63]
	v_mfma_f32_16x16x32_bf16 v[56:59], v[238:241], v[186:189], v[56:59]
	v_mfma_f32_16x16x32_bf16 v[52:55], v[230:233], v[194:197], v[52:55]
	v_mfma_f32_16x16x32_bf16 v[48:51], v[238:241], v[194:197], v[48:51]
	v_mfma_f32_16x16x32_bf16 v[44:47], v[230:233], v[206:209], v[44:47]
	v_mfma_f32_16x16x32_bf16 v[40:43], v[238:241], v[206:209], v[40:43]
	v_mfma_f32_16x16x32_bf16 v[36:39], v[230:233], v[214:217], v[36:39]
	s_setprio 0
	v_mfma_f32_16x16x32_bf16 v[32:35], v[238:241], v[214:217], v[32:35]
	s_barrier
	ds_read_b128 v[152:155], v201 offset:16384
	ds_read_b128 v[186:189], v201 offset:17408
	ds_read_b128 v[190:193], v201 offset:18432
	ds_read_b128 v[194:197], v201 offset:19456
	ds_read_b128 v[202:205], v201 offset:20480
	ds_read_b128 v[206:209], v201 offset:21504
	ds_read_b128 v[210:213], v201 offset:22528
	ds_read_b128 v[214:217], v201 offset:23552
	s_mov_b32 m0, s28
	s_nop 0
	global_load_lds_dwordx4 v142, s[22:23]
	s_mov_b64 s[100:101], s[22:23]
	s_mov_b32 m0, s29
	s_nop 0
	global_load_lds_dwordx4 v140, s[22:23]
	s_waitcnt lgkmcnt(0)
	s_setprio 1
	s_barrier
	v_mfma_f32_16x16x32_bf16 v[92:95], v[96:99], v[152:155], v[92:95]
	v_mfma_f32_16x16x32_bf16 v[88:91], v[136:139], v[152:155], v[88:91]
	v_mfma_f32_16x16x32_bf16 v[84:87], v[96:99], v[190:193], v[84:87]
	v_mfma_f32_16x16x32_bf16 v[80:83], v[136:139], v[190:193], v[80:83]
	v_mfma_f32_16x16x32_bf16 v[76:79], v[96:99], v[202:205], v[76:79]
	v_mfma_f32_16x16x32_bf16 v[72:75], v[136:139], v[202:205], v[72:75]
	v_mfma_f32_16x16x32_bf16 v[68:71], v[96:99], v[210:213], v[68:71]
	v_mfma_f32_16x16x32_bf16 v[64:67], v[136:139], v[210:213], v[64:67]
	v_mfma_f32_16x16x32_bf16 v[92:95], v[100:103], v[186:189], v[92:95]
	v_mfma_f32_16x16x32_bf16 v[88:91], v[148:151], v[186:189], v[88:91]
	v_mfma_f32_16x16x32_bf16 v[84:87], v[100:103], v[194:197], v[84:87]
	v_mfma_f32_16x16x32_bf16 v[80:83], v[148:151], v[194:197], v[80:83]
	v_mfma_f32_16x16x32_bf16 v[76:79], v[100:103], v[206:209], v[76:79]
	v_mfma_f32_16x16x32_bf16 v[72:75], v[148:151], v[206:209], v[72:75]
	v_mfma_f32_16x16x32_bf16 v[68:71], v[100:103], v[214:217], v[68:71]
	s_setprio 0
	v_mfma_f32_16x16x32_bf16 v[64:67], v[148:151], v[214:217], v[64:67]
	s_barrier
	s_add_u32 s16, s20, 0x160000
	s_addc_u32 s17, s21, 0
	s_add_i32 s39, s40, s27
	s_mov_b32 m0, s39
	s_nop 0
	global_load_lds_dwordx4 v142, s[16:17]
	s_add_i32 m0, s39, 0x2000
	s_nop 0
	global_load_lds_dwordx4 v140, s[16:17]
	s_waitcnt vmcnt(6)
	s_setprio 1
	s_barrier
; #define PG8_STAGE(bufoff, gbase) do { _Pragma("unroll") for (int _i = 0; _i < 2; ++_i) \
;         __builtin_amdgcn_global_load_lds((const unsigned*)((const char*)(gbase) + voff[_i]), (LAS unsigned*)(lds + (bufoff) + ldsw + _i * 8192), 16, 0, 0); } while (0)
; #define PG8_LDA(dst, b, h) do { _Pragma("unroll") for (int m = 0; m < 4; ++m) _Pragma("unroll") for (int k = 0; k < 2; ++k) dst[m][k] = *(const LAS bf16x8*)(lds + PG8_SA(b, h) + aoff + m * 2048 + k * 1024); } while (0)
; #define PG8_LDB(dst, b, h) do { _Pragma("unroll") for (int n = 0; n < 2; ++n) _Pragma("unroll") for (int k = 0; k < 2; ++k) dst[n][k] = *(const LAS bf16x8*)(lds + PG8_SB(b, h) + boff + n * 2048 + k * 1024); } while (0)
; #define PG8_MMA(ai, bj, At, Bt) do { __builtin_amdgcn_s_setprio(1); _Pragma("unroll") for (int m = 0; m < 4; ++m) _Pragma("unroll") for (int n = 0; n < 2; ++n) _Pragma("unroll") for (int k = 0; k < 2; ++k) \
;         acc[ai][bj][m][n] = __builtin_amdgcn_mfma_f32_16x16x32_bf16(Bt[n][k], At[m][k], acc[ai][bj][m][n], 0, 0, 0); __builtin_amdgcn_s_setprio(0); } while (0)
; #define PG8_WAIT_V(n) asm volatile("s_waitcnt vmcnt(" #n ")" ::: "memory")
; #define PG8_WAIT_L(n) asm volatile("s_waitcnt lgkmcnt(" #n ")" ::: "memory")
; #define PG8_BAR __builtin_amdgcn_s_barrier()
; #define PG8_SCHED __builtin_amdgcn_sched_barrier(0)
; template <class Epi>
; DI void gemm_phase(LAS unsigned char* lds, const Gemm g, const StaticOrder& S, const Epi& E) {
;     ...
;             PG8_WAIT_V(6); PG8_BAR; PG8_MMA(1, 1, At, B1); PG8_BAR;
;             PG8_LDB(B0, 1, 0); PG8_SCHED; PG8_LDA(At, 1, 0); PG8_STAGE(PG8_SA(0, 1), a2 + hstep);
;             PG8_WAIT_L(8); PG8_BAR; PG8_WAIT_L(0); PG8_MMA(0, 0, At, B0); PG8_BAR; PG8_SCHED;
;             PG8_LDB(B1, 1, 1); PG8_STAGE(PG8_SB(1, 0), b3);
;             PG8_BAR; PG8_WAIT_L(0); PG8_MMA(0, 1, At, B1); PG8_BAR;
;             PG8_LDA(At, 1, 1); PG8_STAGE(PG8_SA(1, 0), a3);
;             PG8_BAR; PG8_WAIT_L(0); PG8_MMA(1, 0, At, B0); PG8_BAR; PG8_SCHED;
	v_mfma_f32_16x16x32_bf16 v[28:31], v[226:229], v[152:155], v[28:31]
	v_mfma_f32_16x16x32_bf16 v[24:27], v[234:237], v[152:155], v[24:27]
	v_mfma_f32_16x16x32_bf16 v[20:23], v[226:229], v[190:193], v[20:23]
	v_mfma_f32_16x16x32_bf16 v[16:19], v[234:237], v[190:193], v[16:19]
	v_mfma_f32_16x16x32_bf16 v[12:15], v[226:229], v[202:205], v[12:15]
	v_mfma_f32_16x16x32_bf16 v[8:11], v[234:237], v[202:205], v[8:11]
	v_mfma_f32_16x16x32_bf16 v[4:7], v[226:229], v[210:213], v[4:7]
	v_mfma_f32_16x16x32_bf16 v[0:3], v[234:237], v[210:213], v[0:3]
	v_mfma_f32_16x16x32_bf16 v[28:31], v[230:233], v[186:189], v[28:31]
	v_mfma_f32_16x16x32_bf16 v[24:27], v[238:241], v[186:189], v[24:27]
	v_mfma_f32_16x16x32_bf16 v[20:23], v[230:233], v[194:197], v[20:23]
	v_mfma_f32_16x16x32_bf16 v[16:19], v[238:241], v[194:197], v[16:19]
	v_mfma_f32_16x16x32_bf16 v[12:15], v[230:233], v[206:209], v[12:15]
	v_mfma_f32_16x16x32_bf16 v[8:11], v[238:241], v[206:209], v[8:11]
	v_mfma_f32_16x16x32_bf16 v[4:7], v[230:233], v[214:217], v[4:7]
	s_setprio 0
	v_mfma_f32_16x16x32_bf16 v[0:3], v[238:241], v[214:217], v[0:3]
	s_barrier
	ds_read_b128 v[96:99], v199 offset:32768
	ds_read_b128 v[100:103], v199 offset:33792
	ds_read_b128 v[136:139], v199 offset:34816
	ds_read_b128 v[148:151], v199 offset:35840
	ds_read_b128 v[152:155], v201 offset:32768
	ds_read_b128 v[186:189], v201 offset:33792
	ds_read_b128 v[190:193], v201 offset:34816
	ds_read_b128 v[194:197], v201 offset:35840
	ds_read_b128 v[202:205], v201 offset:36864
	ds_read_b128 v[206:209], v201 offset:37888
	ds_read_b128 v[210:213], v201 offset:38912
	ds_read_b128 v[214:217], v201 offset:39936
	s_add_i32 s39, 0, 0x18000
	s_add_u32 s16, s22, 0x160000
	s_addc_u32 s17, s23, 0
	s_mov_b32 m0, s30
	s_nop 0
	global_load_lds_dwordx4 v142, s[16:17]
	s_mov_b32 m0, s31
	s_nop 0
	global_load_lds_dwordx4 v140, s[16:17]
	s_waitcnt lgkmcnt(8)
	s_setprio 1
	s_barrier
	s_waitcnt lgkmcnt(0)
	v_mfma_f32_16x16x32_bf16 v[132:135], v[96:99], v[152:155], v[132:135]
	v_mfma_f32_16x16x32_bf16 v[128:131], v[136:139], v[152:155], v[128:131]
	v_mfma_f32_16x16x32_bf16 v[124:127], v[96:99], v[190:193], v[124:127]
	v_mfma_f32_16x16x32_bf16 v[120:123], v[136:139], v[190:193], v[120:123]
	v_mfma_f32_16x16x32_bf16 v[116:119], v[96:99], v[202:205], v[116:119]
	v_mfma_f32_16x16x32_bf16 v[112:115], v[136:139], v[202:205], v[112:115]
	v_mfma_f32_16x16x32_bf16 v[108:111], v[96:99], v[210:213], v[108:111]
	v_mfma_f32_16x16x32_bf16 v[104:107], v[136:139], v[210:213], v[104:107]
	v_mfma_f32_16x16x32_bf16 v[132:135], v[100:103], v[186:189], v[132:135]
	v_mfma_f32_16x16x32_bf16 v[128:131], v[148:151], v[186:189], v[128:131]
	v_mfma_f32_16x16x32_bf16 v[124:127], v[100:103], v[194:197], v[124:127]
	v_mfma_f32_16x16x32_bf16 v[120:123], v[148:151], v[194:197], v[120:123]
	v_mfma_f32_16x16x32_bf16 v[116:119], v[100:103], v[206:209], v[116:119]
	v_mfma_f32_16x16x32_bf16 v[112:115], v[148:151], v[206:209], v[112:115]
	v_mfma_f32_16x16x32_bf16 v[108:111], v[100:103], v[214:217], v[108:111]
	s_setprio 0
	v_mfma_f32_16x16x32_bf16 v[104:107], v[148:151], v[214:217], v[104:107]
	s_barrier
	ds_read_b128 v[226:229], v199 offset:49152
	ds_read_b128 v[230:233], v199 offset:50176
	ds_read_b128 v[234:237], v199 offset:51200
	ds_read_b128 v[238:241], v199 offset:52224
	s_add_i32 s22, 0, 0x1c000
	s_add_i32 s16, s39, s27
	s_add_i32 m0, s16, 0xffffff80
	s_nop 0
	global_load_lds_dwordx4 v142, s[20:21] offset:128
	s_add_i32 m0, s16, 0x1f80
	s_nop 0
	global_load_lds_dwordx4 v140, s[20:21] offset:128
	s_waitcnt lgkmcnt(0)
	s_setprio 1
	s_barrier
	v_mfma_f32_16x16x32_bf16 v[60:63], v[226:229], v[152:155], v[60:63]
	v_mfma_f32_16x16x32_bf16 v[56:59], v[234:237], v[152:155], v[56:59]
	v_mfma_f32_16x16x32_bf16 v[52:55], v[226:229], v[190:193], v[52:55]
	v_mfma_f32_16x16x32_bf16 v[48:51], v[234:237], v[190:193], v[48:51]
	v_mfma_f32_16x16x32_bf16 v[44:47], v[226:229], v[202:205], v[44:47]
	v_mfma_f32_16x16x32_bf16 v[40:43], v[234:237], v[202:205], v[40:43]
	v_mfma_f32_16x16x32_bf16 v[36:39], v[226:229], v[210:213], v[36:39]
	v_mfma_f32_16x16x32_bf16 v[32:35], v[234:237], v[210:213], v[32:35]
	v_mfma_f32_16x16x32_bf16 v[60:63], v[230:233], v[186:189], v[60:63]
	v_mfma_f32_16x16x32_bf16 v[56:59], v[238:241], v[186:189], v[56:59]
	v_mfma_f32_16x16x32_bf16 v[52:55], v[230:233], v[194:197], v[52:55]
	v_mfma_f32_16x16x32_bf16 v[48:51], v[238:241], v[194:197], v[48:51]
	v_mfma_f32_16x16x32_bf16 v[44:47], v[230:233], v[206:209], v[44:47]
	v_mfma_f32_16x16x32_bf16 v[40:43], v[238:241], v[206:209], v[40:43]
	v_mfma_f32_16x16x32_bf16 v[36:39], v[230:233], v[214:217], v[36:39]
	s_setprio 0
	v_mfma_f32_16x16x32_bf16 v[32:35], v[238:241], v[214:217], v[32:35]
	s_barrier
	ds_read_b128 v[152:155], v201 offset:49152
	ds_read_b128 v[186:189], v201 offset:50176
	ds_read_b128 v[190:193], v201 offset:51200
	ds_read_b128 v[194:197], v201 offset:52224
	ds_read_b128 v[202:205], v201 offset:53248
	ds_read_b128 v[206:209], v201 offset:54272
	ds_read_b128 v[210:213], v201 offset:55296
	ds_read_b128 v[214:217], v201 offset:56320
	s_add_i32 m0, s34, 0xffffff80
	s_nop 0
	global_load_lds_dwordx4 v142, s[100:101] offset:128
	s_add_i32 m0, s35, 0xffffff80
	s_nop 0
	global_load_lds_dwordx4 v140, s[100:101] offset:128
	s_waitcnt lgkmcnt(0)
	s_setprio 1
	s_barrier
; #define PG8_BAR __builtin_amdgcn_s_barrier()
; template <class Epi>
; DI void gemm_phase(LAS unsigned char* lds, const Gemm g, const StaticOrder& S, const Epi& E) {
;     ...
;             PG8_BAR; PG8_WAIT_L(0); PG8_MMA(1, 0, At, B0); PG8_BAR; PG8_SCHED;
;             PG8_STAGE(PG8_SB(1, 1), b3 + hstep);
;             PG8_WAIT_V(6); PG8_BAR; PG8_MMA(1, 1, At, B1); PG8_BAR;
;     template <bool LN, int BJ, int LO, int HI> DI void batch(const f32x4 (&acc)[2][2][4][2], unsigned row0, unsigned col0, const f32x4 (&gv)[2], const f32x4 (&bv)[2]) const {
;         f32x4 r[HI - LO]; float mean[(HI - LO) / 2], rstd[(HI - LO) / 2];
; #pragma unroll
;         for (int i = LO; i < HI; ++i) { const int ai = i >> 3, m = (i >> 1) & 3, n = i & 1; const unsigned row = row0 + ai * HALF + m * 16;
;             if (n == 0) { mean[(i - LO) >> 1] = 0.f; rstd[(i - LO) >> 1] = 1.f;
;                 if (LN) { const float2 st = *(const float2*)(stats + row * 2u); mean[(i - LO) >> 1] = st.x; rstd[(i - LO) >> 1] = st.y; } }
;             r[i - LO] = *(const f32x4*)(src + (row * (unsigned)DM + col0 + BJ * HALF + n * 16)); }
; #pragma unroll
;         for (int i = LO; i < HI; ++i) { const int ai = i >> 3, m = (i >> 1) & 3, n = i & 1; const unsigned row = row0 + ai * HALF + m * 16;
;             *(f32x4*)(Y + (row * (unsigned)DM + col0 + BJ * HALF + n * 16)) = acc[ai][BJ][m][n] + ((r[i - LO] - mean[(i - LO) >> 1]) * rstd[(i - LO) >> 1]) * gv[n] + bv[n]; }
;         __builtin_amdgcn_sched_barrier(0);
;     }
;     template <bool LN, int BJ> DI void load_gb(unsigned col0, f32x4 (&gv)[2], f32x4 (&bv)[2]) const {
; #pragma unroll
;         for (int n = 0; n < 2; ++n) {
;             if (LN) { gv[n] = *(const f32x4*)(gam + col0 + BJ * HALF + n * 16) * ALPHA; bv[n] = *(const f32x4*)(bet + col0 + BJ * HALF + n * 16) * ALPHA; }
;             else { gv[n] = (f32x4){ALPHA, ALPHA, ALPHA, ALPHA}; bv[n] = (f32x4){0.f, 0.f, 0.f, 0.f}; }
;         }
;     }
;     template <bool LN> DI void run(const f32x4 (&acc)[2][2][4][2], const Unit& u, int wr, int wc, int fr, int fq) const {
;         const unsigned row0 = u.pm * BM + wr * 64 + fr, col0 = u.pn * BM + wc * 32 + 4 * fq;
;         f32x4 gv[2], bv[2];
;         load_gb<LN, 0>(col0, gv, bv);
;         batch<LN, 0, 0, 4>(acc, row0, col0, gv, bv);
;         batch<LN, 0, 4, 8>(acc, row0, col0, gv, bv);
;         batch<LN, 0, 8, 12>(acc, row0, col0, gv, bv);
	v_mfma_f32_16x16x32_bf16 v[92:95], v[96:99], v[152:155], v[92:95]
	v_mfma_f32_16x16x32_bf16 v[88:91], v[136:139], v[152:155], v[88:91]
	v_mfma_f32_16x16x32_bf16 v[84:87], v[96:99], v[190:193], v[84:87]
	v_mfma_f32_16x16x32_bf16 v[80:83], v[136:139], v[190:193], v[80:83]
	v_mfma_f32_16x16x32_bf16 v[76:79], v[96:99], v[202:205], v[76:79]
	v_mfma_f32_16x16x32_bf16 v[72:75], v[136:139], v[202:205], v[72:75]
	v_mfma_f32_16x16x32_bf16 v[68:71], v[96:99], v[210:213], v[68:71]
	v_mfma_f32_16x16x32_bf16 v[64:67], v[136:139], v[210:213], v[64:67]
	v_mfma_f32_16x16x32_bf16 v[92:95], v[100:103], v[186:189], v[92:95]
	v_mfma_f32_16x16x32_bf16 v[88:91], v[148:151], v[186:189], v[88:91]
	v_mfma_f32_16x16x32_bf16 v[84:87], v[100:103], v[194:197], v[84:87]
	v_mfma_f32_16x16x32_bf16 v[80:83], v[148:151], v[194:197], v[80:83]
	v_mfma_f32_16x16x32_bf16 v[76:79], v[100:103], v[206:209], v[76:79]
	v_mfma_f32_16x16x32_bf16 v[72:75], v[148:151], v[206:209], v[72:75]
	v_mfma_f32_16x16x32_bf16 v[68:71], v[100:103], v[214:217], v[68:71]
	s_setprio 0
	v_mfma_f32_16x16x32_bf16 v[64:67], v[148:151], v[214:217], v[64:67]
	s_barrier
	s_add_u32 s16, s20, 0x160080
	s_addc_u32 s17, s21, 0
	s_add_i32 s20, s22, s27
	s_mov_b32 m0, s20
	s_nop 0
	global_load_lds_dwordx4 v142, s[16:17]
	s_add_i32 m0, s20, 0x2000
	s_nop 0
	global_load_lds_dwordx4 v140, s[16:17]
	s_waitcnt vmcnt(6)
	s_setprio 1
	s_barrier
	v_mfma_f32_16x16x32_bf16 v[28:31], v[226:229], v[152:155], v[28:31]
	v_mfma_f32_16x16x32_bf16 v[24:27], v[234:237], v[152:155], v[24:27]
	v_mfma_f32_16x16x32_bf16 v[20:23], v[226:229], v[190:193], v[20:23]
	v_mfma_f32_16x16x32_bf16 v[16:19], v[234:237], v[190:193], v[16:19]
	v_mfma_f32_16x16x32_bf16 v[12:15], v[226:229], v[202:205], v[12:15]
	v_mfma_f32_16x16x32_bf16 v[8:11], v[234:237], v[202:205], v[8:11]
	v_mfma_f32_16x16x32_bf16 v[4:7], v[226:229], v[210:213], v[4:7]
	v_mfma_f32_16x16x32_bf16 v[0:3], v[234:237], v[210:213], v[0:3]
	v_mfma_f32_16x16x32_bf16 v[28:31], v[230:233], v[186:189], v[28:31]
	s_add_i32 s33, s33, 2
	v_mfma_f32_16x16x32_bf16 v[24:27], v[238:241], v[186:189], v[24:27]
	s_add_u32 s4, s4, 0x100
	v_mfma_f32_16x16x32_bf16 v[20:23], v[230:233], v[194:197], v[20:23]
	s_addc_u32 s5, s5, 0
	v_mfma_f32_16x16x32_bf16 v[16:19], v[238:241], v[194:197], v[16:19]
	s_cmpk_gt_u32 s33, 0x55
	v_mfma_f32_16x16x32_bf16 v[12:15], v[230:233], v[206:209], v[12:15]
	s_mov_b64 s[16:17], s[18:19]
	v_mfma_f32_16x16x32_bf16 v[8:11], v[238:241], v[206:209], v[8:11]
	v_mfma_f32_16x16x32_bf16 v[4:7], v[230:233], v[214:217], v[4:7]
	s_setprio 0
	v_mfma_f32_16x16x32_bf16 v[0:3], v[238:241], v[214:217], v[0:3]
	s_barrier
	s_cbranch_scc0 .LBB0_134
	v_lshl_or_b32 v158, s2, 8, v200
	v_lshlrev_b64 v[100:101], 2, v[158:159]
	v_lshl_add_u64 v[150:151], s[12:13], 0, v[100:101]
	global_load_dwordx4 v[96:99], v[150:151], off
	v_lshl_add_u64 v[152:153], s[14:15], 0, v[100:101]
	v_lshl_add_u32 v203, s3, 8, v198
	v_lshlrev_b32_e32 v202, 11, v203
	v_add_u32_e32 v148, v202, v158
	v_mov_b32_e32 v149, v159
	v_lshlrev_b32_e32 v136, 1, v203
	v_mov_b32_e32 v137, v159
	v_lshlrev_b64 v[220:221], 2, v[148:149]
	v_lshl_add_u64 v[154:155], v[136:137], 2, s[96:97]
	v_lshl_add_u64 v[136:137], s[90:91], 0, v[220:221]
	v_or_b32_e32 v204, 16, v158
	v_or_b32_e32 v138, 16, v203
	v_lshlrev_b32_e32 v149, 11, v138
	s_waitcnt vmcnt(0)
	v_pk_mul_f32 v[192:193], v[98:99], s[78:79] op_sel_hi:[1,0]
	v_pk_mul_f32 v[194:195], v[96:97], s[78:79] op_sel_hi:[1,0]
	global_load_dwordx4 v[100:103], v[152:153], off
	global_load_dwordx4 v[96:99], v[150:151], off offset:64
	global_load_dwordx2 v[218:219], v[154:155], off
	global_load_dwordx4 v[206:209], v[136:137], off
	v_add_u32_e32 v136, v202, v204
	v_mov_b32_e32 v137, v159
	v_lshl_add_u64 v[136:137], v[136:137], 2, s[90:91]
	global_load_dwordx4 v[210:213], v[136:137], off
	v_lshlrev_b32_e32 v136, 1, v138
	v_mov_b32_e32 v137, v159
	v_lshl_add_u64 v[186:187], v[136:137], 2, s[96:97]
	v_add_u32_e32 v136, v149, v158
	v_lshl_add_u64 v[136:137], v[136:137], 2, s[90:91]
	global_load_dwordx2 v[196:197], v[186:187], off
	global_load_dwordx4 v[214:217], v[136:137], off
	v_add_u32_e32 v136, v149, v204
	v_mov_b32_e32 v137, v159
	v_lshl_add_u64 v[136:137], v[136:137], 2, s[90:91]
	global_load_dwordx4 v[136:139], v[136:137], off
	s_waitcnt vmcnt(0)
	v_pk_mul_f32 v[188:189], v[98:99], s[78:79] op_sel_hi:[1,0]
	v_pk_mul_f32 v[190:191], v[96:97], s[78:79] op_sel_hi:[1,0]
	global_load_dwordx4 v[96:99], v[152:153], off offset:64
	v_sub_f32_e32 v207, v207, v218
	v_sub_f32_e32 v206, v206, v218
	v_sub_f32_e32 v209, v209, v218
	v_sub_f32_e32 v208, v208, v218
	v_pk_mul_f32 v[208:209], v[218:219], v[208:209] op_sel:[1,0]
	v_pk_mul_f32 v[206:207], v[218:219], v[206:207] op_sel:[1,0]
	v_pk_fma_f32 v[134:135], v[192:193], v[208:209], v[134:135]
	v_pk_fma_f32 v[132:133], v[194:195], v[206:207], v[132:133]
	v_pk_fma_f32 v[134:135], v[102:103], s[78:79], v[134:135] op_sel_hi:[1,0,1]
	v_pk_fma_f32 v[132:133], v[100:101], s[78:79], v[132:133] op_sel_hi:[1,0,1]
	v_lshl_add_u64 v[206:207], s[88:89], 0, v[220:221]
	global_store_dwordx4 v[206:207], v[132:135], off
	s_nop 1
	v_sub_f32_e32 v133, v211, v218
	v_sub_f32_e32 v132, v210, v218
	v_sub_f32_e32 v135, v213, v218
	v_sub_f32_e32 v134, v212, v218
	v_pk_mul_f32 v[134:135], v[218:219], v[134:135] op_sel:[1,0]
	v_pk_mul_f32 v[132:133], v[218:219], v[132:133] op_sel:[1,0]
	v_pk_fma_f32 v[130:131], v[188:189], v[134:135], v[130:131]
	v_pk_fma_f32 v[128:129], v[190:191], v[132:133], v[128:129]
	v_or_b32_e32 v132, 16, v148
	v_mov_b32_e32 v133, v159
	v_lshl_add_u64 v[132:133], v[132:133], 2, s[88:89]
	s_waitcnt vmcnt(0)
;     template <bool LN, int BJ, int LO, int HI> DI void batch(const f32x4 (&acc)[2][2][4][2], unsigned row0, unsigned col0, const f32x4 (&gv)[2], const f32x4 (&bv)[2]) const {
;         f32x4 r[HI - LO]; float mean[(HI - LO) / 2], rstd[(HI - LO) / 2];
; #pragma unroll
;         for (int i = LO; i < HI; ++i) { const int ai = i >> 3, m = (i >> 1) & 3, n = i & 1; const unsigned row = row0 + ai * HALF + m * 16;
;             if (n == 0) { mean[(i - LO) >> 1] = 0.f; rstd[(i - LO) >> 1] = 1.f;
;                 if (LN) { const float2 st = *(const float2*)(stats + row * 2u); mean[(i - LO) >> 1] = st.x; rstd[(i - LO) >> 1] = st.y; } }
;             r[i - LO] = *(const f32x4*)(src + (row * (unsigned)DM + col0 + BJ * HALF + n * 16)); }
; #pragma unroll
;         for (int i = LO; i < HI; ++i) { const int ai = i >> 3, m = (i >> 1) & 3, n = i & 1; const unsigned row = row0 + ai * HALF + m * 16;
;             *(f32x4*)(Y + (row * (unsigned)DM + col0 + BJ * HALF + n * 16)) = acc[ai][BJ][m][n] + ((r[i - LO] - mean[(i - LO) >> 1]) * rstd[(i - LO) >> 1]) * gv[n] + bv[n]; }
	v_pk_fma_f32 v[130:131], v[98:99], s[78:79], v[130:131] op_sel_hi:[1,0,1]
	v_pk_fma_f32 v[128:129], v[96:97], s[78:79], v[128:129] op_sel_hi:[1,0,1]
	global_store_dwordx4 v[132:133], v[128:131], off
	s_nop 1
	v_sub_f32_e32 v129, v215, v196
	v_sub_f32_e32 v128, v214, v196
	v_sub_f32_e32 v131, v217, v196
	v_sub_f32_e32 v130, v216, v196
	v_pk_mul_f32 v[130:131], v[196:197], v[130:131] op_sel:[1,0]
	v_pk_mul_f32 v[128:129], v[196:197], v[128:129] op_sel:[1,0]
	v_pk_fma_f32 v[126:127], v[192:193], v[130:131], v[126:127]
	v_pk_fma_f32 v[124:125], v[194:195], v[128:129], v[124:125]
	v_add_u32_e32 v128, 0x8000, v148
	v_mov_b32_e32 v129, v159
	v_pk_fma_f32 v[126:127], v[102:103], s[78:79], v[126:127] op_sel_hi:[1,0,1]
	v_pk_fma_f32 v[124:125], v[100:101], s[78:79], v[124:125] op_sel_hi:[1,0,1]
	v_lshl_add_u64 v[128:129], v[128:129], 2, s[88:89]
	global_store_dwordx4 v[128:129], v[124:127], off
	s_nop 1
	v_sub_f32_e32 v125, v137, v196
	v_sub_f32_e32 v124, v136, v196
	v_sub_f32_e32 v127, v139, v196
	v_sub_f32_e32 v126, v138, v196
	v_pk_mul_f32 v[126:127], v[196:197], v[126:127] op_sel:[1,0]
	v_pk_mul_f32 v[124:125], v[196:197], v[124:125] op_sel:[1,0]
	v_pk_fma_f32 v[122:123], v[188:189], v[126:127], v[122:123]
	v_pk_fma_f32 v[120:121], v[190:191], v[124:125], v[120:121]
	v_add_u32_e32 v124, 0x8010, v148
	v_mov_b32_e32 v125, v159
	v_pk_fma_f32 v[122:123], v[98:99], s[78:79], v[122:123] op_sel_hi:[1,0,1]
	v_pk_fma_f32 v[120:121], v[96:97], s[78:79], v[120:121] op_sel_hi:[1,0,1]
	v_lshl_add_u64 v[124:125], v[124:125], 2, s[88:89]
	global_store_dwordx4 v[124:125], v[120:123], off
	s_nop 1
	v_or_b32_e32 v122, 32, v203
	v_lshlrev_b32_e32 v124, 11, v122
	v_lshlrev_b32_e32 v120, 1, v122
	v_mov_b32_e32 v121, v159
	v_add_u32_e32 v122, v124, v158
	v_mov_b32_e32 v123, v159
	v_lshl_add_u64 v[120:121], v[120:121], 2, s[96:97]
	v_lshl_add_u64 v[122:123], v[122:123], 2, s[90:91]
	global_load_dwordx2 v[138:139], v[120:121], off
	global_load_dwordx4 v[126:129], v[122:123], off
	v_add_u32_e32 v122, v124, v204
	v_mov_b32_e32 v123, v159
	v_lshl_add_u64 v[122:123], v[122:123], 2, s[90:91]
	global_load_dwordx4 v[130:133], v[122:123], off
	v_or_b32_e32 v125, 48, v203
	v_lshlrev_b32_e32 v122, 1, v125
	v_lshlrev_b32_e32 v125, 11, v125
	v_mov_b32_e32 v123, v159
	v_add_u32_e32 v134, v125, v158
	v_mov_b32_e32 v135, v159
	v_lshl_add_u64 v[122:123], v[122:123], 2, s[96:97]
	v_lshl_add_u64 v[134:135], v[134:135], 2, s[90:91]
	global_load_dwordx2 v[196:197], v[122:123], off
	v_add_u32_e32 v206, v125, v204
	global_load_dwordx4 v[134:137], v[134:135], off
	v_mov_b32_e32 v207, v159
	v_lshl_add_u64 v[206:207], v[206:207], 2, s[90:91]
	global_load_dwordx4 v[206:209], v[206:207], off
	s_waitcnt vmcnt(0)
	v_sub_f32_e32 v127, v127, v138
	v_sub_f32_e32 v126, v126, v138
	v_sub_f32_e32 v129, v129, v138
	v_sub_f32_e32 v128, v128, v138
	v_pk_mul_f32 v[128:129], v[138:139], v[128:129] op_sel:[1,0]
	v_pk_mul_f32 v[126:127], v[138:139], v[126:127] op_sel:[1,0]
	v_pk_fma_f32 v[118:119], v[192:193], v[128:129], v[118:119]
	v_pk_fma_f32 v[116:117], v[194:195], v[126:127], v[116:117]
	v_add_u32_e32 v126, 0x10000, v148
	v_mov_b32_e32 v127, v159
	v_pk_fma_f32 v[118:119], v[102:103], s[78:79], v[118:119] op_sel_hi:[1,0,1]
	v_pk_fma_f32 v[116:117], v[100:101], s[78:79], v[116:117] op_sel_hi:[1,0,1]
	v_lshl_add_u64 v[126:127], v[126:127], 2, s[88:89]
	global_store_dwordx4 v[126:127], v[116:119], off
	s_nop 1
	v_sub_f32_e32 v117, v131, v138
	v_sub_f32_e32 v116, v130, v138
	v_sub_f32_e32 v119, v133, v138
	v_sub_f32_e32 v118, v132, v138
	v_pk_mul_f32 v[118:119], v[138:139], v[118:119] op_sel:[1,0]
	v_pk_mul_f32 v[116:117], v[138:139], v[116:117] op_sel:[1,0]
	v_pk_fma_f32 v[114:115], v[188:189], v[118:119], v[114:115]
	v_pk_fma_f32 v[112:113], v[190:191], v[116:117], v[112:113]
	v_add_u32_e32 v116, 0x10010, v148
	v_mov_b32_e32 v117, v159
	v_pk_fma_f32 v[114:115], v[98:99], s[78:79], v[114:115] op_sel_hi:[1,0,1]
	v_pk_fma_f32 v[112:113], v[96:97], s[78:79], v[112:113] op_sel_hi:[1,0,1]
	v_lshl_add_u64 v[116:117], v[116:117], 2, s[88:89]
	global_store_dwordx4 v[116:117], v[112:115], off
	s_nop 1
	v_sub_f32_e32 v113, v135, v196
	v_sub_f32_e32 v112, v134, v196
	v_sub_f32_e32 v115, v137, v196
	v_sub_f32_e32 v114, v136, v196
	v_pk_mul_f32 v[114:115], v[196:197], v[114:115] op_sel:[1,0]
	v_pk_mul_f32 v[112:113], v[196:197], v[112:113] op_sel:[1,0]
	v_pk_fma_f32 v[110:111], v[192:193], v[114:115], v[110:111]
	v_pk_fma_f32 v[108:109], v[194:195], v[112:113], v[108:109]
	v_add_u32_e32 v112, 0x18000, v148
	v_mov_b32_e32 v113, v159
	v_pk_fma_f32 v[110:111], v[102:103], s[78:79], v[110:111] op_sel_hi:[1,0,1]
	v_pk_fma_f32 v[108:109], v[100:101], s[78:79], v[108:109] op_sel_hi:[1,0,1]
	v_lshl_add_u64 v[112:113], v[112:113], 2, s[88:89]
	global_store_dwordx4 v[112:113], v[108:111], off
	s_nop 1
	v_sub_f32_e32 v109, v207, v196
	v_sub_f32_e32 v108, v206, v196
	v_sub_f32_e32 v111, v209, v196
	v_sub_f32_e32 v110, v208, v196
	v_pk_mul_f32 v[110:111], v[196:197], v[110:111] op_sel:[1,0]
	v_pk_mul_f32 v[108:109], v[196:197], v[108:109] op_sel:[1,0]
	v_pk_fma_f32 v[106:107], v[188:189], v[110:111], v[106:107]
	v_pk_fma_f32 v[104:105], v[190:191], v[108:109], v[104:105]
	v_add_u32_e32 v108, 0x18010, v148
	v_mov_b32_e32 v109, v159
	v_pk_fma_f32 v[106:107], v[98:99], s[78:79], v[106:107] op_sel_hi:[1,0,1]
	v_pk_fma_f32 v[104:105], v[96:97], s[78:79], v[104:105] op_sel_hi:[1,0,1]
	v_lshl_add_u64 v[108:109], v[108:109], 2, s[88:89]
	global_store_dwordx4 v[108:109], v[104:107], off
	s_nop 1
	v_add_u32_e32 v106, 0x80, v203
	v_lshlrev_b32_e32 v114, 11, v106
	v_lshlrev_b32_e32 v104, 1, v106
	v_mov_b32_e32 v105, v159
	v_add_u32_e32 v106, v114, v158
	v_mov_b32_e32 v107, v159
	v_lshl_add_u64 v[104:105], v[104:105], 2, s[96:97]
	v_lshl_add_u64 v[106:107], v[106:107], 2, s[90:91]
	global_load_dwordx2 v[112:113], v[104:105], off
	global_load_dwordx4 v[108:111], v[106:107], off
	v_add_u32_e32 v106, v114, v204
	v_mov_b32_e32 v107, v159
	v_lshl_add_u64 v[106:107], v[106:107], 2, s[90:91]
	global_load_dwordx4 v[116:119], v[106:107], off
	v_add_u32_e32 v115, 0x90, v203
	v_lshlrev_b32_e32 v106, 1, v115
	v_lshlrev_b32_e32 v115, 11, v115
	v_mov_b32_e32 v107, v159
	v_add_u32_e32 v126, v115, v158
	v_mov_b32_e32 v127, v159
	v_lshl_add_u64 v[106:107], v[106:107], 2, s[96:97]
	v_lshl_add_u64 v[126:127], v[126:127], 2, s[90:91]
	global_load_dwordx2 v[134:135], v[106:107], off
	v_add_u32_e32 v130, v115, v204
	global_load_dwordx4 v[126:129], v[126:127], off
	v_mov_b32_e32 v131, v159
	v_lshl_add_u64 v[130:131], v[130:131], 2, s[90:91]
	global_load_dwordx4 v[130:133], v[130:131], off
	s_waitcnt vmcnt(0)
;     template <bool LN, int BJ, int LO, int HI> DI void batch(const f32x4 (&acc)[2][2][4][2], unsigned row0, unsigned col0, const f32x4 (&gv)[2], const f32x4 (&bv)[2]) const {
;         f32x4 r[HI - LO]; float mean[(HI - LO) / 2], rstd[(HI - LO) / 2];
; #pragma unroll
;         for (int i = LO; i < HI; ++i) { const int ai = i >> 3, m = (i >> 1) & 3, n = i & 1; const unsigned row = row0 + ai * HALF + m * 16;
;             if (n == 0) { mean[(i - LO) >> 1] = 0.f; rstd[(i - LO) >> 1] = 1.f;
;                 if (LN) { const float2 st = *(const float2*)(stats + row * 2u); mean[(i - LO) >> 1] = st.x; rstd[(i - LO) >> 1] = st.y; } }
;             r[i - LO] = *(const f32x4*)(src + (row * (unsigned)DM + col0 + BJ * HALF + n * 16)); }
; #pragma unroll
;         for (int i = LO; i < HI; ++i) { const int ai = i >> 3, m = (i >> 1) & 3, n = i & 1; const unsigned row = row0 + ai * HALF + m * 16;
;             *(f32x4*)(Y + (row * (unsigned)DM + col0 + BJ * HALF + n * 16)) = acc[ai][BJ][m][n] + ((r[i - LO] - mean[(i - LO) >> 1]) * rstd[(i - LO) >> 1]) * gv[n] + bv[n]; }
	v_sub_f32_e32 v109, v109, v112
	v_sub_f32_e32 v108, v108, v112
	v_sub_f32_e32 v111, v111, v112
	v_sub_f32_e32 v110, v110, v112
	v_pk_mul_f32 v[110:111], v[112:113], v[110:111] op_sel:[1,0]
	v_pk_mul_f32 v[108:109], v[112:113], v[108:109] op_sel:[1,0]
	v_pk_fma_f32 v[94:95], v[192:193], v[110:111], v[94:95]
	v_pk_fma_f32 v[92:93], v[194:195], v[108:109], v[92:93]
	v_add_u32_e32 v108, 0x40000, v148
	v_mov_b32_e32 v109, v159
	v_pk_fma_f32 v[94:95], v[102:103], s[78:79], v[94:95] op_sel_hi:[1,0,1]
	v_pk_fma_f32 v[92:93], v[100:101], s[78:79], v[92:93] op_sel_hi:[1,0,1]
	v_lshl_add_u64 v[108:109], v[108:109], 2, s[88:89]
	global_store_dwordx4 v[108:109], v[92:95], off
	s_nop 1
	v_sub_f32_e32 v93, v117, v112
	v_sub_f32_e32 v92, v116, v112
	v_sub_f32_e32 v95, v119, v112
	v_sub_f32_e32 v94, v118, v112
	v_pk_mul_f32 v[94:95], v[112:113], v[94:95] op_sel:[1,0]
	v_pk_mul_f32 v[92:93], v[112:113], v[92:93] op_sel:[1,0]
	v_pk_fma_f32 v[90:91], v[188:189], v[94:95], v[90:91]
	v_pk_fma_f32 v[88:89], v[190:191], v[92:93], v[88:89]
	v_add_u32_e32 v92, 0x40010, v148
	v_mov_b32_e32 v93, v159
	v_pk_fma_f32 v[90:91], v[98:99], s[78:79], v[90:91] op_sel_hi:[1,0,1]
	v_pk_fma_f32 v[88:89], v[96:97], s[78:79], v[88:89] op_sel_hi:[1,0,1]
	v_lshl_add_u64 v[92:93], v[92:93], 2, s[88:89]
	global_store_dwordx4 v[92:93], v[88:91], off
	s_nop 1
	v_sub_f32_e32 v89, v127, v134
	v_sub_f32_e32 v88, v126, v134
	v_sub_f32_e32 v91, v129, v134
	v_sub_f32_e32 v90, v128, v134
	v_pk_mul_f32 v[90:91], v[134:135], v[90:91] op_sel:[1,0]
	v_pk_mul_f32 v[88:89], v[134:135], v[88:89] op_sel:[1,0]
	v_pk_fma_f32 v[86:87], v[192:193], v[90:91], v[86:87]
	v_pk_fma_f32 v[84:85], v[194:195], v[88:89], v[84:85]
	v_add_u32_e32 v88, 0x48000, v148
	v_mov_b32_e32 v89, v159
	v_pk_fma_f32 v[86:87], v[102:103], s[78:79], v[86:87] op_sel_hi:[1,0,1]
	v_pk_fma_f32 v[84:85], v[100:101], s[78:79], v[84:85] op_sel_hi:[1,0,1]
	v_lshl_add_u64 v[88:89], v[88:89], 2, s[88:89]
	global_store_dwordx4 v[88:89], v[84:87], off
	s_nop 1
	v_sub_f32_e32 v85, v131, v134
	v_sub_f32_e32 v84, v130, v134
	v_sub_f32_e32 v87, v133, v134
	v_sub_f32_e32 v86, v132, v134
	v_pk_mul_f32 v[86:87], v[134:135], v[86:87] op_sel:[1,0]
	v_pk_mul_f32 v[84:85], v[134:135], v[84:85] op_sel:[1,0]
	v_pk_fma_f32 v[82:83], v[188:189], v[86:87], v[82:83]
	v_pk_fma_f32 v[80:81], v[190:191], v[84:85], v[80:81]
	v_add_u32_e32 v84, 0x48010, v148
	v_mov_b32_e32 v85, v159
	v_pk_fma_f32 v[82:83], v[98:99], s[78:79], v[82:83] op_sel_hi:[1,0,1]
	v_pk_fma_f32 v[80:81], v[96:97], s[78:79], v[80:81] op_sel_hi:[1,0,1]
	v_lshl_add_u64 v[84:85], v[84:85], 2, s[88:89]
	global_store_dwordx4 v[84:85], v[80:83], off
	s_nop 1
	v_add_u32_e32 v82, 0xa0, v203
	v_lshlrev_b32_e32 v80, 1, v82
	v_mov_b32_e32 v81, v159
	v_lshlrev_b32_e32 v116, 11, v82
	v_lshl_add_u64 v[108:109], v[80:81], 2, s[96:97]
	v_add_u32_e32 v80, v116, v158
	v_lshl_add_u64 v[80:81], v[80:81], 2, s[90:91]
	global_load_dwordx2 v[112:113], v[108:109], off
	v_add_u32_e32 v84, v116, v204
	global_load_dwordx4 v[80:83], v[80:81], off
	v_mov_b32_e32 v85, v159
	v_lshl_add_u64 v[84:85], v[84:85], 2, s[90:91]
	global_load_dwordx4 v[84:87], v[84:85], off
	v_add_u32_e32 v90, 0xb0, v203
	v_lshlrev_b32_e32 v88, 1, v90
	v_mov_b32_e32 v89, v159
	v_lshlrev_b32_e32 v117, 11, v90
	v_lshl_add_u64 v[110:111], v[88:89], 2, s[96:97]
	v_add_u32_e32 v88, v117, v158
	v_lshl_add_u64 v[88:89], v[88:89], 2, s[90:91]
	global_load_dwordx2 v[118:119], v[110:111], off
	v_add_u32_e32 v92, v117, v204
	global_load_dwordx4 v[88:91], v[88:89], off
	v_mov_b32_e32 v93, v159
	v_lshl_add_u64 v[92:93], v[92:93], 2, s[90:91]
	global_load_dwordx4 v[92:95], v[92:93], off
	s_waitcnt vmcnt(0)
	v_sub_f32_e32 v81, v81, v112
	v_sub_f32_e32 v80, v80, v112
	v_sub_f32_e32 v83, v83, v112
	v_sub_f32_e32 v82, v82, v112
	v_pk_mul_f32 v[82:83], v[112:113], v[82:83] op_sel:[1,0]
	v_pk_mul_f32 v[80:81], v[112:113], v[80:81] op_sel:[1,0]
	v_pk_fma_f32 v[78:79], v[192:193], v[82:83], v[78:79]
	v_pk_fma_f32 v[76:77], v[194:195], v[80:81], v[76:77]
	v_add_u32_e32 v80, 0x50000, v148
	v_mov_b32_e32 v81, v159
	v_pk_fma_f32 v[78:79], v[102:103], s[78:79], v[78:79] op_sel_hi:[1,0,1]
	v_pk_fma_f32 v[76:77], v[100:101], s[78:79], v[76:77] op_sel_hi:[1,0,1]
	v_lshl_add_u64 v[80:81], v[80:81], 2, s[88:89]
	global_store_dwordx4 v[80:81], v[76:79], off
	s_nop 1
	v_sub_f32_e32 v77, v85, v112
	v_sub_f32_e32 v76, v84, v112
	v_sub_f32_e32 v79, v87, v112
	v_sub_f32_e32 v78, v86, v112
	v_pk_mul_f32 v[78:79], v[112:113], v[78:79] op_sel:[1,0]
	v_pk_mul_f32 v[76:77], v[112:113], v[76:77] op_sel:[1,0]
	v_pk_fma_f32 v[74:75], v[188:189], v[78:79], v[74:75]
	v_pk_fma_f32 v[72:73], v[190:191], v[76:77], v[72:73]
	v_add_u32_e32 v76, 0x50010, v148
	v_mov_b32_e32 v77, v159
	v_pk_fma_f32 v[74:75], v[98:99], s[78:79], v[74:75] op_sel_hi:[1,0,1]
	v_pk_fma_f32 v[72:73], v[96:97], s[78:79], v[72:73] op_sel_hi:[1,0,1]
	v_lshl_add_u64 v[76:77], v[76:77], 2, s[88:89]
	global_store_dwordx4 v[76:77], v[72:75], off
	s_nop 1
	v_sub_f32_e32 v73, v89, v118
	v_sub_f32_e32 v72, v88, v118
	v_sub_f32_e32 v75, v91, v118
	v_sub_f32_e32 v74, v90, v118
	v_pk_mul_f32 v[74:75], v[118:119], v[74:75] op_sel:[1,0]
	v_pk_mul_f32 v[72:73], v[118:119], v[72:73] op_sel:[1,0]
	v_pk_fma_f32 v[70:71], v[192:193], v[74:75], v[70:71]
	v_pk_fma_f32 v[68:69], v[194:195], v[72:73], v[68:69]
	v_add_u32_e32 v72, 0x58000, v148
	v_mov_b32_e32 v73, v159
	v_pk_fma_f32 v[70:71], v[102:103], s[78:79], v[70:71] op_sel_hi:[1,0,1]
	v_pk_fma_f32 v[68:69], v[100:101], s[78:79], v[68:69] op_sel_hi:[1,0,1]
	v_lshl_add_u64 v[72:73], v[72:73], 2, s[88:89]
	global_store_dwordx4 v[72:73], v[68:71], off
	s_nop 1
	v_sub_f32_e32 v69, v93, v118
	v_sub_f32_e32 v68, v92, v118
	v_sub_f32_e32 v71, v95, v118
	v_sub_f32_e32 v70, v94, v118
	v_pk_mul_f32 v[70:71], v[118:119], v[70:71] op_sel:[1,0]
	v_pk_mul_f32 v[68:69], v[118:119], v[68:69] op_sel:[1,0]
	v_pk_fma_f32 v[66:67], v[188:189], v[70:71], v[66:67]
	v_pk_fma_f32 v[64:65], v[190:191], v[68:69], v[64:65]
	v_add_u32_e32 v68, 0x58010, v148
	v_mov_b32_e32 v69, v159
	v_pk_fma_f32 v[66:67], v[98:99], s[78:79], v[66:67] op_sel_hi:[1,0,1]
	v_pk_fma_f32 v[64:65], v[96:97], s[78:79], v[64:65] op_sel_hi:[1,0,1]
	v_lshl_add_u64 v[68:69], v[68:69], 2, s[88:89]
	global_store_dwordx4 v[68:69], v[64:67], off
	global_load_dwordx4 v[64:67], v[150:151], off offset:512
	v_or_b32_e32 v119, 0x80, v158
	v_add_u32_e32 v72, v202, v119
	v_mov_b32_e32 v73, v159
	v_lshl_add_u64 v[72:73], v[72:73], 2, s[90:91]
	v_or_b32_e32 v118, 0x90, v158
	v_add_u32_e32 v158, v202, v118
	s_waitcnt vmcnt(0)
;     template <bool LN, int BJ, int LO, int HI> DI void batch(const f32x4 (&acc)[2][2][4][2], unsigned row0, unsigned col0, const f32x4 (&gv)[2], const f32x4 (&bv)[2]) const {
;         f32x4 r[HI - LO]; float mean[(HI - LO) / 2], rstd[(HI - LO) / 2];
; #pragma unroll
;         for (int i = LO; i < HI; ++i) { const int ai = i >> 3, m = (i >> 1) & 3, n = i & 1; const unsigned row = row0 + ai * HALF + m * 16;
;             if (n == 0) { mean[(i - LO) >> 1] = 0.f; rstd[(i - LO) >> 1] = 1.f;
;                 if (LN) { const float2 st = *(const float2*)(stats + row * 2u); mean[(i - LO) >> 1] = st.x; rstd[(i - LO) >> 1] = st.y; } }
;             r[i - LO] = *(const f32x4*)(src + (row * (unsigned)DM + col0 + BJ * HALF + n * 16)); }
; #pragma unroll
;         for (int i = LO; i < HI; ++i) { const int ai = i >> 3, m = (i >> 1) & 3, n = i & 1; const unsigned row = row0 + ai * HALF + m * 16;
;             *(f32x4*)(Y + (row * (unsigned)DM + col0 + BJ * HALF + n * 16)) = acc[ai][BJ][m][n] + ((r[i - LO] - mean[(i - LO) >> 1]) * rstd[(i - LO) >> 1]) * gv[n] + bv[n]; }
;         __builtin_amdgcn_sched_barrier(0);
;     }
;     template <bool LN, int BJ> DI void load_gb(unsigned col0, f32x4 (&gv)[2], f32x4 (&bv)[2]) const {
; #pragma unroll
;         for (int n = 0; n < 2; ++n) {
;             if (LN) { gv[n] = *(const f32x4*)(gam + col0 + BJ * HALF + n * 16) * ALPHA; bv[n] = *(const f32x4*)(bet + col0 + BJ * HALF + n * 16) * ALPHA; }
;             else { gv[n] = (f32x4){ALPHA, ALPHA, ALPHA, ALPHA}; bv[n] = (f32x4){0.f, 0.f, 0.f, 0.f}; }
;         }
;     }
;     template <bool LN> DI void run(const f32x4 (&acc)[2][2][4][2], const Unit& u, int wr, int wc, int fr, int fq) const {
;         const unsigned row0 = u.pm * BM + wr * 64 + fr, col0 = u.pn * BM + wc * 32 + 4 * fq;
;         f32x4 gv[2], bv[2];
;         load_gb<LN, 0>(col0, gv, bv);
;         batch<LN, 0, 0, 4>(acc, row0, col0, gv, bv);
;         batch<LN, 0, 4, 8>(acc, row0, col0, gv, bv);
;         batch<LN, 0, 8, 12>(acc, row0, col0, gv, bv);
;         batch<LN, 0, 12, 16>(acc, row0, col0, gv, bv);
;         load_gb<LN, 1>(col0, gv, bv);
;         batch<LN, 1, 0, 8>(acc, row0, col0, gv, bv);
	v_pk_mul_f32 v[96:97], v[66:67], s[78:79] op_sel_hi:[1,0]
	v_pk_mul_f32 v[98:99], v[64:65], s[78:79] op_sel_hi:[1,0]
	global_load_dwordx4 v[68:71], v[152:153], off offset:512
	global_load_dwordx4 v[64:67], v[150:151], off offset:576
	global_load_dwordx2 v[138:139], v[154:155], off
	global_load_dwordx4 v[126:129], v[72:73], off
	v_lshl_add_u64 v[72:73], v[158:159], 2, s[90:91]
	v_add_u32_e32 v158, v149, v119
	s_waitcnt vmcnt(0)
	v_pk_mul_f32 v[92:93], v[66:67], s[78:79] op_sel_hi:[1,0]
	v_pk_mul_f32 v[94:95], v[64:65], s[78:79] op_sel_hi:[1,0]
	global_load_dwordx4 v[64:67], v[152:153], off offset:576
	global_load_dwordx4 v[130:133], v[72:73], off
	global_load_dwordx2 v[112:113], v[186:187], off
	v_lshl_add_u64 v[72:73], v[158:159], 2, s[90:91]
	global_load_dwordx4 v[134:137], v[72:73], off
	v_add_u32_e32 v158, v149, v118
	v_lshl_add_u64 v[72:73], v[158:159], 2, s[90:91]
	global_load_dwordx4 v[88:91], v[72:73], off
	global_load_dwordx2 v[102:103], v[120:121], off
	v_add_u32_e32 v158, v124, v119
	v_lshl_add_u64 v[72:73], v[158:159], 2, s[90:91]
	global_load_dwordx4 v[84:87], v[72:73], off
	v_add_u32_e32 v158, v124, v118
	v_lshl_add_u64 v[72:73], v[158:159], 2, s[90:91]
	global_load_dwordx4 v[80:83], v[72:73], off
	global_load_dwordx2 v[100:101], v[122:123], off
	v_add_u32_e32 v158, v125, v119
	v_lshl_add_u64 v[72:73], v[158:159], 2, s[90:91]
	global_load_dwordx4 v[76:79], v[72:73], off
	v_add_u32_e32 v158, v125, v118
	v_lshl_add_u64 v[72:73], v[158:159], 2, s[90:91]
	global_load_dwordx4 v[72:75], v[72:73], off
	v_sub_f32_e32 v121, v127, v138
	v_sub_f32_e32 v120, v126, v138
	v_sub_f32_e32 v123, v129, v138
	v_sub_f32_e32 v122, v128, v138
	v_pk_mul_f32 v[122:123], v[138:139], v[122:123] op_sel:[1,0]
	v_pk_mul_f32 v[120:121], v[138:139], v[120:121] op_sel:[1,0]
	v_or_b32_e32 v158, 0x80, v148
	v_pk_fma_f32 v[60:61], v[98:99], v[120:121], v[60:61]
	v_pk_fma_f32 v[62:63], v[96:97], v[122:123], v[62:63]
	v_pk_fma_f32 v[60:61], v[68:69], s[78:79], v[60:61] op_sel_hi:[1,0,1]
	v_pk_fma_f32 v[62:63], v[70:71], s[78:79], v[62:63] op_sel_hi:[1,0,1]
	v_lshl_add_u64 v[120:121], v[158:159], 2, s[88:89]
	global_store_dwordx4 v[120:121], v[60:63], off
	v_or_b32_e32 v158, 0x90, v148
	s_waitcnt vmcnt(0)
	v_sub_f32_e32 v61, v131, v138
	v_sub_f32_e32 v60, v130, v138
	v_sub_f32_e32 v63, v133, v138
	v_sub_f32_e32 v62, v132, v138
	v_pk_mul_f32 v[62:63], v[138:139], v[62:63] op_sel:[1,0]
	v_pk_mul_f32 v[60:61], v[138:139], v[60:61] op_sel:[1,0]
	v_pk_fma_f32 v[58:59], v[92:93], v[62:63], v[58:59]
	v_pk_fma_f32 v[56:57], v[94:95], v[60:61], v[56:57]
	v_pk_fma_f32 v[58:59], v[66:67], s[78:79], v[58:59] op_sel_hi:[1,0,1]
	v_pk_fma_f32 v[56:57], v[64:65], s[78:79], v[56:57] op_sel_hi:[1,0,1]
	v_lshl_add_u64 v[60:61], v[158:159], 2, s[88:89]
	global_store_dwordx4 v[60:61], v[56:59], off
	v_add_u32_e32 v158, 0x8080, v148
	s_nop 0
	v_sub_f32_e32 v57, v135, v112
	v_sub_f32_e32 v56, v134, v112
	v_sub_f32_e32 v59, v137, v112
	v_sub_f32_e32 v58, v136, v112
	v_pk_mul_f32 v[58:59], v[112:113], v[58:59] op_sel:[1,0]
	v_pk_mul_f32 v[56:57], v[112:113], v[56:57] op_sel:[1,0]
	v_pk_fma_f32 v[54:55], v[96:97], v[58:59], v[54:55]
	v_pk_fma_f32 v[52:53], v[98:99], v[56:57], v[52:53]
	v_pk_fma_f32 v[54:55], v[70:71], s[78:79], v[54:55] op_sel_hi:[1,0,1]
	v_pk_fma_f32 v[52:53], v[68:69], s[78:79], v[52:53] op_sel_hi:[1,0,1]
	v_lshl_add_u64 v[56:57], v[158:159], 2, s[88:89]
	global_store_dwordx4 v[56:57], v[52:55], off
	v_add_u32_e32 v158, 0x8090, v148
	s_nop 0
	v_sub_f32_e32 v53, v89, v112
	v_sub_f32_e32 v52, v88, v112
	v_sub_f32_e32 v55, v91, v112
	v_sub_f32_e32 v54, v90, v112
	v_pk_mul_f32 v[54:55], v[112:113], v[54:55] op_sel:[1,0]
	v_pk_mul_f32 v[52:53], v[112:113], v[52:53] op_sel:[1,0]
	v_pk_fma_f32 v[50:51], v[92:93], v[54:55], v[50:51]
	v_pk_fma_f32 v[48:49], v[94:95], v[52:53], v[48:49]
	v_pk_fma_f32 v[50:51], v[66:67], s[78:79], v[50:51] op_sel_hi:[1,0,1]
	v_pk_fma_f32 v[48:49], v[64:65], s[78:79], v[48:49] op_sel_hi:[1,0,1]
	v_lshl_add_u64 v[52:53], v[158:159], 2, s[88:89]
	global_store_dwordx4 v[52:53], v[48:51], off
	v_add_u32_e32 v158, 0x10080, v148
	s_nop 0
	v_sub_f32_e32 v49, v85, v102
	v_sub_f32_e32 v48, v84, v102
	v_sub_f32_e32 v51, v87, v102
	v_sub_f32_e32 v50, v86, v102
	v_pk_mul_f32 v[50:51], v[102:103], v[50:51] op_sel:[1,0]
	v_pk_mul_f32 v[48:49], v[102:103], v[48:49] op_sel:[1,0]
	v_pk_fma_f32 v[46:47], v[96:97], v[50:51], v[46:47]
	v_pk_fma_f32 v[44:45], v[98:99], v[48:49], v[44:45]
	v_pk_fma_f32 v[46:47], v[70:71], s[78:79], v[46:47] op_sel_hi:[1,0,1]
	v_pk_fma_f32 v[44:45], v[68:69], s[78:79], v[44:45] op_sel_hi:[1,0,1]
	v_lshl_add_u64 v[48:49], v[158:159], 2, s[88:89]
	global_store_dwordx4 v[48:49], v[44:47], off
	v_add_u32_e32 v158, 0x10090, v148
	s_nop 0
	v_sub_f32_e32 v45, v81, v102
	v_sub_f32_e32 v44, v80, v102
	v_sub_f32_e32 v47, v83, v102
	v_sub_f32_e32 v46, v82, v102
	v_pk_mul_f32 v[46:47], v[102:103], v[46:47] op_sel:[1,0]
	v_pk_mul_f32 v[44:45], v[102:103], v[44:45] op_sel:[1,0]
	v_pk_fma_f32 v[42:43], v[92:93], v[46:47], v[42:43]
	v_pk_fma_f32 v[40:41], v[94:95], v[44:45], v[40:41]
	v_pk_fma_f32 v[42:43], v[66:67], s[78:79], v[42:43] op_sel_hi:[1,0,1]
	v_pk_fma_f32 v[40:41], v[64:65], s[78:79], v[40:41] op_sel_hi:[1,0,1]
	v_lshl_add_u64 v[44:45], v[158:159], 2, s[88:89]
	global_store_dwordx4 v[44:45], v[40:43], off
	v_add_u32_e32 v158, 0x18080, v148
	s_nop 0
	v_sub_f32_e32 v41, v77, v100
	v_sub_f32_e32 v40, v76, v100
	v_sub_f32_e32 v43, v79, v100
	v_sub_f32_e32 v42, v78, v100
	v_pk_mul_f32 v[42:43], v[100:101], v[42:43] op_sel:[1,0]
	v_pk_mul_f32 v[40:41], v[100:101], v[40:41] op_sel:[1,0]
	v_pk_fma_f32 v[38:39], v[96:97], v[42:43], v[38:39]
;     template <bool LN, int BJ, int LO, int HI> DI void batch(const f32x4 (&acc)[2][2][4][2], unsigned row0, unsigned col0, const f32x4 (&gv)[2], const f32x4 (&bv)[2]) const {
;         f32x4 r[HI - LO]; float mean[(HI - LO) / 2], rstd[(HI - LO) / 2];
; #pragma unroll
;         for (int i = LO; i < HI; ++i) { const int ai = i >> 3, m = (i >> 1) & 3, n = i & 1; const unsigned row = row0 + ai * HALF + m * 16;
;             if (n == 0) { mean[(i - LO) >> 1] = 0.f; rstd[(i - LO) >> 1] = 1.f;
;                 if (LN) { const float2 st = *(const float2*)(stats + row * 2u); mean[(i - LO) >> 1] = st.x; rstd[(i - LO) >> 1] = st.y; } }
;             r[i - LO] = *(const f32x4*)(src + (row * (unsigned)DM + col0 + BJ * HALF + n * 16)); }
; #pragma unroll
;         for (int i = LO; i < HI; ++i) { const int ai = i >> 3, m = (i >> 1) & 3, n = i & 1; const unsigned row = row0 + ai * HALF + m * 16;
;             *(f32x4*)(Y + (row * (unsigned)DM + col0 + BJ * HALF + n * 16)) = acc[ai][BJ][m][n] + ((r[i - LO] - mean[(i - LO) >> 1]) * rstd[(i - LO) >> 1]) * gv[n] + bv[n]; }
	v_pk_fma_f32 v[36:37], v[98:99], v[40:41], v[36:37]
	v_pk_fma_f32 v[38:39], v[70:71], s[78:79], v[38:39] op_sel_hi:[1,0,1]
	v_pk_fma_f32 v[36:37], v[68:69], s[78:79], v[36:37] op_sel_hi:[1,0,1]
	v_lshl_add_u64 v[40:41], v[158:159], 2, s[88:89]
	global_store_dwordx4 v[40:41], v[36:39], off
	v_add_u32_e32 v158, 0x18090, v148
	s_nop 0
	v_sub_f32_e32 v37, v73, v100
	v_sub_f32_e32 v36, v72, v100
	v_sub_f32_e32 v39, v75, v100
	v_sub_f32_e32 v38, v74, v100
	v_pk_mul_f32 v[38:39], v[100:101], v[38:39] op_sel:[1,0]
	v_pk_mul_f32 v[36:37], v[100:101], v[36:37] op_sel:[1,0]
	v_pk_fma_f32 v[34:35], v[92:93], v[38:39], v[34:35]
	v_pk_fma_f32 v[32:33], v[94:95], v[36:37], v[32:33]
	v_pk_fma_f32 v[34:35], v[66:67], s[78:79], v[34:35] op_sel_hi:[1,0,1]
	v_pk_fma_f32 v[32:33], v[64:65], s[78:79], v[32:33] op_sel_hi:[1,0,1]
	v_lshl_add_u64 v[36:37], v[158:159], 2, s[88:89]
	global_store_dwordx4 v[36:37], v[32:35], off
	v_add_u32_e32 v158, v114, v119
	s_nop 0
	v_lshl_add_u64 v[32:33], v[158:159], 2, s[90:91]
	global_load_dwordx2 v[62:63], v[104:105], off
	global_load_dwordx4 v[54:57], v[32:33], off
	v_add_u32_e32 v158, v114, v118
	v_lshl_add_u64 v[32:33], v[158:159], 2, s[90:91]
	global_load_dwordx4 v[58:61], v[32:33], off
	global_load_dwordx2 v[52:53], v[106:107], off
	v_add_u32_e32 v158, v115, v119
	v_lshl_add_u64 v[32:33], v[158:159], 2, s[90:91]
	global_load_dwordx4 v[72:75], v[32:33], off
	v_add_u32_e32 v158, v115, v118
	v_lshl_add_u64 v[32:33], v[158:159], 2, s[90:91]
	global_load_dwordx4 v[76:79], v[32:33], off
	global_load_dwordx2 v[50:51], v[108:109], off
	v_add_u32_e32 v158, v116, v119
	v_lshl_add_u64 v[32:33], v[158:159], 2, s[90:91]
	global_load_dwordx4 v[44:47], v[32:33], off
	v_add_u32_e32 v158, v116, v118
	v_lshl_add_u64 v[32:33], v[158:159], 2, s[90:91]
	global_load_dwordx4 v[40:43], v[32:33], off
	global_load_dwordx2 v[48:49], v[110:111], off
	v_add_u32_e32 v158, v117, v119
	v_lshl_add_u64 v[32:33], v[158:159], 2, s[90:91]
	global_load_dwordx4 v[36:39], v[32:33], off
	v_add_u32_e32 v158, v117, v118
	v_lshl_add_u64 v[32:33], v[158:159], 2, s[90:91]
	global_load_dwordx4 v[32:35], v[32:33], off
	v_add_u32_e32 v158, 0x40080, v148
	s_waitcnt vmcnt(0)
; #define PG8_WAIT_V(n) asm volatile("s_waitcnt vmcnt(" #n ")" ::: "memory")
; #define PG8_BAR __builtin_amdgcn_s_barrier()
; template <class Epi>
; DI void gemm_phase(LAS unsigned char* lds, const Gemm g, const StaticOrder& S, const Epi& E) {
;     ...
;         if (!has_next) break;
; #pragma unroll
;         for (int a = 0; a < 2; ++a)
; #pragma unroll
;             for (int b = 0; b < 2; ++b)
; #pragma unroll
;                 for (int m = 0; m < 4; ++m)
; #pragma unroll
;                     for (int n = 0; n < 2; ++n) acc[a][b][m][n] = (f32x4){0.f, 0.f, 0.f, 0.f};
;         cur = nxt; cA = nA; cB = nB; ++ui;
;     }
;     PG8_WAIT_V(0);
;     if (wr == 0) PG8_BAR;
;     PG8_BAR;
;     template <bool LN, int BJ, int LO, int HI> DI void batch(const f32x4 (&acc)[2][2][4][2], unsigned row0, unsigned col0, const f32x4 (&gv)[2], const f32x4 (&bv)[2]) const {
;         f32x4 r[HI - LO]; float mean[(HI - LO) / 2], rstd[(HI - LO) / 2];
; #pragma unroll
;         for (int i = LO; i < HI; ++i) { const int ai = i >> 3, m = (i >> 1) & 3, n = i & 1; const unsigned row = row0 + ai * HALF + m * 16;
;             if (n == 0) { mean[(i - LO) >> 1] = 0.f; rstd[(i - LO) >> 1] = 1.f;
;                 if (LN) { const float2 st = *(const float2*)(stats + row * 2u); mean[(i - LO) >> 1] = st.x; rstd[(i - LO) >> 1] = st.y; } }
;             r[i - LO] = *(const f32x4*)(src + (row * (unsigned)DM + col0 + BJ * HALF + n * 16)); }
; #pragma unroll
;         for (int i = LO; i < HI; ++i) { const int ai = i >> 3, m = (i >> 1) & 3, n = i & 1; const unsigned row = row0 + ai * HALF + m * 16;
;             *(f32x4*)(Y + (row * (unsigned)DM + col0 + BJ * HALF + n * 16)) = acc[ai][BJ][m][n] + ((r[i - LO] - mean[(i - LO) >> 1]) * rstd[(i - LO) >> 1]) * gv[n] + bv[n]; }
	v_sub_f32_e32 v55, v55, v62
	v_sub_f32_e32 v54, v54, v62
	v_sub_f32_e32 v57, v57, v62
	v_sub_f32_e32 v56, v56, v62
	v_pk_mul_f32 v[56:57], v[62:63], v[56:57] op_sel:[1,0]
	v_pk_mul_f32 v[54:55], v[62:63], v[54:55] op_sel:[1,0]
	v_pk_fma_f32 v[30:31], v[96:97], v[56:57], v[30:31]
	v_pk_fma_f32 v[28:29], v[98:99], v[54:55], v[28:29]
	v_pk_fma_f32 v[30:31], v[70:71], s[78:79], v[30:31] op_sel_hi:[1,0,1]
	v_pk_fma_f32 v[28:29], v[68:69], s[78:79], v[28:29] op_sel_hi:[1,0,1]
	v_lshl_add_u64 v[54:55], v[158:159], 2, s[88:89]
	global_store_dwordx4 v[54:55], v[28:31], off
	v_add_u32_e32 v158, 0x40090, v148
	s_nop 0
	v_sub_f32_e32 v29, v59, v62
	v_sub_f32_e32 v28, v58, v62
	v_sub_f32_e32 v31, v61, v62
	v_sub_f32_e32 v30, v60, v62
	v_pk_mul_f32 v[30:31], v[62:63], v[30:31] op_sel:[1,0]
	v_pk_mul_f32 v[28:29], v[62:63], v[28:29] op_sel:[1,0]
	v_pk_fma_f32 v[26:27], v[92:93], v[30:31], v[26:27]
	v_pk_fma_f32 v[24:25], v[94:95], v[28:29], v[24:25]
	v_pk_fma_f32 v[26:27], v[66:67], s[78:79], v[26:27] op_sel_hi:[1,0,1]
	v_pk_fma_f32 v[24:25], v[64:65], s[78:79], v[24:25] op_sel_hi:[1,0,1]
	v_lshl_add_u64 v[28:29], v[158:159], 2, s[88:89]
	global_store_dwordx4 v[28:29], v[24:27], off
	v_add_u32_e32 v158, 0x48080, v148
	s_nop 0
	v_sub_f32_e32 v25, v73, v52
	v_sub_f32_e32 v24, v72, v52
	v_sub_f32_e32 v27, v75, v52
	v_sub_f32_e32 v26, v74, v52
	v_pk_mul_f32 v[26:27], v[52:53], v[26:27] op_sel:[1,0]
	v_pk_mul_f32 v[24:25], v[52:53], v[24:25] op_sel:[1,0]
	v_pk_fma_f32 v[22:23], v[96:97], v[26:27], v[22:23]
	v_pk_fma_f32 v[20:21], v[98:99], v[24:25], v[20:21]
	v_pk_fma_f32 v[22:23], v[70:71], s[78:79], v[22:23] op_sel_hi:[1,0,1]
	v_pk_fma_f32 v[20:21], v[68:69], s[78:79], v[20:21] op_sel_hi:[1,0,1]
	v_lshl_add_u64 v[24:25], v[158:159], 2, s[88:89]
	global_store_dwordx4 v[24:25], v[20:23], off
	v_add_u32_e32 v158, 0x48090, v148
	s_nop 0
	v_sub_f32_e32 v21, v77, v52
	v_sub_f32_e32 v20, v76, v52
	v_sub_f32_e32 v23, v79, v52
	v_sub_f32_e32 v22, v78, v52
	v_pk_mul_f32 v[22:23], v[52:53], v[22:23] op_sel:[1,0]
	v_pk_mul_f32 v[20:21], v[52:53], v[20:21] op_sel:[1,0]
	v_pk_fma_f32 v[18:19], v[92:93], v[22:23], v[18:19]
	v_pk_fma_f32 v[16:17], v[94:95], v[20:21], v[16:17]
	v_pk_fma_f32 v[18:19], v[66:67], s[78:79], v[18:19] op_sel_hi:[1,0,1]
	v_pk_fma_f32 v[16:17], v[64:65], s[78:79], v[16:17] op_sel_hi:[1,0,1]
	v_lshl_add_u64 v[20:21], v[158:159], 2, s[88:89]
	global_store_dwordx4 v[20:21], v[16:19], off
	v_add_u32_e32 v158, 0x50080, v148
	s_nop 0
	v_sub_f32_e32 v17, v45, v50
	v_sub_f32_e32 v16, v44, v50
	v_sub_f32_e32 v19, v47, v50
	v_sub_f32_e32 v18, v46, v50
	v_pk_mul_f32 v[18:19], v[50:51], v[18:19] op_sel:[1,0]
	v_pk_mul_f32 v[16:17], v[50:51], v[16:17] op_sel:[1,0]
	v_pk_fma_f32 v[14:15], v[96:97], v[18:19], v[14:15]
	v_pk_fma_f32 v[12:13], v[98:99], v[16:17], v[12:13]
	v_pk_fma_f32 v[14:15], v[70:71], s[78:79], v[14:15] op_sel_hi:[1,0,1]
	v_pk_fma_f32 v[12:13], v[68:69], s[78:79], v[12:13] op_sel_hi:[1,0,1]
	v_lshl_add_u64 v[16:17], v[158:159], 2, s[88:89]
	global_store_dwordx4 v[16:17], v[12:15], off
	v_add_u32_e32 v158, 0x50090, v148
	s_nop 0
	v_sub_f32_e32 v13, v41, v50
	v_sub_f32_e32 v12, v40, v50
	v_sub_f32_e32 v15, v43, v50
	v_sub_f32_e32 v14, v42, v50
	v_pk_mul_f32 v[14:15], v[50:51], v[14:15] op_sel:[1,0]
	v_pk_mul_f32 v[12:13], v[50:51], v[12:13] op_sel:[1,0]
	v_pk_fma_f32 v[10:11], v[92:93], v[14:15], v[10:11]
	v_pk_fma_f32 v[8:9], v[94:95], v[12:13], v[8:9]
	v_pk_fma_f32 v[10:11], v[66:67], s[78:79], v[10:11] op_sel_hi:[1,0,1]
	v_pk_fma_f32 v[8:9], v[64:65], s[78:79], v[8:9] op_sel_hi:[1,0,1]
	v_lshl_add_u64 v[12:13], v[158:159], 2, s[88:89]
	global_store_dwordx4 v[12:13], v[8:11], off
	v_add_u32_e32 v158, 0x58080, v148
	s_nop 0
	v_sub_f32_e32 v9, v37, v48
	v_sub_f32_e32 v8, v36, v48
	v_sub_f32_e32 v11, v39, v48
	v_sub_f32_e32 v10, v38, v48
	v_pk_mul_f32 v[10:11], v[48:49], v[10:11] op_sel:[1,0]
	v_pk_mul_f32 v[8:9], v[48:49], v[8:9] op_sel:[1,0]
	v_pk_fma_f32 v[6:7], v[96:97], v[10:11], v[6:7]
	v_pk_fma_f32 v[4:5], v[98:99], v[8:9], v[4:5]
	v_pk_fma_f32 v[6:7], v[70:71], s[78:79], v[6:7] op_sel_hi:[1,0,1]
	v_pk_fma_f32 v[4:5], v[68:69], s[78:79], v[4:5] op_sel_hi:[1,0,1]
	v_lshl_add_u64 v[8:9], v[158:159], 2, s[88:89]
	global_store_dwordx4 v[8:9], v[4:7], off
	v_add_u32_e32 v158, 0x58090, v148
	s_nop 0
	v_sub_f32_e32 v5, v33, v48
	v_sub_f32_e32 v4, v32, v48
	v_sub_f32_e32 v7, v35, v48
	v_sub_f32_e32 v6, v34, v48
	v_pk_mul_f32 v[6:7], v[48:49], v[6:7] op_sel:[1,0]
	v_pk_mul_f32 v[4:5], v[48:49], v[4:5] op_sel:[1,0]
	v_pk_fma_f32 v[2:3], v[92:93], v[6:7], v[2:3]
	v_pk_fma_f32 v[0:1], v[94:95], v[4:5], v[0:1]
	v_pk_fma_f32 v[2:3], v[66:67], s[78:79], v[2:3] op_sel_hi:[1,0,1]
	v_pk_fma_f32 v[0:1], v[64:65], s[78:79], v[0:1] op_sel_hi:[1,0,1]
	v_lshl_add_u64 v[4:5], v[158:159], 2, s[88:89]
	global_store_dwordx4 v[4:5], v[0:3], off
	s_and_b64 vcc, exec, s[6:7]
	s_mov_b32 s2, s37
	s_mov_b32 s3, s38
	s_mov_b64 s[18:19], s[10:11]
	s_mov_b64 s[16:17], s[8:9]
	v_readlane_b32 s33, v255, 39
	s_cbranch_vccz .LBB0_123
	s_waitcnt vmcnt(0)
	s_cmpk_gt_u32 s24, 0xff
	s_cbranch_scc1 .LBB0_138
	s_barrier

; #define PG8_STAGE(bufoff, gbase) do { _Pragma("unroll") for (int _i = 0; _i < 2; ++_i) \
;         __builtin_amdgcn_global_load_lds((const unsigned*)((const char*)(gbase) + voff[_i]), (LAS unsigned*)(lds + (bufoff) + ldsw + _i * 8192), 16, 0, 0); } while (0)
; #define PG8_LDA(dst, b, h) do { _Pragma("unroll") for (int m = 0; m < 4; ++m) _Pragma("unroll") for (int k = 0; k < 2; ++k) dst[m][k] = *(const LAS bf16x8*)(lds + PG8_SA(b, h) + aoff + m * 2048 + k * 1024); } while (0)
; #define PG8_LDB(dst, b, h) do { _Pragma("unroll") for (int n = 0; n < 2; ++n) _Pragma("unroll") for (int k = 0; k < 2; ++k) dst[n][k] = *(const LAS bf16x8*)(lds + PG8_SB(b, h) + boff + n * 2048 + k * 1024); } while (0)
; #define PG8_MMA(ai, bj, At, Bt) do { __builtin_amdgcn_s_setprio(1); _Pragma("unroll") for (int m = 0; m < 4; ++m) _Pragma("unroll") for (int n = 0; n < 2; ++n) _Pragma("unroll") for (int k = 0; k < 2; ++k) \
;         acc[ai][bj][m][n] = __builtin_amdgcn_mfma_f32_16x16x32_bf16(Bt[n][k], At[m][k], acc[ai][bj][m][n], 0, 0, 0); __builtin_amdgcn_s_setprio(0); } while (0)
; #define PG8_WAIT_V(n) asm volatile("s_waitcnt vmcnt(" #n ")" ::: "memory")
; #define PG8_WAIT_L(n) asm volatile("s_waitcnt lgkmcnt(" #n ")" ::: "memory")
; #define PG8_BAR __builtin_amdgcn_s_barrier()
; #define PG8_SCHED __builtin_amdgcn_sched_barrier(0)
; template <class Epi>
; DI void gemm_phase(LAS unsigned char* lds, const Gemm g, const StaticOrder& S, const Epi& E) {
;     ...
;         for (int t = 0; t < nt; t += 2) {
;             const bool last = (t == nt - 2);
;             const char* a1 = cA + (size_t)(t + 1) * kstep;
;             const char* a2 = last ? nA : cA + (size_t)(t + 2) * kstep; const char* b2 = last ? nB : cB + (size_t)(t + 2) * kstep;
;             const char* a3 = a2 + kstep; const char* b3 = b2 + kstep;
;             PG8_LDB(B0, 0, 0); PG8_SCHED; PG8_LDA(At, 0, 0); PG8_STAGE(PG8_SA(1, 1), a1 + hstep);
;             PG8_WAIT_L(8); PG8_BAR; PG8_WAIT_L(0); PG8_MMA(0, 0, At, B0); PG8_BAR; PG8_SCHED;
;             PG8_LDB(B1, 0, 1); PG8_STAGE(PG8_SB(0, 0), b2);
;             PG8_BAR; PG8_WAIT_L(0); PG8_MMA(0, 1, At, B1); PG8_BAR;
;             PG8_LDA(At, 0, 1); PG8_STAGE(PG8_SA(0, 0), a2);
;             PG8_BAR; PG8_WAIT_L(0); PG8_MMA(1, 0, At, B0); PG8_BAR; PG8_SCHED;
;             PG8_STAGE(PG8_SB(0, 1), b2 + hstep);
;             PG8_WAIT_V(6); PG8_BAR; PG8_MMA(1, 1, At, B1); PG8_BAR;
.LBB0_202:
	s_add_u32 s18, s8, 0xfff80080
	s_addc_u32 s19, s9, -1
	s_add_i32 s37, 0, 0x10000
	s_waitcnt lgkmcnt(0)
	ds_read_b128 v[128:131], v187
	ds_read_b128 v[132:135], v187 offset:1024
	ds_read_b128 v[136:139], v187 offset:2048
	ds_read_b128 v[190:193], v187 offset:3072
	s_cmp_eq_u32 s36, 28
	s_cselect_b32 s21, s4, s19
	s_cselect_b32 s20, s5, s18
	s_cselect_b32 s19, s11, s35
	s_cselect_b32 s18, s13, s33
	s_add_i32 m0, s26, 0xc000
	ds_read_b128 v[194:197], v189
	ds_read_b128 v[198:201], v189 offset:1024
	ds_read_b128 v[202:205], v189 offset:2048
	ds_read_b128 v[206:209], v189 offset:3072
	ds_read_b128 v[210:213], v189 offset:4096
	ds_read_b128 v[214:217], v189 offset:5120
	ds_read_b128 v[226:229], v189 offset:6144
	ds_read_b128 v[230:233], v189 offset:7168
	global_load_lds_dwordx4 v150, s[8:9]
	s_add_i32 m0, s26, 0xe000
	s_nop 0
	global_load_lds_dwordx4 v152, s[8:9]
	s_waitcnt lgkmcnt(8)
	s_setprio 1
	s_barrier
	s_waitcnt lgkmcnt(0)
	v_mfma_f32_16x16x32_bf16 v[124:127], v[128:131], v[194:197], v[124:127]
	v_mfma_f32_16x16x32_bf16 v[120:123], v[136:139], v[194:197], v[120:123]
	v_mfma_f32_16x16x32_bf16 v[108:111], v[128:131], v[202:205], v[108:111]
	v_mfma_f32_16x16x32_bf16 v[104:107], v[136:139], v[202:205], v[104:107]
	v_mfma_f32_16x16x32_bf16 v[92:95], v[128:131], v[210:213], v[92:95]
	v_mfma_f32_16x16x32_bf16 v[88:91], v[136:139], v[210:213], v[88:91]
	v_mfma_f32_16x16x32_bf16 v[76:79], v[128:131], v[226:229], v[76:79]
	v_mfma_f32_16x16x32_bf16 v[72:75], v[136:139], v[226:229], v[72:75]
	v_mfma_f32_16x16x32_bf16 v[124:127], v[132:135], v[198:201], v[124:127]
	v_mfma_f32_16x16x32_bf16 v[120:123], v[190:193], v[198:201], v[120:123]
	v_mfma_f32_16x16x32_bf16 v[108:111], v[132:135], v[206:209], v[108:111]
	v_mfma_f32_16x16x32_bf16 v[104:107], v[190:193], v[206:209], v[104:107]
	v_mfma_f32_16x16x32_bf16 v[92:95], v[132:135], v[214:217], v[92:95]
	v_mfma_f32_16x16x32_bf16 v[88:91], v[190:193], v[214:217], v[88:91]
	v_mfma_f32_16x16x32_bf16 v[76:79], v[132:135], v[230:233], v[76:79]
	s_setprio 0
	v_mfma_f32_16x16x32_bf16 v[72:75], v[190:193], v[230:233], v[72:75]
	s_barrier
	ds_read_b128 v[234:237], v187 offset:16384
	ds_read_b128 v[238:241], v187 offset:17408
	ds_read_b128 v[242:245], v187 offset:18432
	ds_read_b128 v[246:249], v187 offset:19456
	s_add_i32 s40, 0, 0x14000
	s_add_i32 s37, s37, s25
	s_mov_b32 m0, s37
	s_nop 0
	global_load_lds_dwordx4 v144, s[18:19]
	s_add_i32 m0, s37, 0x2000
	s_nop 0
	global_load_lds_dwordx4 v142, s[18:19]
	s_waitcnt lgkmcnt(0)
	s_setprio 1
	s_barrier
	v_mfma_f32_16x16x32_bf16 v[116:119], v[234:237], v[194:197], v[116:119]
	v_mfma_f32_16x16x32_bf16 v[112:115], v[242:245], v[194:197], v[112:115]
	v_mfma_f32_16x16x32_bf16 v[100:103], v[234:237], v[202:205], v[100:103]
	v_mfma_f32_16x16x32_bf16 v[96:99], v[242:245], v[202:205], v[96:99]
	v_mfma_f32_16x16x32_bf16 v[84:87], v[234:237], v[210:213], v[84:87]
	v_mfma_f32_16x16x32_bf16 v[80:83], v[242:245], v[210:213], v[80:83]
	v_mfma_f32_16x16x32_bf16 v[68:71], v[234:237], v[226:229], v[68:71]
	v_mfma_f32_16x16x32_bf16 v[64:67], v[242:245], v[226:229], v[64:67]
	v_mfma_f32_16x16x32_bf16 v[116:119], v[238:241], v[198:201], v[116:119]
	v_mfma_f32_16x16x32_bf16 v[112:115], v[246:249], v[198:201], v[112:115]
	v_mfma_f32_16x16x32_bf16 v[100:103], v[238:241], v[206:209], v[100:103]
	v_mfma_f32_16x16x32_bf16 v[96:99], v[246:249], v[206:209], v[96:99]
	v_mfma_f32_16x16x32_bf16 v[84:87], v[238:241], v[214:217], v[84:87]
	v_mfma_f32_16x16x32_bf16 v[80:83], v[246:249], v[214:217], v[80:83]
	v_mfma_f32_16x16x32_bf16 v[68:71], v[238:241], v[230:233], v[68:71]
	s_setprio 0
	v_mfma_f32_16x16x32_bf16 v[64:67], v[246:249], v[230:233], v[64:67]
	s_barrier
	ds_read_b128 v[194:197], v189 offset:16384
	ds_read_b128 v[198:201], v189 offset:17408
	ds_read_b128 v[202:205], v189 offset:18432
	ds_read_b128 v[206:209], v189 offset:19456
	ds_read_b128 v[210:213], v189 offset:20480
	ds_read_b128 v[214:217], v189 offset:21504
	ds_read_b128 v[226:229], v189 offset:22528
	ds_read_b128 v[230:233], v189 offset:23552
	s_mov_b32 m0, s26
	s_nop 0
	global_load_lds_dwordx4 v144, s[20:21]
	s_mov_b64 s[100:101], s[20:21]
	s_mov_b32 m0, s27
	s_nop 0
	global_load_lds_dwordx4 v142, s[20:21]
	s_waitcnt lgkmcnt(0)
	s_setprio 1
	s_barrier
	v_mfma_f32_16x16x32_bf16 v[60:63], v[128:131], v[194:197], v[60:63]
	v_mfma_f32_16x16x32_bf16 v[56:59], v[136:139], v[194:197], v[56:59]
	v_mfma_f32_16x16x32_bf16 v[44:47], v[128:131], v[202:205], v[44:47]
	v_mfma_f32_16x16x32_bf16 v[40:43], v[136:139], v[202:205], v[40:43]
	v_mfma_f32_16x16x32_bf16 v[28:31], v[128:131], v[210:213], v[28:31]
	v_mfma_f32_16x16x32_bf16 v[24:27], v[136:139], v[210:213], v[24:27]
	v_mfma_f32_16x16x32_bf16 v[12:15], v[128:131], v[226:229], v[12:15]
	v_mfma_f32_16x16x32_bf16 v[8:11], v[136:139], v[226:229], v[8:11]
	v_mfma_f32_16x16x32_bf16 v[60:63], v[132:135], v[198:201], v[60:63]
	v_mfma_f32_16x16x32_bf16 v[56:59], v[190:193], v[198:201], v[56:59]
	v_mfma_f32_16x16x32_bf16 v[44:47], v[132:135], v[206:209], v[44:47]
	v_mfma_f32_16x16x32_bf16 v[40:43], v[190:193], v[206:209], v[40:43]
	v_mfma_f32_16x16x32_bf16 v[28:31], v[132:135], v[214:217], v[28:31]
	v_mfma_f32_16x16x32_bf16 v[24:27], v[190:193], v[214:217], v[24:27]
	v_mfma_f32_16x16x32_bf16 v[12:15], v[132:135], v[230:233], v[12:15]
	s_setprio 0
	v_mfma_f32_16x16x32_bf16 v[8:11], v[190:193], v[230:233], v[8:11]
	s_barrier
	s_add_u32 s38, s18, 0x80000
	s_addc_u32 s39, s19, 0
	s_add_i32 s37, s40, s25
	s_mov_b32 m0, s37
	s_nop 0
	global_load_lds_dwordx4 v144, s[38:39]
	s_add_i32 m0, s37, 0x2000
	s_nop 0
	global_load_lds_dwordx4 v142, s[38:39]
	s_waitcnt vmcnt(6)
	s_setprio 1
	s_barrier
; #define PG8_STAGE(bufoff, gbase) do { _Pragma("unroll") for (int _i = 0; _i < 2; ++_i) \
;         __builtin_amdgcn_global_load_lds((const unsigned*)((const char*)(gbase) + voff[_i]), (LAS unsigned*)(lds + (bufoff) + ldsw + _i * 8192), 16, 0, 0); } while (0)
; #define PG8_LDA(dst, b, h) do { _Pragma("unroll") for (int m = 0; m < 4; ++m) _Pragma("unroll") for (int k = 0; k < 2; ++k) dst[m][k] = *(const LAS bf16x8*)(lds + PG8_SA(b, h) + aoff + m * 2048 + k * 1024); } while (0)
; #define PG8_LDB(dst, b, h) do { _Pragma("unroll") for (int n = 0; n < 2; ++n) _Pragma("unroll") for (int k = 0; k < 2; ++k) dst[n][k] = *(const LAS bf16x8*)(lds + PG8_SB(b, h) + boff + n * 2048 + k * 1024); } while (0)
; #define PG8_MMA(ai, bj, At, Bt) do { __builtin_amdgcn_s_setprio(1); _Pragma("unroll") for (int m = 0; m < 4; ++m) _Pragma("unroll") for (int n = 0; n < 2; ++n) _Pragma("unroll") for (int k = 0; k < 2; ++k) \
;         acc[ai][bj][m][n] = __builtin_amdgcn_mfma_f32_16x16x32_bf16(Bt[n][k], At[m][k], acc[ai][bj][m][n], 0, 0, 0); __builtin_amdgcn_s_setprio(0); } while (0)
; #define PG8_WAIT_V(n) asm volatile("s_waitcnt vmcnt(" #n ")" ::: "memory")
; #define PG8_WAIT_L(n) asm volatile("s_waitcnt lgkmcnt(" #n ")" ::: "memory")
; #define PG8_BAR __builtin_amdgcn_s_barrier()
; #define PG8_SCHED __builtin_amdgcn_sched_barrier(0)
; template <class Epi>
; DI void gemm_phase(LAS unsigned char* lds, const Gemm g, const StaticOrder& S, const Epi& E) {
;     ...
;             PG8_WAIT_V(6); PG8_BAR; PG8_MMA(1, 1, At, B1); PG8_BAR;
;             PG8_LDB(B0, 1, 0); PG8_SCHED; PG8_LDA(At, 1, 0); PG8_STAGE(PG8_SA(0, 1), a2 + hstep);
;             PG8_WAIT_L(8); PG8_BAR; PG8_WAIT_L(0); PG8_MMA(0, 0, At, B0); PG8_BAR; PG8_SCHED;
;             PG8_LDB(B1, 1, 1); PG8_STAGE(PG8_SB(1, 0), b3);
;             PG8_BAR; PG8_WAIT_L(0); PG8_MMA(0, 1, At, B1); PG8_BAR;
;             PG8_LDA(At, 1, 1); PG8_STAGE(PG8_SA(1, 0), a3);
;             PG8_BAR; PG8_WAIT_L(0); PG8_MMA(1, 0, At, B0); PG8_BAR; PG8_SCHED;
	v_mfma_f32_16x16x32_bf16 v[52:55], v[234:237], v[194:197], v[52:55]
	v_mfma_f32_16x16x32_bf16 v[48:51], v[242:245], v[194:197], v[48:51]
	v_mfma_f32_16x16x32_bf16 v[36:39], v[234:237], v[202:205], v[36:39]
	v_mfma_f32_16x16x32_bf16 v[32:35], v[242:245], v[202:205], v[32:35]
	v_mfma_f32_16x16x32_bf16 v[20:23], v[234:237], v[210:213], v[20:23]
	v_mfma_f32_16x16x32_bf16 v[16:19], v[242:245], v[210:213], v[16:19]
	v_mfma_f32_16x16x32_bf16 v[4:7], v[234:237], v[226:229], v[4:7]
	v_mfma_f32_16x16x32_bf16 v[0:3], v[242:245], v[226:229], v[0:3]
	v_mfma_f32_16x16x32_bf16 v[52:55], v[238:241], v[198:201], v[52:55]
	v_mfma_f32_16x16x32_bf16 v[48:51], v[246:249], v[198:201], v[48:51]
	v_mfma_f32_16x16x32_bf16 v[36:39], v[238:241], v[206:209], v[36:39]
	v_mfma_f32_16x16x32_bf16 v[32:35], v[246:249], v[206:209], v[32:35]
	v_mfma_f32_16x16x32_bf16 v[20:23], v[238:241], v[214:217], v[20:23]
	v_mfma_f32_16x16x32_bf16 v[16:19], v[246:249], v[214:217], v[16:19]
	v_mfma_f32_16x16x32_bf16 v[4:7], v[238:241], v[230:233], v[4:7]
	s_setprio 0
	v_mfma_f32_16x16x32_bf16 v[0:3], v[246:249], v[230:233], v[0:3]
	s_barrier
	ds_read_b128 v[128:131], v187 offset:32768
	ds_read_b128 v[132:135], v187 offset:33792
	ds_read_b128 v[136:139], v187 offset:34816
	ds_read_b128 v[190:193], v187 offset:35840
	ds_read_b128 v[194:197], v189 offset:32768
	ds_read_b128 v[198:201], v189 offset:33792
	ds_read_b128 v[202:205], v189 offset:34816
	ds_read_b128 v[206:209], v189 offset:35840
	ds_read_b128 v[210:213], v189 offset:36864
	ds_read_b128 v[214:217], v189 offset:37888
	ds_read_b128 v[226:229], v189 offset:38912
	ds_read_b128 v[230:233], v189 offset:39936
	s_add_i32 s37, 0, 0x18000
	s_add_u32 s20, s20, 0x80000
	s_addc_u32 s21, s21, 0
	s_mov_b32 m0, s28
	s_nop 0
	global_load_lds_dwordx4 v144, s[20:21]
	s_mov_b32 m0, s29
	s_nop 0
	global_load_lds_dwordx4 v142, s[20:21]
	s_waitcnt lgkmcnt(8)
	s_setprio 1
	s_barrier
	s_waitcnt lgkmcnt(0)
	v_mfma_f32_16x16x32_bf16 v[124:127], v[128:131], v[194:197], v[124:127]
	v_mfma_f32_16x16x32_bf16 v[120:123], v[136:139], v[194:197], v[120:123]
	v_mfma_f32_16x16x32_bf16 v[108:111], v[128:131], v[202:205], v[108:111]
	v_mfma_f32_16x16x32_bf16 v[104:107], v[136:139], v[202:205], v[104:107]
	v_mfma_f32_16x16x32_bf16 v[92:95], v[128:131], v[210:213], v[92:95]
	v_mfma_f32_16x16x32_bf16 v[88:91], v[136:139], v[210:213], v[88:91]
	v_mfma_f32_16x16x32_bf16 v[76:79], v[128:131], v[226:229], v[76:79]
	v_mfma_f32_16x16x32_bf16 v[72:75], v[136:139], v[226:229], v[72:75]
	v_mfma_f32_16x16x32_bf16 v[124:127], v[132:135], v[198:201], v[124:127]
	v_mfma_f32_16x16x32_bf16 v[120:123], v[190:193], v[198:201], v[120:123]
	v_mfma_f32_16x16x32_bf16 v[108:111], v[132:135], v[206:209], v[108:111]
	v_mfma_f32_16x16x32_bf16 v[104:107], v[190:193], v[206:209], v[104:107]
	v_mfma_f32_16x16x32_bf16 v[92:95], v[132:135], v[214:217], v[92:95]
	v_mfma_f32_16x16x32_bf16 v[88:91], v[190:193], v[214:217], v[88:91]
	v_mfma_f32_16x16x32_bf16 v[76:79], v[132:135], v[230:233], v[76:79]
	s_setprio 0
	v_mfma_f32_16x16x32_bf16 v[72:75], v[190:193], v[230:233], v[72:75]
	s_barrier
	ds_read_b128 v[234:237], v187 offset:49152
	ds_read_b128 v[238:241], v187 offset:50176
	ds_read_b128 v[242:245], v187 offset:51200
	ds_read_b128 v[246:249], v187 offset:52224
	s_add_i32 s20, 0, 0x1c000
	s_add_i32 s21, s37, s25
	s_add_i32 m0, s21, 0xffffff80
	s_nop 0
	global_load_lds_dwordx4 v144, s[18:19] offset:128
	s_add_i32 m0, s21, 0x1f80
	s_nop 0
	global_load_lds_dwordx4 v142, s[18:19] offset:128
	s_waitcnt lgkmcnt(0)
	s_setprio 1
	s_barrier
	v_mfma_f32_16x16x32_bf16 v[116:119], v[234:237], v[194:197], v[116:119]
	v_mfma_f32_16x16x32_bf16 v[112:115], v[242:245], v[194:197], v[112:115]
	v_mfma_f32_16x16x32_bf16 v[100:103], v[234:237], v[202:205], v[100:103]
	v_mfma_f32_16x16x32_bf16 v[96:99], v[242:245], v[202:205], v[96:99]
	v_mfma_f32_16x16x32_bf16 v[84:87], v[234:237], v[210:213], v[84:87]
	v_mfma_f32_16x16x32_bf16 v[80:83], v[242:245], v[210:213], v[80:83]
	v_mfma_f32_16x16x32_bf16 v[68:71], v[234:237], v[226:229], v[68:71]
	v_mfma_f32_16x16x32_bf16 v[64:67], v[242:245], v[226:229], v[64:67]
	v_mfma_f32_16x16x32_bf16 v[116:119], v[238:241], v[198:201], v[116:119]
	v_mfma_f32_16x16x32_bf16 v[112:115], v[246:249], v[198:201], v[112:115]
	v_mfma_f32_16x16x32_bf16 v[100:103], v[238:241], v[206:209], v[100:103]
	v_mfma_f32_16x16x32_bf16 v[96:99], v[246:249], v[206:209], v[96:99]
	v_mfma_f32_16x16x32_bf16 v[84:87], v[238:241], v[214:217], v[84:87]
	v_mfma_f32_16x16x32_bf16 v[80:83], v[246:249], v[214:217], v[80:83]
	v_mfma_f32_16x16x32_bf16 v[68:71], v[238:241], v[230:233], v[68:71]
	s_setprio 0
	v_mfma_f32_16x16x32_bf16 v[64:67], v[246:249], v[230:233], v[64:67]
	s_barrier
; #define PG8_STAGE(bufoff, gbase) do { _Pragma("unroll") for (int _i = 0; _i < 2; ++_i) \
;         __builtin_amdgcn_global_load_lds((const unsigned*)((const char*)(gbase) + voff[_i]), (LAS unsigned*)(lds + (bufoff) + ldsw + _i * 8192), 16, 0, 0); } while (0)
; #define PG8_MMA(ai, bj, At, Bt) do { __builtin_amdgcn_s_setprio(1); _Pragma("unroll") for (int m = 0; m < 4; ++m) _Pragma("unroll") for (int n = 0; n < 2; ++n) _Pragma("unroll") for (int k = 0; k < 2; ++k) \
;         acc[ai][bj][m][n] = __builtin_amdgcn_mfma_f32_16x16x32_bf16(Bt[n][k], At[m][k], acc[ai][bj][m][n], 0, 0, 0); __builtin_amdgcn_s_setprio(0); } while (0)
; #define PG8_WAIT_V(n) asm volatile("s_waitcnt vmcnt(" #n ")" ::: "memory")
; #define PG8_WAIT_L(n) asm volatile("s_waitcnt lgkmcnt(" #n ")" ::: "memory")
; #define PG8_BAR __builtin_amdgcn_s_barrier()
; #define PG8_SCHED __builtin_amdgcn_sched_barrier(0)
; template <class Epi>
; DI void gemm_phase(LAS unsigned char* lds, const Gemm g, const StaticOrder& S, const Epi& E) {
;     ...
;             PG8_BAR; PG8_WAIT_L(0); PG8_MMA(1, 0, At, B0); PG8_BAR; PG8_SCHED;
;             PG8_STAGE(PG8_SB(1, 1), b3 + hstep);
;             PG8_WAIT_V(6); PG8_BAR; PG8_MMA(1, 1, At, B1); PG8_BAR;
;     DI void operator()(const f32x4 (&acc)[2][2][4][2], const Unit& u, int wr, int wc, int fr, int fq) const {
;         const int row0 = u.pm * BM + wr * 64 + fr, col0 = u.pn * BM + wc * 16 + 4 * fq;
;         const bool rot = u.pn < 18;
; #pragma unroll
;         for (int ai = 0; ai < 2; ++ai)
; #pragma unroll
;             for (int m = 0; m < 4; ++m) { const int row = row0 + ai * HALF + m * 16; u16* rowp = O + (size_t)row * NQKV_DIL + col0;
;                 f32x4 c4 = (f32x4){1.f, 1.f, 1.f, 1.f}, s4 = (f32x4){0.f, 0.f, 0.f, 0.f};
;                 if (rot) { const int pos = row & (SEQ - 1); c4 = *(const f32x4*)(cs + pos * 64 + wc * 16 + 4 * fq); s4 = *(const f32x4*)(sn + pos * 64 + wc * 16 + 4 * fq); }
	ds_read_b128 v[194:197], v189 offset:49152
	ds_read_b128 v[198:201], v189 offset:50176
	ds_read_b128 v[202:205], v189 offset:51200
	ds_read_b128 v[206:209], v189 offset:52224
	ds_read_b128 v[210:213], v189 offset:53248
	ds_read_b128 v[214:217], v189 offset:54272
	ds_read_b128 v[226:229], v189 offset:55296
	ds_read_b128 v[230:233], v189 offset:56320
	s_add_i32 m0, s30, 0xffffff80
	s_nop 0
	global_load_lds_dwordx4 v144, s[100:101] offset:128
	s_add_i32 m0, s31, 0xffffff80
	s_nop 0
	global_load_lds_dwordx4 v142, s[100:101] offset:128
	s_waitcnt lgkmcnt(0)
	s_setprio 1
	s_barrier
	v_mfma_f32_16x16x32_bf16 v[60:63], v[128:131], v[194:197], v[60:63]
	v_mfma_f32_16x16x32_bf16 v[56:59], v[136:139], v[194:197], v[56:59]
	v_mfma_f32_16x16x32_bf16 v[44:47], v[128:131], v[202:205], v[44:47]
	v_mfma_f32_16x16x32_bf16 v[40:43], v[136:139], v[202:205], v[40:43]
	v_mfma_f32_16x16x32_bf16 v[28:31], v[128:131], v[210:213], v[28:31]
	v_mfma_f32_16x16x32_bf16 v[24:27], v[136:139], v[210:213], v[24:27]
	v_mfma_f32_16x16x32_bf16 v[12:15], v[128:131], v[226:229], v[12:15]
	v_mfma_f32_16x16x32_bf16 v[8:11], v[136:139], v[226:229], v[8:11]
	v_mfma_f32_16x16x32_bf16 v[60:63], v[132:135], v[198:201], v[60:63]
	v_mfma_f32_16x16x32_bf16 v[56:59], v[190:193], v[198:201], v[56:59]
	v_mfma_f32_16x16x32_bf16 v[44:47], v[132:135], v[206:209], v[44:47]
	v_mfma_f32_16x16x32_bf16 v[40:43], v[190:193], v[206:209], v[40:43]
	v_mfma_f32_16x16x32_bf16 v[28:31], v[132:135], v[214:217], v[28:31]
	v_mfma_f32_16x16x32_bf16 v[24:27], v[190:193], v[214:217], v[24:27]
	v_mfma_f32_16x16x32_bf16 v[12:15], v[132:135], v[230:233], v[12:15]
	s_setprio 0
	v_mfma_f32_16x16x32_bf16 v[8:11], v[190:193], v[230:233], v[8:11]
	s_barrier
	s_add_u32 s18, s18, 0x80080
	s_addc_u32 s19, s19, 0
	s_add_i32 s20, s20, s25
	s_mov_b32 m0, s20
	s_nop 0
	global_load_lds_dwordx4 v144, s[18:19]
	s_add_i32 m0, s20, 0x2000
	s_nop 0
	global_load_lds_dwordx4 v142, s[18:19]
	s_waitcnt vmcnt(6)
	s_setprio 1
	s_barrier
	v_mfma_f32_16x16x32_bf16 v[52:55], v[234:237], v[194:197], v[52:55]
	v_mfma_f32_16x16x32_bf16 v[48:51], v[242:245], v[194:197], v[48:51]
	v_mfma_f32_16x16x32_bf16 v[36:39], v[234:237], v[202:205], v[36:39]
	v_mfma_f32_16x16x32_bf16 v[32:35], v[242:245], v[202:205], v[32:35]
	v_mfma_f32_16x16x32_bf16 v[20:23], v[234:237], v[210:213], v[20:23]
	v_mfma_f32_16x16x32_bf16 v[16:19], v[242:245], v[210:213], v[16:19]
	v_mfma_f32_16x16x32_bf16 v[4:7], v[234:237], v[226:229], v[4:7]
	v_mfma_f32_16x16x32_bf16 v[0:3], v[242:245], v[226:229], v[0:3]
	v_mfma_f32_16x16x32_bf16 v[52:55], v[238:241], v[198:201], v[52:55]
	s_add_i32 s36, s36, 2
	v_mfma_f32_16x16x32_bf16 v[48:51], v[246:249], v[198:201], v[48:51]
	s_add_u32 s8, s8, 0x100
	v_mfma_f32_16x16x32_bf16 v[36:39], v[238:241], v[206:209], v[36:39]
	s_addc_u32 s9, s9, 0
	v_mfma_f32_16x16x32_bf16 v[32:35], v[246:249], v[206:209], v[32:35]
	s_add_u32 s33, s33, 0x100
	v_mfma_f32_16x16x32_bf16 v[20:23], v[238:241], v[214:217], v[20:23]
	s_addc_u32 s35, s35, 0
	v_mfma_f32_16x16x32_bf16 v[16:19], v[246:249], v[214:217], v[16:19]
	s_cmp_gt_u32 s36, 29
	v_mfma_f32_16x16x32_bf16 v[4:7], v[238:241], v[230:233], v[4:7]
	s_setprio 0
	v_mfma_f32_16x16x32_bf16 v[0:3], v[246:249], v[230:233], v[0:3]
	s_barrier
	s_cbranch_scc0 .LBB0_202
	s_cmp_lt_i32 s2, 18
	v_lshl_add_u32 v190, s3, 8, v186
	v_mov_b32_e32 v128, 1.0
	v_mov_b32_e32 v132, 0
	s_cselect_b64 s[18:19], -1, 0
	s_cmp_gt_i32 s2, 17
	v_mov_b32_e32 v134, 0
	v_mov_b32_e32 v135, 0
	v_mov_b32_e32 v136, 0
	v_mov_b32_e32 v137, 0
	v_mov_b32_e32 v138, 1.0
	v_mov_b32_e32 v139, 1.0
	v_mov_b32_e32 v140, 1.0
	v_mov_b32_e32 v141, 1.0
	s_cbranch_scc1 .LBB0_205
	v_lshlrev_b32_e32 v129, 8, v190
	v_and_b32_e32 v158, 0xfcf00, v129
	v_lshl_add_u64 v[130:131], v[146:147], 0, v[158:159]
	v_lshl_add_u64 v[134:135], v[148:149], 0, v[158:159]
	global_load_dwordx4 v[138:141], v[130:131], off
	s_nop 0
	global_load_dwordx4 v[134:137], v[134:135], off

; #define PG8_STAGE(bufoff, gbase) do { _Pragma("unroll") for (int _i = 0; _i < 2; ++_i) \
;         __builtin_amdgcn_global_load_lds((const unsigned*)((const char*)(gbase) + voff[_i]), (LAS unsigned*)(lds + (bufoff) + ldsw + _i * 8192), 16, 0, 0); } while (0)
; #define PG8_LDA(dst, b, h) do { _Pragma("unroll") for (int m = 0; m < 4; ++m) _Pragma("unroll") for (int k = 0; k < 2; ++k) dst[m][k] = *(const LAS bf16x8*)(lds + PG8_SA(b, h) + aoff + m * 2048 + k * 1024); } while (0)
; #define PG8_LDB(dst, b, h) do { _Pragma("unroll") for (int n = 0; n < 2; ++n) _Pragma("unroll") for (int k = 0; k < 2; ++k) dst[n][k] = *(const LAS bf16x8*)(lds + PG8_SB(b, h) + boff + n * 2048 + k * 1024); } while (0)
; #define PG8_MMA(ai, bj, At, Bt) do { __builtin_amdgcn_s_setprio(1); _Pragma("unroll") for (int m = 0; m < 4; ++m) _Pragma("unroll") for (int n = 0; n < 2; ++n) _Pragma("unroll") for (int k = 0; k < 2; ++k) \
;         acc[ai][bj][m][n] = __builtin_amdgcn_mfma_f32_16x16x32_bf16(Bt[n][k], At[m][k], acc[ai][bj][m][n], 0, 0, 0); __builtin_amdgcn_s_setprio(0); } while (0)
; #define PG8_WAIT_V(n) asm volatile("s_waitcnt vmcnt(" #n ")" ::: "memory")
; #define PG8_WAIT_L(n) asm volatile("s_waitcnt lgkmcnt(" #n ")" ::: "memory")
; #define PG8_BAR __builtin_amdgcn_s_barrier()
; #define PG8_SCHED __builtin_amdgcn_sched_barrier(0)
; template <class Epi>
; DI void gemm_phase(LAS unsigned char* lds, const Gemm g, const StaticOrder& S, const Epi& E) {
;     ...
;             PG8_LDB(B0, 0, 0); PG8_SCHED; PG8_LDA(At, 0, 0); PG8_STAGE(PG8_SA(1, 1), a1 + hstep);
;             PG8_WAIT_L(8); PG8_BAR; PG8_WAIT_L(0); PG8_MMA(0, 0, At, B0); PG8_BAR; PG8_SCHED;
;             PG8_LDB(B1, 0, 1); PG8_STAGE(PG8_SB(0, 0), b2);
;             PG8_BAR; PG8_WAIT_L(0); PG8_MMA(0, 1, At, B1); PG8_BAR;
;             PG8_LDA(At, 0, 1); PG8_STAGE(PG8_SA(0, 0), a2);
;             PG8_BAR; PG8_WAIT_L(0); PG8_MMA(1, 0, At, B0); PG8_BAR; PG8_SCHED;
;             PG8_STAGE(PG8_SB(0, 1), b2 + hstep);
;             PG8_WAIT_V(6); PG8_BAR; PG8_MMA(1, 1, At, B1); PG8_BAR;
.LBB0_231:
	ds_read_b128 v[138:141], v135
	ds_read_b128 v[142:145], v135 offset:1024
	ds_read_b128 v[146:149], v135 offset:2048
	ds_read_b128 v[150:153], v135 offset:3072
	ds_read_b128 v[186:189], v137
	ds_read_b128 v[190:193], v137 offset:1024
	ds_read_b128 v[194:197], v137 offset:2048
	ds_read_b128 v[198:201], v137 offset:3072
	ds_read_b128 v[202:205], v137 offset:4096
	ds_read_b128 v[206:209], v137 offset:5120
	ds_read_b128 v[210:213], v137 offset:6144
	ds_read_b128 v[214:217], v137 offset:7168
	s_add_u32 s18, s16, 0xfff80080
	s_addc_u32 s19, s17, -1
	s_add_i32 s37, 0, 0x10000
	s_cmp_eq_u32 s36, 28
	s_cselect_b32 s21, s4, s19
	s_cselect_b32 s20, s5, s18
	s_cselect_b32 s19, s9, s35
	s_cselect_b32 s18, s11, s34
	s_add_i32 m0, s24, 0xc000
	s_nop 0
	global_load_lds_dwordx4 v130, s[16:17]
	s_add_i32 m0, s24, 0xe000
	s_nop 0
	global_load_lds_dwordx4 v132, s[16:17]
	s_waitcnt lgkmcnt(8)
	s_setprio 1
	s_barrier
	s_waitcnt lgkmcnt(0)
	v_mfma_f32_16x16x32_bf16 v[124:127], v[138:141], v[186:189], v[124:127]
	v_mfma_f32_16x16x32_bf16 v[120:123], v[146:149], v[186:189], v[120:123]
	v_mfma_f32_16x16x32_bf16 v[116:119], v[138:141], v[194:197], v[116:119]
	v_mfma_f32_16x16x32_bf16 v[112:115], v[146:149], v[194:197], v[112:115]
	v_mfma_f32_16x16x32_bf16 v[100:103], v[138:141], v[202:205], v[100:103]
	v_mfma_f32_16x16x32_bf16 v[96:99], v[146:149], v[202:205], v[96:99]
	v_mfma_f32_16x16x32_bf16 v[84:87], v[138:141], v[210:213], v[84:87]
	v_mfma_f32_16x16x32_bf16 v[80:83], v[146:149], v[210:213], v[80:83]
	v_mfma_f32_16x16x32_bf16 v[124:127], v[142:145], v[190:193], v[124:127]
	v_mfma_f32_16x16x32_bf16 v[120:123], v[150:153], v[190:193], v[120:123]
	v_mfma_f32_16x16x32_bf16 v[116:119], v[142:145], v[198:201], v[116:119]
	v_mfma_f32_16x16x32_bf16 v[112:115], v[150:153], v[198:201], v[112:115]
	v_mfma_f32_16x16x32_bf16 v[100:103], v[142:145], v[206:209], v[100:103]
	v_mfma_f32_16x16x32_bf16 v[96:99], v[150:153], v[206:209], v[96:99]
	v_mfma_f32_16x16x32_bf16 v[84:87], v[142:145], v[214:217], v[84:87]
	s_setprio 0
	v_mfma_f32_16x16x32_bf16 v[80:83], v[150:153], v[214:217], v[80:83]
	s_barrier
	ds_read_b128 v[226:229], v135 offset:16384
	ds_read_b128 v[230:233], v135 offset:17408
	ds_read_b128 v[234:237], v135 offset:18432
	ds_read_b128 v[238:241], v135 offset:19456
	s_add_i32 s40, 0, 0x14000
	s_add_i32 s37, s37, s23
	s_mov_b32 m0, s37
	s_nop 0
	global_load_lds_dwordx4 v158, s[18:19]
	s_add_i32 m0, s37, 0x2000
	s_nop 0
	global_load_lds_dwordx4 v128, s[18:19]
	s_waitcnt lgkmcnt(0)
	s_setprio 1
	s_barrier
	v_mfma_f32_16x16x32_bf16 v[108:111], v[226:229], v[186:189], v[108:111]
	v_mfma_f32_16x16x32_bf16 v[104:107], v[234:237], v[186:189], v[104:107]
	v_mfma_f32_16x16x32_bf16 v[92:95], v[226:229], v[194:197], v[92:95]
	v_mfma_f32_16x16x32_bf16 v[88:91], v[234:237], v[194:197], v[88:91]
	v_mfma_f32_16x16x32_bf16 v[76:79], v[226:229], v[202:205], v[76:79]
	v_mfma_f32_16x16x32_bf16 v[72:75], v[234:237], v[202:205], v[72:75]
	v_mfma_f32_16x16x32_bf16 v[68:71], v[226:229], v[210:213], v[68:71]
	v_mfma_f32_16x16x32_bf16 v[64:67], v[234:237], v[210:213], v[64:67]
	v_mfma_f32_16x16x32_bf16 v[108:111], v[230:233], v[190:193], v[108:111]
	v_mfma_f32_16x16x32_bf16 v[104:107], v[238:241], v[190:193], v[104:107]
	v_mfma_f32_16x16x32_bf16 v[92:95], v[230:233], v[198:201], v[92:95]
	v_mfma_f32_16x16x32_bf16 v[88:91], v[238:241], v[198:201], v[88:91]
	v_mfma_f32_16x16x32_bf16 v[76:79], v[230:233], v[206:209], v[76:79]
	v_mfma_f32_16x16x32_bf16 v[72:75], v[238:241], v[206:209], v[72:75]
	v_mfma_f32_16x16x32_bf16 v[68:71], v[230:233], v[214:217], v[68:71]
	s_setprio 0
	v_mfma_f32_16x16x32_bf16 v[64:67], v[238:241], v[214:217], v[64:67]
	s_barrier
	ds_read_b128 v[186:189], v137 offset:16384
	ds_read_b128 v[190:193], v137 offset:17408
	ds_read_b128 v[194:197], v137 offset:18432
	ds_read_b128 v[198:201], v137 offset:19456
	ds_read_b128 v[202:205], v137 offset:20480
	ds_read_b128 v[206:209], v137 offset:21504
	ds_read_b128 v[210:213], v137 offset:22528
	ds_read_b128 v[214:217], v137 offset:23552
	s_mov_b32 m0, s24
	s_nop 0
	global_load_lds_dwordx4 v158, s[20:21]
	s_mov_b64 s[100:101], s[20:21]
	s_mov_b32 m0, s25
	s_nop 0
	global_load_lds_dwordx4 v128, s[20:21]
	s_waitcnt lgkmcnt(0)
	s_setprio 1
	s_barrier
	v_mfma_f32_16x16x32_bf16 v[60:63], v[138:141], v[186:189], v[60:63]
	v_mfma_f32_16x16x32_bf16 v[56:59], v[146:149], v[186:189], v[56:59]
	v_mfma_f32_16x16x32_bf16 v[52:55], v[138:141], v[194:197], v[52:55]
	v_mfma_f32_16x16x32_bf16 v[48:51], v[146:149], v[194:197], v[48:51]
	v_mfma_f32_16x16x32_bf16 v[36:39], v[138:141], v[202:205], v[36:39]
	v_mfma_f32_16x16x32_bf16 v[32:35], v[146:149], v[202:205], v[32:35]
	v_mfma_f32_16x16x32_bf16 v[20:23], v[138:141], v[210:213], v[20:23]
	v_mfma_f32_16x16x32_bf16 v[16:19], v[146:149], v[210:213], v[16:19]
	v_mfma_f32_16x16x32_bf16 v[60:63], v[142:145], v[190:193], v[60:63]
	v_mfma_f32_16x16x32_bf16 v[56:59], v[150:153], v[190:193], v[56:59]
	v_mfma_f32_16x16x32_bf16 v[52:55], v[142:145], v[198:201], v[52:55]
	v_mfma_f32_16x16x32_bf16 v[48:51], v[150:153], v[198:201], v[48:51]
	v_mfma_f32_16x16x32_bf16 v[36:39], v[142:145], v[206:209], v[36:39]
	v_mfma_f32_16x16x32_bf16 v[32:35], v[150:153], v[206:209], v[32:35]
	v_mfma_f32_16x16x32_bf16 v[20:23], v[142:145], v[214:217], v[20:23]
	s_setprio 0
	v_mfma_f32_16x16x32_bf16 v[16:19], v[150:153], v[214:217], v[16:19]
	s_barrier
	s_add_u32 s38, s18, 0x80000
	s_addc_u32 s39, s19, 0
	s_add_i32 s37, s40, s23
	s_mov_b32 m0, s37
	s_nop 0
	global_load_lds_dwordx4 v158, s[38:39]
	s_add_i32 m0, s37, 0x2000
	s_nop 0
	global_load_lds_dwordx4 v128, s[38:39]
	s_waitcnt vmcnt(6)
	s_setprio 1
	s_barrier
; #define PG8_STAGE(bufoff, gbase) do { _Pragma("unroll") for (int _i = 0; _i < 2; ++_i) \
;         __builtin_amdgcn_global_load_lds((const unsigned*)((const char*)(gbase) + voff[_i]), (LAS unsigned*)(lds + (bufoff) + ldsw + _i * 8192), 16, 0, 0); } while (0)
; #define PG8_LDA(dst, b, h) do { _Pragma("unroll") for (int m = 0; m < 4; ++m) _Pragma("unroll") for (int k = 0; k < 2; ++k) dst[m][k] = *(const LAS bf16x8*)(lds + PG8_SA(b, h) + aoff + m * 2048 + k * 1024); } while (0)
; #define PG8_LDB(dst, b, h) do { _Pragma("unroll") for (int n = 0; n < 2; ++n) _Pragma("unroll") for (int k = 0; k < 2; ++k) dst[n][k] = *(const LAS bf16x8*)(lds + PG8_SB(b, h) + boff + n * 2048 + k * 1024); } while (0)
; #define PG8_MMA(ai, bj, At, Bt) do { __builtin_amdgcn_s_setprio(1); _Pragma("unroll") for (int m = 0; m < 4; ++m) _Pragma("unroll") for (int n = 0; n < 2; ++n) _Pragma("unroll") for (int k = 0; k < 2; ++k) \
;         acc[ai][bj][m][n] = __builtin_amdgcn_mfma_f32_16x16x32_bf16(Bt[n][k], At[m][k], acc[ai][bj][m][n], 0, 0, 0); __builtin_amdgcn_s_setprio(0); } while (0)
; #define PG8_WAIT_V(n) asm volatile("s_waitcnt vmcnt(" #n ")" ::: "memory")
; #define PG8_WAIT_L(n) asm volatile("s_waitcnt lgkmcnt(" #n ")" ::: "memory")
; #define PG8_BAR __builtin_amdgcn_s_barrier()
; #define PG8_SCHED __builtin_amdgcn_sched_barrier(0)
; template <class Epi>
; DI void gemm_phase(LAS unsigned char* lds, const Gemm g, const StaticOrder& S, const Epi& E) {
;     ...
;             PG8_WAIT_V(6); PG8_BAR; PG8_MMA(1, 1, At, B1); PG8_BAR;
;             PG8_LDB(B0, 1, 0); PG8_SCHED; PG8_LDA(At, 1, 0); PG8_STAGE(PG8_SA(0, 1), a2 + hstep);
;             PG8_WAIT_L(8); PG8_BAR; PG8_WAIT_L(0); PG8_MMA(0, 0, At, B0); PG8_BAR; PG8_SCHED;
;             PG8_LDB(B1, 1, 1); PG8_STAGE(PG8_SB(1, 0), b3);
;             PG8_BAR; PG8_WAIT_L(0); PG8_MMA(0, 1, At, B1); PG8_BAR;
;             PG8_LDA(At, 1, 1); PG8_STAGE(PG8_SA(1, 0), a3);
;             PG8_BAR; PG8_WAIT_L(0); PG8_MMA(1, 0, At, B0); PG8_BAR; PG8_SCHED;
	v_mfma_f32_16x16x32_bf16 v[44:47], v[226:229], v[186:189], v[44:47]
	v_mfma_f32_16x16x32_bf16 v[40:43], v[234:237], v[186:189], v[40:43]
	v_mfma_f32_16x16x32_bf16 v[28:31], v[226:229], v[194:197], v[28:31]
	v_mfma_f32_16x16x32_bf16 v[24:27], v[234:237], v[194:197], v[24:27]
	v_mfma_f32_16x16x32_bf16 v[12:15], v[226:229], v[202:205], v[12:15]
	v_mfma_f32_16x16x32_bf16 v[8:11], v[234:237], v[202:205], v[8:11]
	v_mfma_f32_16x16x32_bf16 v[4:7], v[226:229], v[210:213], v[4:7]
	v_mfma_f32_16x16x32_bf16 v[0:3], v[234:237], v[210:213], v[0:3]
	v_mfma_f32_16x16x32_bf16 v[44:47], v[230:233], v[190:193], v[44:47]
	v_mfma_f32_16x16x32_bf16 v[40:43], v[238:241], v[190:193], v[40:43]
	v_mfma_f32_16x16x32_bf16 v[28:31], v[230:233], v[198:201], v[28:31]
	v_mfma_f32_16x16x32_bf16 v[24:27], v[238:241], v[198:201], v[24:27]
	v_mfma_f32_16x16x32_bf16 v[12:15], v[230:233], v[206:209], v[12:15]
	v_mfma_f32_16x16x32_bf16 v[8:11], v[238:241], v[206:209], v[8:11]
	v_mfma_f32_16x16x32_bf16 v[4:7], v[230:233], v[214:217], v[4:7]
	s_setprio 0
	v_mfma_f32_16x16x32_bf16 v[0:3], v[238:241], v[214:217], v[0:3]
	s_barrier
	ds_read_b128 v[138:141], v135 offset:32768
	ds_read_b128 v[142:145], v135 offset:33792
	ds_read_b128 v[146:149], v135 offset:34816
	ds_read_b128 v[150:153], v135 offset:35840
	ds_read_b128 v[186:189], v137 offset:32768
	ds_read_b128 v[190:193], v137 offset:33792
	ds_read_b128 v[194:197], v137 offset:34816
	ds_read_b128 v[198:201], v137 offset:35840
	ds_read_b128 v[202:205], v137 offset:36864
	ds_read_b128 v[206:209], v137 offset:37888
	ds_read_b128 v[210:213], v137 offset:38912
	ds_read_b128 v[214:217], v137 offset:39936
	s_add_i32 s37, 0, 0x18000
	s_add_u32 s20, s20, 0x80000
	s_addc_u32 s21, s21, 0
	s_mov_b32 m0, s26
	s_nop 0
	global_load_lds_dwordx4 v158, s[20:21]
	s_mov_b32 m0, s27
	s_nop 0
	global_load_lds_dwordx4 v128, s[20:21]
	s_waitcnt lgkmcnt(8)
	s_setprio 1
	s_barrier
	s_waitcnt lgkmcnt(0)
	v_mfma_f32_16x16x32_bf16 v[124:127], v[138:141], v[186:189], v[124:127]
	v_mfma_f32_16x16x32_bf16 v[120:123], v[146:149], v[186:189], v[120:123]
	v_mfma_f32_16x16x32_bf16 v[116:119], v[138:141], v[194:197], v[116:119]
	v_mfma_f32_16x16x32_bf16 v[112:115], v[146:149], v[194:197], v[112:115]
	v_mfma_f32_16x16x32_bf16 v[100:103], v[138:141], v[202:205], v[100:103]
	v_mfma_f32_16x16x32_bf16 v[96:99], v[146:149], v[202:205], v[96:99]
	v_mfma_f32_16x16x32_bf16 v[84:87], v[138:141], v[210:213], v[84:87]
	v_mfma_f32_16x16x32_bf16 v[80:83], v[146:149], v[210:213], v[80:83]
	v_mfma_f32_16x16x32_bf16 v[124:127], v[142:145], v[190:193], v[124:127]
	v_mfma_f32_16x16x32_bf16 v[120:123], v[150:153], v[190:193], v[120:123]
	v_mfma_f32_16x16x32_bf16 v[116:119], v[142:145], v[198:201], v[116:119]
	v_mfma_f32_16x16x32_bf16 v[112:115], v[150:153], v[198:201], v[112:115]
	v_mfma_f32_16x16x32_bf16 v[100:103], v[142:145], v[206:209], v[100:103]
	v_mfma_f32_16x16x32_bf16 v[96:99], v[150:153], v[206:209], v[96:99]
	v_mfma_f32_16x16x32_bf16 v[84:87], v[142:145], v[214:217], v[84:87]
	s_setprio 0
	v_mfma_f32_16x16x32_bf16 v[80:83], v[150:153], v[214:217], v[80:83]
	s_barrier
	ds_read_b128 v[226:229], v135 offset:49152
	ds_read_b128 v[230:233], v135 offset:50176
	ds_read_b128 v[234:237], v135 offset:51200
	ds_read_b128 v[238:241], v135 offset:52224
	s_add_i32 s20, 0, 0x1c000
	s_add_i32 s21, s37, s23
	s_add_i32 m0, s21, 0xffffff80
	s_nop 0
	global_load_lds_dwordx4 v158, s[18:19] offset:128
	s_add_i32 m0, s21, 0x1f80
	s_nop 0
	global_load_lds_dwordx4 v128, s[18:19] offset:128
	s_waitcnt lgkmcnt(0)
	s_setprio 1
	s_barrier
	v_mfma_f32_16x16x32_bf16 v[108:111], v[226:229], v[186:189], v[108:111]
	v_mfma_f32_16x16x32_bf16 v[104:107], v[234:237], v[186:189], v[104:107]
	v_mfma_f32_16x16x32_bf16 v[92:95], v[226:229], v[194:197], v[92:95]
	v_mfma_f32_16x16x32_bf16 v[88:91], v[234:237], v[194:197], v[88:91]
	v_mfma_f32_16x16x32_bf16 v[76:79], v[226:229], v[202:205], v[76:79]
	v_mfma_f32_16x16x32_bf16 v[72:75], v[234:237], v[202:205], v[72:75]
	v_mfma_f32_16x16x32_bf16 v[68:71], v[226:229], v[210:213], v[68:71]
	v_mfma_f32_16x16x32_bf16 v[64:67], v[234:237], v[210:213], v[64:67]
	v_mfma_f32_16x16x32_bf16 v[108:111], v[230:233], v[190:193], v[108:111]
	v_mfma_f32_16x16x32_bf16 v[104:107], v[238:241], v[190:193], v[104:107]
	v_mfma_f32_16x16x32_bf16 v[92:95], v[230:233], v[198:201], v[92:95]
	v_mfma_f32_16x16x32_bf16 v[88:91], v[238:241], v[198:201], v[88:91]
	v_mfma_f32_16x16x32_bf16 v[76:79], v[230:233], v[206:209], v[76:79]
	v_mfma_f32_16x16x32_bf16 v[72:75], v[238:241], v[206:209], v[72:75]
	v_mfma_f32_16x16x32_bf16 v[68:71], v[230:233], v[214:217], v[68:71]
	s_setprio 0
	v_mfma_f32_16x16x32_bf16 v[64:67], v[238:241], v[214:217], v[64:67]
	s_barrier
	ds_read_b128 v[186:189], v137 offset:49152
	ds_read_b128 v[190:193], v137 offset:50176
	ds_read_b128 v[194:197], v137 offset:51200
	ds_read_b128 v[198:201], v137 offset:52224
	ds_read_b128 v[202:205], v137 offset:53248
	ds_read_b128 v[206:209], v137 offset:54272
	ds_read_b128 v[210:213], v137 offset:55296
	ds_read_b128 v[214:217], v137 offset:56320
	s_add_i32 m0, s28, 0xffffff80
	s_nop 0
	global_load_lds_dwordx4 v158, s[100:101] offset:128
	s_add_i32 m0, s29, 0xffffff80
	s_nop 0
	global_load_lds_dwordx4 v128, s[100:101] offset:128
	s_waitcnt lgkmcnt(0)
	s_setprio 1
	s_barrier
; #define PG8_STAGE(bufoff, gbase) do { _Pragma("unroll") for (int _i = 0; _i < 2; ++_i) \
;         __builtin_amdgcn_global_load_lds((const unsigned*)((const char*)(gbase) + voff[_i]), (LAS unsigned*)(lds + (bufoff) + ldsw + _i * 8192), 16, 0, 0); } while (0)
; #define PG8_MMA(ai, bj, At, Bt) do { __builtin_amdgcn_s_setprio(1); _Pragma("unroll") for (int m = 0; m < 4; ++m) _Pragma("unroll") for (int n = 0; n < 2; ++n) _Pragma("unroll") for (int k = 0; k < 2; ++k) \
;         acc[ai][bj][m][n] = __builtin_amdgcn_mfma_f32_16x16x32_bf16(Bt[n][k], At[m][k], acc[ai][bj][m][n], 0, 0, 0); __builtin_amdgcn_s_setprio(0); } while (0)
; #define PG8_WAIT_V(n) asm volatile("s_waitcnt vmcnt(" #n ")" ::: "memory")
; #define PG8_WAIT_L(n) asm volatile("s_waitcnt lgkmcnt(" #n ")" ::: "memory")
; #define PG8_BAR __builtin_amdgcn_s_barrier()
; #define PG8_SCHED __builtin_amdgcn_sched_barrier(0)
; template <class Epi>
; DI void gemm_phase(LAS unsigned char* lds, const Gemm g, const StaticOrder& S, const Epi& E) {
;     ...
;             PG8_BAR; PG8_WAIT_L(0); PG8_MMA(1, 0, At, B0); PG8_BAR; PG8_SCHED;
;             PG8_STAGE(PG8_SB(1, 1), b3 + hstep);
;             PG8_WAIT_V(6); PG8_BAR; PG8_MMA(1, 1, At, B1); PG8_BAR;
;         }
	v_mfma_f32_16x16x32_bf16 v[60:63], v[138:141], v[186:189], v[60:63]
	v_mfma_f32_16x16x32_bf16 v[56:59], v[146:149], v[186:189], v[56:59]
	v_mfma_f32_16x16x32_bf16 v[52:55], v[138:141], v[194:197], v[52:55]
	v_mfma_f32_16x16x32_bf16 v[48:51], v[146:149], v[194:197], v[48:51]
	v_mfma_f32_16x16x32_bf16 v[36:39], v[138:141], v[202:205], v[36:39]
	v_mfma_f32_16x16x32_bf16 v[32:35], v[146:149], v[202:205], v[32:35]
	v_mfma_f32_16x16x32_bf16 v[20:23], v[138:141], v[210:213], v[20:23]
	v_mfma_f32_16x16x32_bf16 v[16:19], v[146:149], v[210:213], v[16:19]
	v_mfma_f32_16x16x32_bf16 v[60:63], v[142:145], v[190:193], v[60:63]
	v_mfma_f32_16x16x32_bf16 v[56:59], v[150:153], v[190:193], v[56:59]
	v_mfma_f32_16x16x32_bf16 v[52:55], v[142:145], v[198:201], v[52:55]
	v_mfma_f32_16x16x32_bf16 v[48:51], v[150:153], v[198:201], v[48:51]
	v_mfma_f32_16x16x32_bf16 v[36:39], v[142:145], v[206:209], v[36:39]
	v_mfma_f32_16x16x32_bf16 v[32:35], v[150:153], v[206:209], v[32:35]
	v_mfma_f32_16x16x32_bf16 v[20:23], v[142:145], v[214:217], v[20:23]
	s_setprio 0
	v_mfma_f32_16x16x32_bf16 v[16:19], v[150:153], v[214:217], v[16:19]
	s_barrier
	s_add_u32 s18, s18, 0x80080
	s_addc_u32 s19, s19, 0
	s_add_i32 s20, s20, s23
	s_mov_b32 m0, s20
	s_nop 0
	global_load_lds_dwordx4 v158, s[18:19]
	s_add_i32 m0, s20, 0x2000
	s_nop 0
	global_load_lds_dwordx4 v128, s[18:19]
	s_waitcnt vmcnt(6)
	s_setprio 1
	s_barrier
	v_mfma_f32_16x16x32_bf16 v[44:47], v[226:229], v[186:189], v[44:47]
	v_mfma_f32_16x16x32_bf16 v[40:43], v[234:237], v[186:189], v[40:43]
	v_mfma_f32_16x16x32_bf16 v[28:31], v[226:229], v[194:197], v[28:31]
	v_mfma_f32_16x16x32_bf16 v[24:27], v[234:237], v[194:197], v[24:27]
	v_mfma_f32_16x16x32_bf16 v[12:15], v[226:229], v[202:205], v[12:15]
	v_mfma_f32_16x16x32_bf16 v[8:11], v[234:237], v[202:205], v[8:11]
	v_mfma_f32_16x16x32_bf16 v[4:7], v[226:229], v[210:213], v[4:7]
	v_mfma_f32_16x16x32_bf16 v[0:3], v[234:237], v[210:213], v[0:3]
	v_mfma_f32_16x16x32_bf16 v[44:47], v[230:233], v[190:193], v[44:47]
	s_add_i32 s36, s36, 2
	v_mfma_f32_16x16x32_bf16 v[40:43], v[238:241], v[190:193], v[40:43]
	s_add_u32 s16, s16, 0x100
	v_mfma_f32_16x16x32_bf16 v[28:31], v[230:233], v[198:201], v[28:31]
	s_addc_u32 s17, s17, 0
	v_mfma_f32_16x16x32_bf16 v[24:27], v[238:241], v[198:201], v[24:27]
	s_add_u32 s34, s34, 0x100
	v_mfma_f32_16x16x32_bf16 v[12:15], v[230:233], v[206:209], v[12:15]
	s_addc_u32 s35, s35, 0
	v_mfma_f32_16x16x32_bf16 v[8:11], v[238:241], v[206:209], v[8:11]
	s_cmp_gt_u32 s36, 29
	v_mfma_f32_16x16x32_bf16 v[4:7], v[230:233], v[214:217], v[4:7]
	s_setprio 0
	v_mfma_f32_16x16x32_bf16 v[0:3], v[238:241], v[214:217], v[0:3]
	s_barrier
	s_cbranch_scc0 .LBB0_231
; #define PG8_WAIT_V(n) asm volatile("s_waitcnt vmcnt(" #n ")" ::: "memory")
; #define PG8_BAR __builtin_amdgcn_s_barrier()
; template <class Epi>
; DI void gemm_phase(LAS unsigned char* lds, const Gemm g, const StaticOrder& S, const Epi& E) {
;     ...
;         E(acc, cur, wr, wc, fr, fq);
;         if (!has_next) break;
; #pragma unroll
;         for (int a = 0; a < 2; ++a)
; #pragma unroll
;             for (int b = 0; b < 2; ++b)
; #pragma unroll
;                 for (int m = 0; m < 4; ++m)
; #pragma unroll
;                     for (int n = 0; n < 2; ++n) acc[a][b][m][n] = (f32x4){0.f, 0.f, 0.f, 0.f};
;         cur = nxt; cA = nA; cB = nB; ++ui;
;     }
;     PG8_WAIT_V(0);
;     if (wr == 0) PG8_BAR;
;     DI void operator()(const f32x4 (&acc)[2][2][4][2], const Unit& u, int wr, int wc, int fr, int fq) const {
;         const int row0 = u.pm * BM + wr * 64 + fr, col0 = u.pn * BM + wc * 32 + 8 * fq;
; #pragma unroll
;         for (int ai = 0; ai < 2; ++ai)
; #pragma unroll
;             for (int m = 0; m < 4; ++m) { u16* rowp = O + (size_t)(row0 + ai * HALF + m * 16) * ldc + col0;
; #pragma unroll
;                 for (int bj = 0; bj < 2; ++bj) { const f32x4 v0 = acc[ai][bj][m][0], v1 = acc[ai][bj][m][1];
;                     *(u32x4*)(rowp + bj * HALF) = (u32x4){pk(v0[0], v0[1]), pk(v0[2], v0[3]), pk(v1[0], v1[1]), pk(v1[2], v1[3])}; } }
	v_lshl_add_u32 v144, s33, 8, v134
	v_lshl_or_b32 v138, s31, 8, v136
	v_ashrrev_i32_e32 v139, 31, v138
	v_mov_b64_e32 v[140:141], s[50:51]
	s_movk_i32 s9, 0x3000
	v_cvt_pk_bf16_f32 v68, v68, v69
	v_cvt_pk_bf16_f32 v69, v70, v71
	v_cvt_pk_bf16_f32 v70, v64, v65
	v_add_u32_e32 v64, 0x80, v144
	v_mad_i64_i32 v[142:143], s[4:5], v144, s9, v[140:141]
	v_lshlrev_b64 v[138:139], 1, v[138:139]
	v_cvt_pk_bf16_f32 v108, v108, v109
	v_cvt_pk_bf16_f32 v109, v110, v111
	v_cvt_pk_bf16_f32 v110, v104, v105
	v_or_b32_e32 v104, 16, v144
	v_mad_i64_i32 v[64:65], s[4:5], v64, s9, v[140:141]
	v_cvt_pk_bf16_f32 v44, v44, v45
	v_cvt_pk_bf16_f32 v45, v46, v47
	v_cvt_pk_bf16_f32 v46, v40, v41
	v_add_u32_e32 v40, 0x90, v144
	v_lshl_add_u64 v[142:143], v[142:143], 0, v[138:139]
	v_cvt_pk_bf16_f32 v111, v106, v107
	v_mad_i64_i32 v[104:105], s[4:5], v104, s9, v[140:141]
	v_cvt_pk_bf16_f32 v92, v92, v93
	v_cvt_pk_bf16_f32 v93, v94, v95
	v_cvt_pk_bf16_f32 v94, v88, v89
	v_or_b32_e32 v88, 32, v144
	v_lshl_add_u64 v[64:65], v[64:65], 0, v[138:139]
	v_cvt_pk_bf16_f32 v47, v42, v43
	v_mad_i64_i32 v[40:41], s[4:5], v40, s9, v[140:141]
	v_cvt_pk_bf16_f32 v28, v28, v29
	v_cvt_pk_bf16_f32 v29, v30, v31
	v_cvt_pk_bf16_f32 v30, v24, v25
	v_add_u32_e32 v24, 0xa0, v144
	global_store_dwordx4 v[142:143], v[108:111], off offset:256
	v_cvt_pk_bf16_f32 v95, v90, v91
	v_mad_i64_i32 v[88:89], s[4:5], v88, s9, v[140:141]
	v_lshl_add_u64 v[108:109], v[104:105], 0, v[138:139]
	v_cvt_pk_bf16_f32 v76, v76, v77
	v_cvt_pk_bf16_f32 v77, v78, v79
	v_cvt_pk_bf16_f32 v78, v72, v73
	v_or_b32_e32 v72, 48, v144
	global_store_dwordx4 v[64:65], v[44:47], off offset:256
	v_cvt_pk_bf16_f32 v31, v26, v27
	v_mad_i64_i32 v[24:25], s[4:5], v24, s9, v[140:141]
	v_lshl_add_u64 v[44:45], v[40:41], 0, v[138:139]
	v_cvt_pk_bf16_f32 v12, v12, v13
	v_cvt_pk_bf16_f32 v13, v14, v15
	v_cvt_pk_bf16_f32 v14, v8, v9
	v_add_u32_e32 v8, 0xb0, v144
	global_store_dwordx4 v[108:109], v[92:95], off offset:256
	v_cvt_pk_bf16_f32 v79, v74, v75
	v_mad_i64_i32 v[72:73], s[4:5], v72, s9, v[140:141]
	v_lshl_add_u64 v[92:93], v[88:89], 0, v[138:139]
	global_store_dwordx4 v[44:45], v[28:31], off offset:256
	v_cvt_pk_bf16_f32 v15, v10, v11
	v_mad_i64_i32 v[8:9], s[4:5], v8, s9, v[140:141]
	v_lshl_add_u64 v[28:29], v[24:25], 0, v[138:139]
	v_cvt_pk_bf16_f32 v124, v124, v125
	v_cvt_pk_bf16_f32 v125, v126, v127
	v_cvt_pk_bf16_f32 v126, v120, v121
	v_cvt_pk_bf16_f32 v127, v122, v123
	v_cvt_pk_bf16_f32 v104, v116, v117
	v_cvt_pk_bf16_f32 v105, v118, v119
	v_cvt_pk_bf16_f32 v106, v112, v113
	v_cvt_pk_bf16_f32 v107, v114, v115
	v_cvt_pk_bf16_f32 v88, v100, v101
	v_cvt_pk_bf16_f32 v89, v102, v103
	v_cvt_pk_bf16_f32 v90, v96, v97
	v_cvt_pk_bf16_f32 v91, v98, v99
	global_store_dwordx4 v[92:93], v[76:79], off offset:256
	v_cvt_pk_bf16_f32 v74, v80, v81
	v_cvt_pk_bf16_f32 v75, v82, v83
	v_lshl_add_u64 v[76:77], v[72:73], 0, v[138:139]
	v_cvt_pk_bf16_f32 v72, v84, v85
	v_cvt_pk_bf16_f32 v73, v86, v87
	v_cvt_pk_bf16_f32 v71, v66, v67
	v_cvt_pk_bf16_f32 v60, v60, v61
	v_cvt_pk_bf16_f32 v61, v62, v63
	v_cvt_pk_bf16_f32 v62, v56, v57
	v_cvt_pk_bf16_f32 v63, v58, v59
	v_cvt_pk_bf16_f32 v40, v52, v53
	v_cvt_pk_bf16_f32 v41, v54, v55
	v_cvt_pk_bf16_f32 v42, v48, v49
	v_cvt_pk_bf16_f32 v43, v50, v51
	v_cvt_pk_bf16_f32 v24, v36, v37
	v_cvt_pk_bf16_f32 v25, v38, v39
	v_cvt_pk_bf16_f32 v26, v32, v33
	v_cvt_pk_bf16_f32 v27, v34, v35
	global_store_dwordx4 v[28:29], v[12:15], off offset:256
	v_cvt_pk_bf16_f32 v10, v16, v17
	v_cvt_pk_bf16_f32 v11, v18, v19
	v_lshl_add_u64 v[12:13], v[8:9], 0, v[138:139]
	v_cvt_pk_bf16_f32 v8, v20, v21
	v_cvt_pk_bf16_f32 v9, v22, v23
	v_cvt_pk_bf16_f32 v4, v4, v5
	v_cvt_pk_bf16_f32 v5, v6, v7
	v_cvt_pk_bf16_f32 v6, v0, v1
	v_cvt_pk_bf16_f32 v7, v2, v3
	s_and_b64 vcc, exec, s[6:7]
	s_mov_b32 s31, s8
	s_mov_b32 s33, s10
	s_mov_b64 s[18:19], s[14:15]
	s_mov_b64 s[16:17], s[12:13]
	global_store_dwordx4 v[142:143], v[124:127], off
	global_store_dwordx4 v[108:109], v[104:107], off
	global_store_dwordx4 v[92:93], v[88:91], off
	global_store_dwordx4 v[76:77], v[72:75], off
	global_store_dwordx4 v[76:77], v[68:71], off offset:256
	global_store_dwordx4 v[64:65], v[60:63], off
	global_store_dwordx4 v[44:45], v[40:43], off
	global_store_dwordx4 v[28:29], v[24:27], off
	global_store_dwordx4 v[12:13], v[8:11], off
	global_store_dwordx4 v[12:13], v[4:7], off offset:256
	s_cbranch_vccz .LBB0_228
	s_waitcnt vmcnt(0)
	s_cmpk_gt_u32 s2, 0xff
	s_cbranch_scc1 .LBB0_235
	s_barrier

; #define PG8_STAGE(bufoff, gbase) do { _Pragma("unroll") for (int _i = 0; _i < 2; ++_i) \
;         __builtin_amdgcn_global_load_lds((const unsigned*)((const char*)(gbase) + voff[_i]), (LAS unsigned*)(lds + (bufoff) + ldsw + _i * 8192), 16, 0, 0); } while (0)
; #define PG8_LDA(dst, b, h) do { _Pragma("unroll") for (int m = 0; m < 4; ++m) _Pragma("unroll") for (int k = 0; k < 2; ++k) dst[m][k] = *(const LAS bf16x8*)(lds + PG8_SA(b, h) + aoff + m * 2048 + k * 1024); } while (0)
; #define PG8_LDB(dst, b, h) do { _Pragma("unroll") for (int n = 0; n < 2; ++n) _Pragma("unroll") for (int k = 0; k < 2; ++k) dst[n][k] = *(const LAS bf16x8*)(lds + PG8_SB(b, h) + boff + n * 2048 + k * 1024); } while (0)
; #define PG8_MMA(ai, bj, At, Bt) do { __builtin_amdgcn_s_setprio(1); _Pragma("unroll") for (int m = 0; m < 4; ++m) _Pragma("unroll") for (int n = 0; n < 2; ++n) _Pragma("unroll") for (int k = 0; k < 2; ++k) \
;         acc[ai][bj][m][n] = __builtin_amdgcn_mfma_f32_16x16x32_bf16(Bt[n][k], At[m][k], acc[ai][bj][m][n], 0, 0, 0); __builtin_amdgcn_s_setprio(0); } while (0)
; #define PG8_WAIT_V(n) asm volatile("s_waitcnt vmcnt(" #n ")" ::: "memory")
; #define PG8_WAIT_L(n) asm volatile("s_waitcnt lgkmcnt(" #n ")" ::: "memory")
; #define PG8_BAR __builtin_amdgcn_s_barrier()
; #define PG8_SCHED __builtin_amdgcn_sched_barrier(0)
; template <class Epi>
; DI void gemm_phase(LAS unsigned char* lds, const Gemm g, const StaticOrder& S, const Epi& E) {
;     ...
;             PG8_LDB(B0, 0, 0); PG8_SCHED; PG8_LDA(At, 0, 0); PG8_STAGE(PG8_SA(1, 1), a1 + hstep);
;             PG8_WAIT_L(8); PG8_BAR; PG8_WAIT_L(0); PG8_MMA(0, 0, At, B0); PG8_BAR; PG8_SCHED;
;             PG8_LDB(B1, 0, 1); PG8_STAGE(PG8_SB(0, 0), b2);
;             PG8_BAR; PG8_WAIT_L(0); PG8_MMA(0, 1, At, B1); PG8_BAR;
;             PG8_LDA(At, 0, 1); PG8_STAGE(PG8_SA(0, 0), a2);
;             PG8_BAR; PG8_WAIT_L(0); PG8_MMA(1, 0, At, B0); PG8_BAR; PG8_SCHED;
;             PG8_STAGE(PG8_SB(0, 1), b2 + hstep);
;             PG8_WAIT_V(6); PG8_BAR; PG8_MMA(1, 1, At, B1); PG8_BAR;
.LBB0_320:
	s_add_u32 s26, s24, 0x100
	s_addc_u32 s27, s25, 0
	s_add_i32 s47, 0, 0x10000
	ds_read_b128 v[128:131], v226
	ds_read_b128 v[132:135], v226 offset:1024
	ds_read_b128 v[136:139], v226 offset:2048
	ds_read_b128 v[140:143], v226 offset:3072
	s_cmp_eq_u32 s46, 28
	s_cselect_b32 s31, s4, s27
	s_cselect_b32 s30, s5, s26
	s_cselect_b32 s29, s9, s45
	s_cselect_b32 s28, s11, s33
	v_lshl_add_u64 v[214:215], s[24:25], 0, v[190:191]
	s_add_i32 m0, s38, 0xc000
	ds_read_b128 v[144:147], v228
	ds_read_b128 v[148:151], v228 offset:1024
	ds_read_b128 v[152:155], v228 offset:2048
	ds_read_b128 v[194:197], v228 offset:3072
	ds_read_b128 v[198:201], v228 offset:4096
	ds_read_b128 v[202:205], v228 offset:5120
	ds_read_b128 v[206:209], v228 offset:6144
	ds_read_b128 v[210:213], v228 offset:7168
	global_load_lds_dwordx4 v[214:215], off
	v_lshl_add_u64 v[214:215], s[24:25], 0, v[192:193]
	s_add_i32 m0, s38, 0xe000
	s_nop 0
	global_load_lds_dwordx4 v[214:215], off
	s_waitcnt lgkmcnt(8)
	s_setprio 1
	s_barrier
	s_waitcnt lgkmcnt(0)
	v_mfma_f32_16x16x32_bf16 v[124:127], v[128:131], v[144:147], v[124:127]
	v_mfma_f32_16x16x32_bf16 v[120:123], v[136:139], v[144:147], v[120:123]
	v_mfma_f32_16x16x32_bf16 v[116:119], v[128:131], v[152:155], v[116:119]
	v_mfma_f32_16x16x32_bf16 v[112:115], v[136:139], v[152:155], v[112:115]
	v_mfma_f32_16x16x32_bf16 v[108:111], v[128:131], v[198:201], v[108:111]
	v_mfma_f32_16x16x32_bf16 v[104:107], v[136:139], v[198:201], v[104:107]
	v_mfma_f32_16x16x32_bf16 v[100:103], v[128:131], v[206:209], v[100:103]
	v_mfma_f32_16x16x32_bf16 v[96:99], v[136:139], v[206:209], v[96:99]
	v_mfma_f32_16x16x32_bf16 v[124:127], v[132:135], v[148:151], v[124:127]
	v_mfma_f32_16x16x32_bf16 v[120:123], v[140:143], v[148:151], v[120:123]
	v_mfma_f32_16x16x32_bf16 v[116:119], v[132:135], v[194:197], v[116:119]
	v_mfma_f32_16x16x32_bf16 v[112:115], v[140:143], v[194:197], v[112:115]
	v_mfma_f32_16x16x32_bf16 v[108:111], v[132:135], v[202:205], v[108:111]
	v_mfma_f32_16x16x32_bf16 v[104:107], v[140:143], v[202:205], v[104:107]
	v_mfma_f32_16x16x32_bf16 v[100:103], v[132:135], v[210:213], v[100:103]
	s_setprio 0
	v_mfma_f32_16x16x32_bf16 v[96:99], v[140:143], v[210:213], v[96:99]
	s_barrier
	ds_read_b128 v[214:217], v226 offset:16384
	ds_read_b128 v[230:233], v226 offset:17408
	ds_read_b128 v[234:237], v226 offset:18432
	ds_read_b128 v[238:241], v226 offset:19456
	s_add_i32 s48, 0, 0x14000
	s_add_i32 s24, s47, s37
	s_mov_b32 m0, s24
	s_nop 0
	global_load_lds_dwordx4 v188, s[28:29]
	s_add_i32 m0, s24, 0x2000
	s_nop 0
	global_load_lds_dwordx4 v186, s[28:29]
	s_waitcnt lgkmcnt(0)
	s_setprio 1
	s_barrier
	v_mfma_f32_16x16x32_bf16 v[60:63], v[214:217], v[144:147], v[60:63]
	v_mfma_f32_16x16x32_bf16 v[56:59], v[234:237], v[144:147], v[56:59]
	v_mfma_f32_16x16x32_bf16 v[52:55], v[214:217], v[152:155], v[52:55]
	v_mfma_f32_16x16x32_bf16 v[48:51], v[234:237], v[152:155], v[48:51]
	v_mfma_f32_16x16x32_bf16 v[44:47], v[214:217], v[198:201], v[44:47]
	v_mfma_f32_16x16x32_bf16 v[40:43], v[234:237], v[198:201], v[40:43]
	v_mfma_f32_16x16x32_bf16 v[36:39], v[214:217], v[206:209], v[36:39]
	v_mfma_f32_16x16x32_bf16 v[32:35], v[234:237], v[206:209], v[32:35]
	v_mfma_f32_16x16x32_bf16 v[60:63], v[230:233], v[148:151], v[60:63]
	v_mfma_f32_16x16x32_bf16 v[56:59], v[238:241], v[148:151], v[56:59]
	v_mfma_f32_16x16x32_bf16 v[52:55], v[230:233], v[194:197], v[52:55]
	v_mfma_f32_16x16x32_bf16 v[48:51], v[238:241], v[194:197], v[48:51]
	v_mfma_f32_16x16x32_bf16 v[44:47], v[230:233], v[202:205], v[44:47]
	v_mfma_f32_16x16x32_bf16 v[40:43], v[238:241], v[202:205], v[40:43]
	v_mfma_f32_16x16x32_bf16 v[36:39], v[230:233], v[210:213], v[36:39]
	s_setprio 0
	v_mfma_f32_16x16x32_bf16 v[32:35], v[238:241], v[210:213], v[32:35]
	s_barrier
	ds_read_b128 v[144:147], v228 offset:16384
	ds_read_b128 v[148:151], v228 offset:17408
	ds_read_b128 v[152:155], v228 offset:18432
	ds_read_b128 v[194:197], v228 offset:19456
	ds_read_b128 v[198:201], v228 offset:20480
	ds_read_b128 v[202:205], v228 offset:21504
	ds_read_b128 v[206:209], v228 offset:22528
	ds_read_b128 v[210:213], v228 offset:23552
	s_mov_b32 m0, s38
	s_nop 0
	global_load_lds_dwordx4 v188, s[30:31]
	s_mov_b64 s[100:101], s[30:31]
	s_mov_b32 m0, s39
	s_nop 0
	global_load_lds_dwordx4 v186, s[30:31]
	s_waitcnt lgkmcnt(0)
	s_setprio 1
	s_barrier
	v_mfma_f32_16x16x32_bf16 v[92:95], v[128:131], v[144:147], v[92:95]
	v_mfma_f32_16x16x32_bf16 v[88:91], v[136:139], v[144:147], v[88:91]
	v_mfma_f32_16x16x32_bf16 v[84:87], v[128:131], v[152:155], v[84:87]
	v_mfma_f32_16x16x32_bf16 v[80:83], v[136:139], v[152:155], v[80:83]
	v_mfma_f32_16x16x32_bf16 v[76:79], v[128:131], v[198:201], v[76:79]
	v_mfma_f32_16x16x32_bf16 v[72:75], v[136:139], v[198:201], v[72:75]
	v_mfma_f32_16x16x32_bf16 v[68:71], v[128:131], v[206:209], v[68:71]
	v_mfma_f32_16x16x32_bf16 v[64:67], v[136:139], v[206:209], v[64:67]
	v_mfma_f32_16x16x32_bf16 v[92:95], v[132:135], v[148:151], v[92:95]
	v_mfma_f32_16x16x32_bf16 v[88:91], v[140:143], v[148:151], v[88:91]
	v_mfma_f32_16x16x32_bf16 v[84:87], v[132:135], v[194:197], v[84:87]
	v_mfma_f32_16x16x32_bf16 v[80:83], v[140:143], v[194:197], v[80:83]
	v_mfma_f32_16x16x32_bf16 v[76:79], v[132:135], v[202:205], v[76:79]
	v_mfma_f32_16x16x32_bf16 v[72:75], v[140:143], v[202:205], v[72:75]
	v_mfma_f32_16x16x32_bf16 v[68:71], v[132:135], v[210:213], v[68:71]
	s_setprio 0
	v_mfma_f32_16x16x32_bf16 v[64:67], v[140:143], v[210:213], v[64:67]
	s_barrier
	s_add_u32 s24, s28, 0x80000
	s_addc_u32 s25, s29, 0
	s_add_i32 s47, s48, s37
	s_mov_b32 m0, s47
	s_nop 0
	global_load_lds_dwordx4 v188, s[24:25]
	s_add_i32 m0, s47, 0x2000
	s_nop 0
	global_load_lds_dwordx4 v186, s[24:25]
	s_waitcnt vmcnt(6)
	s_setprio 1
	s_barrier
; #define PG8_STAGE(bufoff, gbase) do { _Pragma("unroll") for (int _i = 0; _i < 2; ++_i) \
;         __builtin_amdgcn_global_load_lds((const unsigned*)((const char*)(gbase) + voff[_i]), (LAS unsigned*)(lds + (bufoff) + ldsw + _i * 8192), 16, 0, 0); } while (0)
; #define PG8_LDA(dst, b, h) do { _Pragma("unroll") for (int m = 0; m < 4; ++m) _Pragma("unroll") for (int k = 0; k < 2; ++k) dst[m][k] = *(const LAS bf16x8*)(lds + PG8_SA(b, h) + aoff + m * 2048 + k * 1024); } while (0)
; #define PG8_LDB(dst, b, h) do { _Pragma("unroll") for (int n = 0; n < 2; ++n) _Pragma("unroll") for (int k = 0; k < 2; ++k) dst[n][k] = *(const LAS bf16x8*)(lds + PG8_SB(b, h) + boff + n * 2048 + k * 1024); } while (0)
; #define PG8_MMA(ai, bj, At, Bt) do { __builtin_amdgcn_s_setprio(1); _Pragma("unroll") for (int m = 0; m < 4; ++m) _Pragma("unroll") for (int n = 0; n < 2; ++n) _Pragma("unroll") for (int k = 0; k < 2; ++k) \
;         acc[ai][bj][m][n] = __builtin_amdgcn_mfma_f32_16x16x32_bf16(Bt[n][k], At[m][k], acc[ai][bj][m][n], 0, 0, 0); __builtin_amdgcn_s_setprio(0); } while (0)
; #define PG8_WAIT_V(n) asm volatile("s_waitcnt vmcnt(" #n ")" ::: "memory")
; #define PG8_WAIT_L(n) asm volatile("s_waitcnt lgkmcnt(" #n ")" ::: "memory")
; #define PG8_BAR __builtin_amdgcn_s_barrier()
; #define PG8_SCHED __builtin_amdgcn_sched_barrier(0)
; template <class Epi>
; DI void gemm_phase(LAS unsigned char* lds, const Gemm g, const StaticOrder& S, const Epi& E) {
;     ...
;             PG8_WAIT_V(6); PG8_BAR; PG8_MMA(1, 1, At, B1); PG8_BAR;
;             PG8_LDB(B0, 1, 0); PG8_SCHED; PG8_LDA(At, 1, 0); PG8_STAGE(PG8_SA(0, 1), a2 + hstep);
;             PG8_WAIT_L(8); PG8_BAR; PG8_WAIT_L(0); PG8_MMA(0, 0, At, B0); PG8_BAR; PG8_SCHED;
;             PG8_LDB(B1, 1, 1); PG8_STAGE(PG8_SB(1, 0), b3);
;             PG8_BAR; PG8_WAIT_L(0); PG8_MMA(0, 1, At, B1); PG8_BAR;
;             PG8_LDA(At, 1, 1); PG8_STAGE(PG8_SA(1, 0), a3);
;             PG8_BAR; PG8_WAIT_L(0); PG8_MMA(1, 0, At, B0); PG8_BAR; PG8_SCHED;
	v_mfma_f32_16x16x32_bf16 v[28:31], v[214:217], v[144:147], v[28:31]
	v_mfma_f32_16x16x32_bf16 v[24:27], v[234:237], v[144:147], v[24:27]
	v_mfma_f32_16x16x32_bf16 v[20:23], v[214:217], v[152:155], v[20:23]
	v_mfma_f32_16x16x32_bf16 v[16:19], v[234:237], v[152:155], v[16:19]
	v_mfma_f32_16x16x32_bf16 v[12:15], v[214:217], v[198:201], v[12:15]
	v_mfma_f32_16x16x32_bf16 v[8:11], v[234:237], v[198:201], v[8:11]
	v_mfma_f32_16x16x32_bf16 v[4:7], v[214:217], v[206:209], v[4:7]
	v_mfma_f32_16x16x32_bf16 v[0:3], v[234:237], v[206:209], v[0:3]
	v_mfma_f32_16x16x32_bf16 v[28:31], v[230:233], v[148:151], v[28:31]
	v_mfma_f32_16x16x32_bf16 v[24:27], v[238:241], v[148:151], v[24:27]
	v_mfma_f32_16x16x32_bf16 v[20:23], v[230:233], v[194:197], v[20:23]
	v_mfma_f32_16x16x32_bf16 v[16:19], v[238:241], v[194:197], v[16:19]
	v_mfma_f32_16x16x32_bf16 v[12:15], v[230:233], v[202:205], v[12:15]
	v_mfma_f32_16x16x32_bf16 v[8:11], v[238:241], v[202:205], v[8:11]
	v_mfma_f32_16x16x32_bf16 v[4:7], v[230:233], v[210:213], v[4:7]
	s_setprio 0
	v_mfma_f32_16x16x32_bf16 v[0:3], v[238:241], v[210:213], v[0:3]
	s_barrier
	ds_read_b128 v[128:131], v226 offset:32768
	ds_read_b128 v[132:135], v226 offset:33792
	ds_read_b128 v[136:139], v226 offset:34816
	ds_read_b128 v[140:143], v226 offset:35840
	ds_read_b128 v[144:147], v228 offset:32768
	ds_read_b128 v[148:151], v228 offset:33792
	ds_read_b128 v[152:155], v228 offset:34816
	ds_read_b128 v[194:197], v228 offset:35840
	ds_read_b128 v[198:201], v228 offset:36864
	ds_read_b128 v[202:205], v228 offset:37888
	ds_read_b128 v[206:209], v228 offset:38912
	ds_read_b128 v[210:213], v228 offset:39936
	s_add_i32 s47, 0, 0x18000
	s_add_u32 s24, s30, 0x80000
	s_addc_u32 s25, s31, 0
	s_mov_b32 m0, s40
	s_nop 0
	global_load_lds_dwordx4 v188, s[24:25]
	s_mov_b32 m0, s41
	s_nop 0
	global_load_lds_dwordx4 v186, s[24:25]
	s_waitcnt lgkmcnt(8)
	s_setprio 1
	s_barrier
	s_waitcnt lgkmcnt(0)
	v_mfma_f32_16x16x32_bf16 v[124:127], v[128:131], v[144:147], v[124:127]
	v_mfma_f32_16x16x32_bf16 v[120:123], v[136:139], v[144:147], v[120:123]
	v_mfma_f32_16x16x32_bf16 v[116:119], v[128:131], v[152:155], v[116:119]
	v_mfma_f32_16x16x32_bf16 v[112:115], v[136:139], v[152:155], v[112:115]
	v_mfma_f32_16x16x32_bf16 v[108:111], v[128:131], v[198:201], v[108:111]
	v_mfma_f32_16x16x32_bf16 v[104:107], v[136:139], v[198:201], v[104:107]
	v_mfma_f32_16x16x32_bf16 v[100:103], v[128:131], v[206:209], v[100:103]
	v_mfma_f32_16x16x32_bf16 v[96:99], v[136:139], v[206:209], v[96:99]
	v_mfma_f32_16x16x32_bf16 v[124:127], v[132:135], v[148:151], v[124:127]
	v_mfma_f32_16x16x32_bf16 v[120:123], v[140:143], v[148:151], v[120:123]
	v_mfma_f32_16x16x32_bf16 v[116:119], v[132:135], v[194:197], v[116:119]
	v_mfma_f32_16x16x32_bf16 v[112:115], v[140:143], v[194:197], v[112:115]
	v_mfma_f32_16x16x32_bf16 v[108:111], v[132:135], v[202:205], v[108:111]
	v_mfma_f32_16x16x32_bf16 v[104:107], v[140:143], v[202:205], v[104:107]
	v_mfma_f32_16x16x32_bf16 v[100:103], v[132:135], v[210:213], v[100:103]
	s_setprio 0
	v_mfma_f32_16x16x32_bf16 v[96:99], v[140:143], v[210:213], v[96:99]
	s_barrier
	ds_read_b128 v[214:217], v226 offset:49152
	ds_read_b128 v[230:233], v226 offset:50176
	ds_read_b128 v[234:237], v226 offset:51200
	ds_read_b128 v[238:241], v226 offset:52224
	s_add_i32 s30, 0, 0x1c000
	s_add_i32 s24, s47, s37
	s_add_i32 m0, s24, 0xffffff80
	s_nop 0
	global_load_lds_dwordx4 v188, s[28:29] offset:128
	s_add_i32 m0, s24, 0x1f80
	s_nop 0
	global_load_lds_dwordx4 v186, s[28:29] offset:128
	s_waitcnt lgkmcnt(0)
	s_setprio 1
	s_barrier
	v_mfma_f32_16x16x32_bf16 v[60:63], v[214:217], v[144:147], v[60:63]
	v_mfma_f32_16x16x32_bf16 v[56:59], v[234:237], v[144:147], v[56:59]
	v_mfma_f32_16x16x32_bf16 v[52:55], v[214:217], v[152:155], v[52:55]
	v_mfma_f32_16x16x32_bf16 v[48:51], v[234:237], v[152:155], v[48:51]
	v_mfma_f32_16x16x32_bf16 v[44:47], v[214:217], v[198:201], v[44:47]
	v_mfma_f32_16x16x32_bf16 v[40:43], v[234:237], v[198:201], v[40:43]
	v_mfma_f32_16x16x32_bf16 v[36:39], v[214:217], v[206:209], v[36:39]
	v_mfma_f32_16x16x32_bf16 v[32:35], v[234:237], v[206:209], v[32:35]
	v_mfma_f32_16x16x32_bf16 v[60:63], v[230:233], v[148:151], v[60:63]
	v_mfma_f32_16x16x32_bf16 v[56:59], v[238:241], v[148:151], v[56:59]
	v_mfma_f32_16x16x32_bf16 v[52:55], v[230:233], v[194:197], v[52:55]
	v_mfma_f32_16x16x32_bf16 v[48:51], v[238:241], v[194:197], v[48:51]
	v_mfma_f32_16x16x32_bf16 v[44:47], v[230:233], v[202:205], v[44:47]
	v_mfma_f32_16x16x32_bf16 v[40:43], v[238:241], v[202:205], v[40:43]
	v_mfma_f32_16x16x32_bf16 v[36:39], v[230:233], v[210:213], v[36:39]
	s_setprio 0
	v_mfma_f32_16x16x32_bf16 v[32:35], v[238:241], v[210:213], v[32:35]
	s_barrier
	ds_read_b128 v[144:147], v228 offset:49152
	ds_read_b128 v[148:151], v228 offset:50176
	ds_read_b128 v[152:155], v228 offset:51200
	ds_read_b128 v[194:197], v228 offset:52224
	ds_read_b128 v[198:201], v228 offset:53248
	ds_read_b128 v[202:205], v228 offset:54272
	ds_read_b128 v[206:209], v228 offset:55296
	ds_read_b128 v[210:213], v228 offset:56320
	s_add_i32 m0, s42, 0xffffff80
	s_nop 0
	global_load_lds_dwordx4 v188, s[100:101] offset:128
	s_add_i32 m0, s43, 0xffffff80
	s_nop 0
	global_load_lds_dwordx4 v186, s[100:101] offset:128
	s_waitcnt lgkmcnt(0)
	s_setprio 1
	s_barrier
; #define PG8_WAIT_V(n) asm volatile("s_waitcnt vmcnt(" #n ")" ::: "memory")
; #define PG8_WAIT_L(n) asm volatile("s_waitcnt lgkmcnt(" #n ")" ::: "memory")
; template <class Epi>
; DI void gemm_phase(LAS unsigned char* lds, const Gemm g, const StaticOrder& S, const Epi& E) {
;     ...
;             PG8_BAR; PG8_WAIT_L(0); PG8_MMA(1, 0, At, B0); PG8_BAR; PG8_SCHED;
;             PG8_STAGE(PG8_SB(1, 1), b3 + hstep);
;             PG8_WAIT_V(6); PG8_BAR; PG8_MMA(1, 1, At, B1); PG8_BAR;
;     template <bool LN, int BJ, int LO, int HI> DI void batch(const f32x4 (&acc)[2][2][4][2], unsigned row0, unsigned col0, const f32x4 (&gv)[2], const f32x4 (&bv)[2]) const {
;         f32x4 r[HI - LO]; float mean[(HI - LO) / 2], rstd[(HI - LO) / 2];
; #pragma unroll
;         for (int i = LO; i < HI; ++i) { const int ai = i >> 3, m = (i >> 1) & 3, n = i & 1; const unsigned row = row0 + ai * HALF + m * 16;
;             if (n == 0) { mean[(i - LO) >> 1] = 0.f; rstd[(i - LO) >> 1] = 1.f;
;                 if (LN) { const float2 st = *(const float2*)(stats + row * 2u); mean[(i - LO) >> 1] = st.x; rstd[(i - LO) >> 1] = st.y; } }
;             r[i - LO] = *(const f32x4*)(src + (row * (unsigned)DM + col0 + BJ * HALF + n * 16)); }
; #pragma unroll
;         for (int i = LO; i < HI; ++i) { const int ai = i >> 3, m = (i >> 1) & 3, n = i & 1; const unsigned row = row0 + ai * HALF + m * 16;
;             *(f32x4*)(Y + (row * (unsigned)DM + col0 + BJ * HALF + n * 16)) = acc[ai][BJ][m][n] + ((r[i - LO] - mean[(i - LO) >> 1]) * rstd[(i - LO) >> 1]) * gv[n] + bv[n]; }
;         __builtin_amdgcn_sched_barrier(0);
;     }
;     template <bool LN, int BJ> DI void load_gb(unsigned col0, f32x4 (&gv)[2], f32x4 (&bv)[2]) const {
; #pragma unroll
;         for (int n = 0; n < 2; ++n) {
;             if (LN) { gv[n] = *(const f32x4*)(gam + col0 + BJ * HALF + n * 16) * ALPHA; bv[n] = *(const f32x4*)(bet + col0 + BJ * HALF + n * 16) * ALPHA; }
;             else { gv[n] = (f32x4){ALPHA, ALPHA, ALPHA, ALPHA}; bv[n] = (f32x4){0.f, 0.f, 0.f, 0.f}; }
;         }
;     }
;     template <bool LN> DI void run(const f32x4 (&acc)[2][2][4][2], const Unit& u, int wr, int wc, int fr, int fq) const {
;         const unsigned row0 = u.pm * BM + wr * 64 + fr, col0 = u.pn * BM + wc * 32 + 4 * fq;
;         f32x4 gv[2], bv[2];
;         load_gb<LN, 0>(col0, gv, bv);
;         batch<LN, 0, 0, 4>(acc, row0, col0, gv, bv);
	v_mfma_f32_16x16x32_bf16 v[92:95], v[128:131], v[144:147], v[92:95]
	v_mfma_f32_16x16x32_bf16 v[88:91], v[136:139], v[144:147], v[88:91]
	v_mfma_f32_16x16x32_bf16 v[84:87], v[128:131], v[152:155], v[84:87]
	v_mfma_f32_16x16x32_bf16 v[80:83], v[136:139], v[152:155], v[80:83]
	v_mfma_f32_16x16x32_bf16 v[76:79], v[128:131], v[198:201], v[76:79]
	v_mfma_f32_16x16x32_bf16 v[72:75], v[136:139], v[198:201], v[72:75]
	v_mfma_f32_16x16x32_bf16 v[68:71], v[128:131], v[206:209], v[68:71]
	v_mfma_f32_16x16x32_bf16 v[64:67], v[136:139], v[206:209], v[64:67]
	v_mfma_f32_16x16x32_bf16 v[92:95], v[132:135], v[148:151], v[92:95]
	v_mfma_f32_16x16x32_bf16 v[88:91], v[140:143], v[148:151], v[88:91]
	v_mfma_f32_16x16x32_bf16 v[84:87], v[132:135], v[194:197], v[84:87]
	v_mfma_f32_16x16x32_bf16 v[80:83], v[140:143], v[194:197], v[80:83]
	v_mfma_f32_16x16x32_bf16 v[76:79], v[132:135], v[202:205], v[76:79]
	v_mfma_f32_16x16x32_bf16 v[72:75], v[140:143], v[202:205], v[72:75]
	v_mfma_f32_16x16x32_bf16 v[68:71], v[132:135], v[210:213], v[68:71]
	s_setprio 0
	v_mfma_f32_16x16x32_bf16 v[64:67], v[140:143], v[210:213], v[64:67]
	s_barrier
	s_add_u32 s24, s28, 0x80080
	s_addc_u32 s25, s29, 0
	s_add_i32 s28, s30, s37
	s_mov_b32 m0, s28
	s_nop 0
	global_load_lds_dwordx4 v188, s[24:25]
	s_add_i32 m0, s28, 0x2000
	s_nop 0
	global_load_lds_dwordx4 v186, s[24:25]
	s_waitcnt vmcnt(6)
	s_setprio 1
	s_barrier
	v_mfma_f32_16x16x32_bf16 v[28:31], v[214:217], v[144:147], v[28:31]
	v_mfma_f32_16x16x32_bf16 v[24:27], v[234:237], v[144:147], v[24:27]
	v_mfma_f32_16x16x32_bf16 v[20:23], v[214:217], v[152:155], v[20:23]
	v_mfma_f32_16x16x32_bf16 v[16:19], v[234:237], v[152:155], v[16:19]
	v_mfma_f32_16x16x32_bf16 v[12:15], v[214:217], v[198:201], v[12:15]
	v_mfma_f32_16x16x32_bf16 v[8:11], v[234:237], v[198:201], v[8:11]
	v_mfma_f32_16x16x32_bf16 v[4:7], v[214:217], v[206:209], v[4:7]
	v_mfma_f32_16x16x32_bf16 v[0:3], v[234:237], v[206:209], v[0:3]
	v_mfma_f32_16x16x32_bf16 v[28:31], v[230:233], v[148:151], v[28:31]
	s_add_i32 s46, s46, 2
	v_mfma_f32_16x16x32_bf16 v[24:27], v[238:241], v[148:151], v[24:27]
	s_add_u32 s33, s33, 0x100
	v_mfma_f32_16x16x32_bf16 v[20:23], v[230:233], v[194:197], v[20:23]
	s_addc_u32 s45, s45, 0
	v_mfma_f32_16x16x32_bf16 v[16:19], v[238:241], v[194:197], v[16:19]
	s_cmp_gt_u32 s46, 29
	v_mfma_f32_16x16x32_bf16 v[12:15], v[230:233], v[202:205], v[12:15]
	s_mov_b64 s[24:25], s[26:27]
	v_mfma_f32_16x16x32_bf16 v[8:11], v[238:241], v[202:205], v[8:11]
	v_mfma_f32_16x16x32_bf16 v[4:7], v[230:233], v[210:213], v[4:7]
	s_setprio 0
	v_mfma_f32_16x16x32_bf16 v[0:3], v[238:241], v[210:213], v[0:3]
	s_barrier
	s_cbranch_scc0 .LBB0_320
	v_lshl_add_u32 v206, s3, 8, v225
	v_lshl_or_b32 v158, s2, 8, v227
	v_lshlrev_b32_e32 v232, 11, v206
	s_andn2_b64 vcc, exec, s[14:15]
	v_or_b32_e32 v231, 16, v158
	v_add_u32_e32 v194, v232, v158
	v_or_b32_e32 v230, 0x80, v158
	v_or_b32_e32 v229, 0x90, v158
	s_cbranch_vccnz .LBB0_323
	v_lshlrev_b64 v[132:133], 2, v[158:159]
	v_lshl_add_u64 v[140:141], s[16:17], 0, v[132:133]
	global_load_dwordx4 v[128:131], v[140:141], off
	v_lshl_add_u64 v[142:143], s[18:19], 0, v[132:133]
	v_readlane_b32 s2, v253, 8
	v_mov_b32_e32 v195, v159
	v_lshlrev_b32_e32 v136, 1, v206
	v_mov_b32_e32 v137, v159
	v_readlane_b32 s3, v253, 9
	v_lshlrev_b64 v[212:213], 2, v[194:195]
	v_add_u32_e32 v146, v232, v231
	v_lshl_add_u64 v[144:145], v[136:137], 2, s[2:3]
	v_lshl_add_u64 v[136:137], s[88:89], 0, v[212:213]
	v_mov_b32_e32 v147, v159
	v_lshl_add_u64 v[146:147], v[146:147], 2, s[88:89]
	v_or_b32_e32 v195, 16, v206
	v_mov_b32_e32 v201, v159
	v_mov_b32_e32 v209, v159
	v_lshl_add_u64 v[212:213], s[90:91], 0, v[212:213]
	s_waitcnt vmcnt(0)
	v_pk_mul_f32 v[152:153], v[130:131], s[78:79] op_sel_hi:[1,0]
	v_pk_mul_f32 v[154:155], v[128:129], s[78:79] op_sel_hi:[1,0]
	global_load_dwordx4 v[132:135], v[142:143], off
	global_load_dwordx4 v[128:131], v[140:141], off offset:64
	global_load_dwordx2 v[204:205], v[144:145], off
	global_load_dwordx4 v[196:199], v[146:147], off
	v_lshlrev_b32_e32 v146, 1, v195
	global_load_dwordx4 v[136:139], v[136:137], off
	v_lshlrev_b32_e32 v195, 11, v195
	v_mov_b32_e32 v147, v159
	v_add_u32_e32 v200, v195, v158
	v_lshl_add_u64 v[146:147], v[146:147], 2, s[2:3]
	v_lshl_add_u64 v[200:201], v[200:201], 2, s[88:89]
	global_load_dwordx2 v[214:215], v[146:147], off
	v_add_u32_e32 v208, v195, v231
	global_load_dwordx4 v[200:203], v[200:201], off
	v_lshl_add_u64 v[208:209], v[208:209], 2, s[88:89]
	global_load_dwordx4 v[208:211], v[208:209], off
	s_waitcnt vmcnt(0)
	v_pk_mul_f32 v[148:149], v[130:131], s[78:79] op_sel_hi:[1,0]
	v_pk_mul_f32 v[150:151], v[128:129], s[78:79] op_sel_hi:[1,0]
	global_load_dwordx4 v[128:131], v[142:143], off offset:64
	v_sub_f32_e32 v137, v137, v204
	v_sub_f32_e32 v136, v136, v204
	v_sub_f32_e32 v139, v139, v204
	v_sub_f32_e32 v138, v138, v204
	v_pk_mul_f32 v[138:139], v[204:205], v[138:139] op_sel:[1,0]
	v_pk_mul_f32 v[136:137], v[204:205], v[136:137] op_sel:[1,0]
	v_pk_fma_f32 v[138:139], v[152:153], v[138:139], v[126:127]
	v_pk_fma_f32 v[136:137], v[154:155], v[136:137], v[124:125]
	v_pk_fma_f32 v[138:139], v[134:135], s[78:79], v[138:139] op_sel_hi:[1,0,1]
	v_pk_fma_f32 v[136:137], v[132:133], s[78:79], v[136:137] op_sel_hi:[1,0,1]
	global_store_dwordx4 v[212:213], v[136:139], off
	s_nop 1
	v_sub_f32_e32 v137, v197, v204
	v_sub_f32_e32 v136, v196, v204
	v_sub_f32_e32 v139, v199, v204
	v_sub_f32_e32 v138, v198, v204
	v_pk_mul_f32 v[138:139], v[204:205], v[138:139] op_sel:[1,0]
	v_pk_mul_f32 v[136:137], v[204:205], v[136:137] op_sel:[1,0]
	v_pk_fma_f32 v[138:139], v[148:149], v[138:139], v[122:123]
	v_pk_fma_f32 v[136:137], v[150:151], v[136:137], v[120:121]
	v_or_b32_e32 v196, 16, v194
	v_mov_b32_e32 v197, v159
	v_lshl_add_u64 v[196:197], v[196:197], 2, s[90:91]
	s_waitcnt vmcnt(0)
;     template <bool LN, int BJ, int LO, int HI> DI void batch(const f32x4 (&acc)[2][2][4][2], unsigned row0, unsigned col0, const f32x4 (&gv)[2], const f32x4 (&bv)[2]) const {
;         f32x4 r[HI - LO]; float mean[(HI - LO) / 2], rstd[(HI - LO) / 2];
; #pragma unroll
;         for (int i = LO; i < HI; ++i) { const int ai = i >> 3, m = (i >> 1) & 3, n = i & 1; const unsigned row = row0 + ai * HALF + m * 16;
;             if (n == 0) { mean[(i - LO) >> 1] = 0.f; rstd[(i - LO) >> 1] = 1.f;
;                 if (LN) { const float2 st = *(const float2*)(stats + row * 2u); mean[(i - LO) >> 1] = st.x; rstd[(i - LO) >> 1] = st.y; } }
;             r[i - LO] = *(const f32x4*)(src + (row * (unsigned)DM + col0 + BJ * HALF + n * 16)); }
; #pragma unroll
;         for (int i = LO; i < HI; ++i) { const int ai = i >> 3, m = (i >> 1) & 3, n = i & 1; const unsigned row = row0 + ai * HALF + m * 16;
;             *(f32x4*)(Y + (row * (unsigned)DM + col0 + BJ * HALF + n * 16)) = acc[ai][BJ][m][n] + ((r[i - LO] - mean[(i - LO) >> 1]) * rstd[(i - LO) >> 1]) * gv[n] + bv[n]; }
	v_pk_fma_f32 v[138:139], v[130:131], s[78:79], v[138:139] op_sel_hi:[1,0,1]
	v_pk_fma_f32 v[136:137], v[128:129], s[78:79], v[136:137] op_sel_hi:[1,0,1]
	global_store_dwordx4 v[196:197], v[136:139], off
	v_add_u32_e32 v196, 0x8000, v194
	v_mov_b32_e32 v197, v159
	v_sub_f32_e32 v137, v201, v214
	v_sub_f32_e32 v136, v200, v214
	v_sub_f32_e32 v139, v203, v214
	v_sub_f32_e32 v138, v202, v214
	v_pk_mul_f32 v[138:139], v[214:215], v[138:139] op_sel:[1,0]
	v_pk_mul_f32 v[136:137], v[214:215], v[136:137] op_sel:[1,0]
	v_pk_fma_f32 v[138:139], v[152:153], v[138:139], v[118:119]
	v_pk_fma_f32 v[136:137], v[154:155], v[136:137], v[116:117]
	v_pk_fma_f32 v[138:139], v[134:135], s[78:79], v[138:139] op_sel_hi:[1,0,1]
	v_pk_fma_f32 v[136:137], v[132:133], s[78:79], v[136:137] op_sel_hi:[1,0,1]
	v_lshl_add_u64 v[196:197], v[196:197], 2, s[90:91]
	global_store_dwordx4 v[196:197], v[136:139], off
	v_add_u32_e32 v196, 0x8010, v194
	v_mov_b32_e32 v197, v159
	v_sub_f32_e32 v137, v209, v214
	v_sub_f32_e32 v136, v208, v214
	v_sub_f32_e32 v139, v211, v214
	v_sub_f32_e32 v138, v210, v214
	v_pk_mul_f32 v[138:139], v[214:215], v[138:139] op_sel:[1,0]
	v_pk_mul_f32 v[136:137], v[214:215], v[136:137] op_sel:[1,0]
	v_pk_fma_f32 v[138:139], v[148:149], v[138:139], v[114:115]
	v_pk_fma_f32 v[136:137], v[150:151], v[136:137], v[112:113]
	v_pk_fma_f32 v[138:139], v[130:131], s[78:79], v[138:139] op_sel_hi:[1,0,1]
	v_pk_fma_f32 v[136:137], v[128:129], s[78:79], v[136:137] op_sel_hi:[1,0,1]
	v_lshl_add_u64 v[196:197], v[196:197], 2, s[90:91]
	global_store_dwordx4 v[196:197], v[136:139], off
	s_nop 1
	v_or_b32_e32 v138, 32, v206
	v_lshlrev_b32_e32 v136, 1, v138
	v_mov_b32_e32 v137, v159
	v_lshlrev_b32_e32 v236, 11, v138
	v_lshl_add_u64 v[200:201], v[136:137], 2, s[2:3]
	v_add_u32_e32 v136, v236, v158
	v_lshl_add_u64 v[136:137], v[136:137], 2, s[88:89]
	global_load_dwordx2 v[204:205], v[200:201], off
	v_add_u32_e32 v196, v236, v231
	global_load_dwordx4 v[136:139], v[136:137], off
	v_mov_b32_e32 v197, v159
	v_lshl_add_u64 v[196:197], v[196:197], 2, s[88:89]
	global_load_dwordx4 v[196:199], v[196:197], off
	v_or_b32_e32 v207, 48, v206
	v_lshlrev_b32_e32 v235, 11, v207
	v_lshlrev_b32_e32 v202, 1, v207
	v_mov_b32_e32 v203, v159
	v_add_u32_e32 v208, v235, v158
	v_mov_b32_e32 v209, v159
	v_lshl_add_u64 v[202:203], v[202:203], 2, s[2:3]
	v_lshl_add_u64 v[208:209], v[208:209], 2, s[88:89]
	global_load_dwordx2 v[216:217], v[202:203], off
	v_add_u32_e32 v212, v235, v231
	global_load_dwordx4 v[208:211], v[208:209], off
	v_mov_b32_e32 v213, v159
	v_lshl_add_u64 v[212:213], v[212:213], 2, s[88:89]
	global_load_dwordx4 v[212:215], v[212:213], off
	v_add_u32_e32 v218, 0x10000, v194
	v_mov_b32_e32 v219, v159
	v_lshl_add_u64 v[218:219], v[218:219], 2, s[90:91]
	s_waitcnt vmcnt(0)
	v_sub_f32_e32 v137, v137, v204
	v_sub_f32_e32 v136, v136, v204
	v_sub_f32_e32 v139, v139, v204
	v_sub_f32_e32 v138, v138, v204
	v_pk_mul_f32 v[138:139], v[204:205], v[138:139] op_sel:[1,0]
	v_pk_mul_f32 v[136:137], v[204:205], v[136:137] op_sel:[1,0]
	v_pk_fma_f32 v[138:139], v[152:153], v[138:139], v[110:111]
	v_pk_fma_f32 v[136:137], v[154:155], v[136:137], v[108:109]
	v_pk_fma_f32 v[138:139], v[134:135], s[78:79], v[138:139] op_sel_hi:[1,0,1]
	v_pk_fma_f32 v[136:137], v[132:133], s[78:79], v[136:137] op_sel_hi:[1,0,1]
	global_store_dwordx4 v[218:219], v[136:139], off
	s_nop 1
	v_sub_f32_e32 v137, v197, v204
	v_sub_f32_e32 v136, v196, v204
	v_sub_f32_e32 v139, v199, v204
	v_sub_f32_e32 v138, v198, v204
	v_pk_mul_f32 v[138:139], v[204:205], v[138:139] op_sel:[1,0]
	v_pk_mul_f32 v[136:137], v[204:205], v[136:137] op_sel:[1,0]
	v_pk_fma_f32 v[138:139], v[148:149], v[138:139], v[106:107]
	v_pk_fma_f32 v[136:137], v[150:151], v[136:137], v[104:105]
	v_add_u32_e32 v196, 0x10010, v194
	v_mov_b32_e32 v197, v159
	v_pk_fma_f32 v[138:139], v[130:131], s[78:79], v[138:139] op_sel_hi:[1,0,1]
	v_pk_fma_f32 v[136:137], v[128:129], s[78:79], v[136:137] op_sel_hi:[1,0,1]
	v_lshl_add_u64 v[196:197], v[196:197], 2, s[90:91]
	global_store_dwordx4 v[196:197], v[136:139], off
	v_add_u32_e32 v196, 0x18000, v194
	v_mov_b32_e32 v197, v159
	v_sub_f32_e32 v137, v209, v216
	v_sub_f32_e32 v136, v208, v216
	v_sub_f32_e32 v139, v211, v216
	v_sub_f32_e32 v138, v210, v216
	v_pk_mul_f32 v[138:139], v[216:217], v[138:139] op_sel:[1,0]
	v_pk_mul_f32 v[136:137], v[216:217], v[136:137] op_sel:[1,0]
	v_pk_fma_f32 v[138:139], v[152:153], v[138:139], v[102:103]
	v_pk_fma_f32 v[136:137], v[154:155], v[136:137], v[100:101]
	v_pk_fma_f32 v[138:139], v[134:135], s[78:79], v[138:139] op_sel_hi:[1,0,1]
	v_pk_fma_f32 v[136:137], v[132:133], s[78:79], v[136:137] op_sel_hi:[1,0,1]
	v_lshl_add_u64 v[196:197], v[196:197], 2, s[90:91]
	global_store_dwordx4 v[196:197], v[136:139], off
	v_add_u32_e32 v196, 0x18010, v194
	v_mov_b32_e32 v197, v159
	v_sub_f32_e32 v137, v213, v216
	v_sub_f32_e32 v136, v212, v216
	v_sub_f32_e32 v139, v215, v216
	v_sub_f32_e32 v138, v214, v216
	v_pk_mul_f32 v[138:139], v[216:217], v[138:139] op_sel:[1,0]
	v_pk_mul_f32 v[136:137], v[216:217], v[136:137] op_sel:[1,0]
	v_pk_fma_f32 v[138:139], v[148:149], v[138:139], v[98:99]
	v_pk_fma_f32 v[136:137], v[150:151], v[136:137], v[96:97]
	v_pk_fma_f32 v[138:139], v[130:131], s[78:79], v[138:139] op_sel_hi:[1,0,1]
	v_pk_fma_f32 v[136:137], v[128:129], s[78:79], v[136:137] op_sel_hi:[1,0,1]
	v_lshl_add_u64 v[196:197], v[196:197], 2, s[90:91]
	global_store_dwordx4 v[196:197], v[136:139], off
	s_nop 1
	v_add_u32_e32 v138, 0x80, v206
	v_lshlrev_b32_e32 v136, 1, v138
	v_mov_b32_e32 v137, v159
	v_lshlrev_b32_e32 v233, 11, v138
	v_lshl_add_u64 v[196:197], v[136:137], 2, s[2:3]
	v_add_u32_e32 v136, v233, v158
	v_lshl_add_u64 v[136:137], v[136:137], 2, s[88:89]
	global_load_dwordx2 v[204:205], v[196:197], off
	v_add_u32_e32 v198, v233, v231
	global_load_dwordx4 v[136:139], v[136:137], off
	v_mov_b32_e32 v199, v159
	v_add_u32_e32 v207, 0x90, v206
	v_lshl_add_u64 v[198:199], v[198:199], 2, s[88:89]
	v_lshlrev_b32_e32 v234, 11, v207
	global_load_dwordx4 v[208:211], v[198:199], off
	v_add_u32_e32 v212, v234, v158
	v_mov_b32_e32 v213, v159
	v_lshl_add_u64 v[212:213], v[212:213], 2, s[88:89]
	global_load_dwordx4 v[212:215], v[212:213], off
	v_lshlrev_b32_e32 v198, 1, v207
	v_mov_b32_e32 v199, v159
	v_lshl_add_u64 v[198:199], v[198:199], 2, s[2:3]
	global_load_dwordx2 v[238:239], v[198:199], off
	v_add_u32_e32 v216, v234, v231
	v_mov_b32_e32 v217, v159
	v_lshl_add_u64 v[216:217], v[216:217], 2, s[88:89]
	global_load_dwordx4 v[216:219], v[216:217], off
	v_add_u32_e32 v240, 0x40000, v194
	v_mov_b32_e32 v241, v159
	v_lshl_add_u64 v[240:241], v[240:241], 2, s[90:91]
	s_waitcnt vmcnt(0)
;     template <bool LN, int BJ, int LO, int HI> DI void batch(const f32x4 (&acc)[2][2][4][2], unsigned row0, unsigned col0, const f32x4 (&gv)[2], const f32x4 (&bv)[2]) const {
;         f32x4 r[HI - LO]; float mean[(HI - LO) / 2], rstd[(HI - LO) / 2];
; #pragma unroll
;         for (int i = LO; i < HI; ++i) { const int ai = i >> 3, m = (i >> 1) & 3, n = i & 1; const unsigned row = row0 + ai * HALF + m * 16;
;             if (n == 0) { mean[(i - LO) >> 1] = 0.f; rstd[(i - LO) >> 1] = 1.f;
;                 if (LN) { const float2 st = *(const float2*)(stats + row * 2u); mean[(i - LO) >> 1] = st.x; rstd[(i - LO) >> 1] = st.y; } }
;             r[i - LO] = *(const f32x4*)(src + (row * (unsigned)DM + col0 + BJ * HALF + n * 16)); }
; #pragma unroll
;         for (int i = LO; i < HI; ++i) { const int ai = i >> 3, m = (i >> 1) & 3, n = i & 1; const unsigned row = row0 + ai * HALF + m * 16;
;             *(f32x4*)(Y + (row * (unsigned)DM + col0 + BJ * HALF + n * 16)) = acc[ai][BJ][m][n] + ((r[i - LO] - mean[(i - LO) >> 1]) * rstd[(i - LO) >> 1]) * gv[n] + bv[n]; }
;         __builtin_amdgcn_sched_barrier(0);
;     }
;     template <bool LN, int BJ> DI void load_gb(unsigned col0, f32x4 (&gv)[2], f32x4 (&bv)[2]) const {
; #pragma unroll
;         for (int n = 0; n < 2; ++n) {
;             if (LN) { gv[n] = *(const f32x4*)(gam + col0 + BJ * HALF + n * 16) * ALPHA; bv[n] = *(const f32x4*)(bet + col0 + BJ * HALF + n * 16) * ALPHA; }
	v_sub_f32_e32 v137, v137, v204
	v_sub_f32_e32 v136, v136, v204
	v_sub_f32_e32 v139, v139, v204
	v_sub_f32_e32 v138, v138, v204
	v_pk_mul_f32 v[138:139], v[204:205], v[138:139] op_sel:[1,0]
	v_pk_mul_f32 v[136:137], v[204:205], v[136:137] op_sel:[1,0]
	v_pk_fma_f32 v[138:139], v[152:153], v[138:139], v[94:95]
	v_pk_fma_f32 v[136:137], v[154:155], v[136:137], v[92:93]
	v_pk_fma_f32 v[138:139], v[134:135], s[78:79], v[138:139] op_sel_hi:[1,0,1]
	v_pk_fma_f32 v[136:137], v[132:133], s[78:79], v[136:137] op_sel_hi:[1,0,1]
	global_store_dwordx4 v[240:241], v[136:139], off
	s_nop 1
	v_sub_f32_e32 v137, v209, v204
	v_sub_f32_e32 v136, v208, v204
	v_sub_f32_e32 v139, v211, v204
	v_sub_f32_e32 v138, v210, v204
	v_pk_mul_f32 v[138:139], v[204:205], v[138:139] op_sel:[1,0]
	v_pk_mul_f32 v[136:137], v[204:205], v[136:137] op_sel:[1,0]
	v_pk_fma_f32 v[138:139], v[148:149], v[138:139], v[90:91]
	v_pk_fma_f32 v[136:137], v[150:151], v[136:137], v[88:89]
	v_add_u32_e32 v204, 0x40010, v194
	v_mov_b32_e32 v205, v159
	v_pk_fma_f32 v[138:139], v[130:131], s[78:79], v[138:139] op_sel_hi:[1,0,1]
	v_pk_fma_f32 v[136:137], v[128:129], s[78:79], v[136:137] op_sel_hi:[1,0,1]
	v_lshl_add_u64 v[204:205], v[204:205], 2, s[90:91]
	global_store_dwordx4 v[204:205], v[136:139], off
	v_add_u32_e32 v204, 0x48000, v194
	v_mov_b32_e32 v205, v159
	v_sub_f32_e32 v137, v213, v238
	v_sub_f32_e32 v136, v212, v238
	v_sub_f32_e32 v139, v215, v238
	v_sub_f32_e32 v138, v214, v238
	v_pk_mul_f32 v[138:139], v[238:239], v[138:139] op_sel:[1,0]
	v_pk_mul_f32 v[136:137], v[238:239], v[136:137] op_sel:[1,0]
	v_pk_fma_f32 v[138:139], v[152:153], v[138:139], v[86:87]
	v_pk_fma_f32 v[136:137], v[154:155], v[136:137], v[84:85]
	v_pk_fma_f32 v[138:139], v[134:135], s[78:79], v[138:139] op_sel_hi:[1,0,1]
	v_pk_fma_f32 v[136:137], v[132:133], s[78:79], v[136:137] op_sel_hi:[1,0,1]
	v_lshl_add_u64 v[204:205], v[204:205], 2, s[90:91]
	global_store_dwordx4 v[204:205], v[136:139], off
	v_add_u32_e32 v204, 0x48010, v194
	v_mov_b32_e32 v205, v159
	v_sub_f32_e32 v137, v217, v238
	v_sub_f32_e32 v136, v216, v238
	v_sub_f32_e32 v139, v219, v238
	v_sub_f32_e32 v138, v218, v238
	v_pk_mul_f32 v[138:139], v[238:239], v[138:139] op_sel:[1,0]
	v_pk_mul_f32 v[136:137], v[238:239], v[136:137] op_sel:[1,0]
	v_pk_fma_f32 v[138:139], v[148:149], v[138:139], v[82:83]
	v_pk_fma_f32 v[136:137], v[150:151], v[136:137], v[80:81]
	v_pk_fma_f32 v[138:139], v[130:131], s[78:79], v[138:139] op_sel_hi:[1,0,1]
	v_pk_fma_f32 v[136:137], v[128:129], s[78:79], v[136:137] op_sel_hi:[1,0,1]
	v_lshl_add_u64 v[204:205], v[204:205], 2, s[90:91]
	global_store_dwordx4 v[204:205], v[136:139], off
	s_nop 1
	v_add_u32_e32 v138, 0xa0, v206
	v_lshlrev_b32_e32 v136, 1, v138
	v_mov_b32_e32 v137, v159
	v_lshlrev_b32_e32 v237, 11, v138
	v_lshl_add_u64 v[204:205], v[136:137], 2, s[2:3]
	v_add_u32_e32 v136, v237, v158
	v_lshl_add_u64 v[136:137], v[136:137], 2, s[88:89]
	global_load_dwordx2 v[240:241], v[204:205], off
	v_add_u32_e32 v208, v237, v231
	global_load_dwordx4 v[136:139], v[136:137], off
	v_mov_b32_e32 v209, v159
	v_lshl_add_u64 v[208:209], v[208:209], 2, s[88:89]
	global_load_dwordx4 v[212:215], v[208:209], off
	v_add_u32_e32 v208, 0xb0, v206
	v_lshlrev_b32_e32 v206, 1, v208
	v_mov_b32_e32 v207, v159
	v_lshlrev_b32_e32 v238, 11, v208
	v_lshl_add_u64 v[210:211], v[206:207], 2, s[2:3]
	v_add_u32_e32 v206, v238, v158
	v_lshl_add_u64 v[206:207], v[206:207], 2, s[88:89]
	global_load_dwordx2 v[242:243], v[210:211], off
	v_add_u32_e32 v216, v238, v231
	global_load_dwordx4 v[206:209], v[206:207], off
	v_mov_b32_e32 v217, v159
	v_lshl_add_u64 v[216:217], v[216:217], 2, s[88:89]
	global_load_dwordx4 v[216:219], v[216:217], off
	v_add_u32_e32 v244, 0x50000, v194
	v_mov_b32_e32 v245, v159
	v_lshl_add_u64 v[244:245], v[244:245], 2, s[90:91]
	s_waitcnt vmcnt(0)
	v_sub_f32_e32 v137, v137, v240
	v_sub_f32_e32 v136, v136, v240
	v_sub_f32_e32 v139, v139, v240
	v_sub_f32_e32 v138, v138, v240
	v_pk_mul_f32 v[138:139], v[240:241], v[138:139] op_sel:[1,0]
	v_pk_mul_f32 v[136:137], v[240:241], v[136:137] op_sel:[1,0]
	v_pk_fma_f32 v[138:139], v[152:153], v[138:139], v[78:79]
	v_pk_fma_f32 v[136:137], v[154:155], v[136:137], v[76:77]
	v_pk_fma_f32 v[138:139], v[134:135], s[78:79], v[138:139] op_sel_hi:[1,0,1]
	v_pk_fma_f32 v[136:137], v[132:133], s[78:79], v[136:137] op_sel_hi:[1,0,1]
	global_store_dwordx4 v[244:245], v[136:139], off
	s_nop 1
	v_sub_f32_e32 v137, v213, v240
	v_sub_f32_e32 v136, v212, v240
	v_sub_f32_e32 v139, v215, v240
	v_sub_f32_e32 v138, v214, v240
	v_pk_mul_f32 v[138:139], v[240:241], v[138:139] op_sel:[1,0]
	v_pk_mul_f32 v[136:137], v[240:241], v[136:137] op_sel:[1,0]
	v_pk_fma_f32 v[138:139], v[148:149], v[138:139], v[74:75]
	v_pk_fma_f32 v[136:137], v[150:151], v[136:137], v[72:73]
	v_add_u32_e32 v212, 0x50010, v194
	v_mov_b32_e32 v213, v159
	v_pk_fma_f32 v[138:139], v[130:131], s[78:79], v[138:139] op_sel_hi:[1,0,1]
	v_pk_fma_f32 v[136:137], v[128:129], s[78:79], v[136:137] op_sel_hi:[1,0,1]
	v_lshl_add_u64 v[212:213], v[212:213], 2, s[90:91]
	global_store_dwordx4 v[212:213], v[136:139], off
	s_nop 1
	v_sub_f32_e32 v137, v207, v242
	v_sub_f32_e32 v136, v206, v242
	v_sub_f32_e32 v139, v209, v242
	v_sub_f32_e32 v138, v208, v242
	v_pk_mul_f32 v[136:137], v[242:243], v[136:137] op_sel:[1,0]
	v_pk_mul_f32 v[138:139], v[242:243], v[138:139] op_sel:[1,0]
	v_pk_fma_f32 v[136:137], v[154:155], v[136:137], v[68:69]
	v_pk_fma_f32 v[138:139], v[152:153], v[138:139], v[70:71]
	v_pk_fma_f32 v[132:133], v[132:133], s[78:79], v[136:137] op_sel_hi:[1,0,1]
	v_add_u32_e32 v136, 0x58000, v194
	v_mov_b32_e32 v137, v159
	v_pk_fma_f32 v[134:135], v[134:135], s[78:79], v[138:139] op_sel_hi:[1,0,1]
	v_lshl_add_u64 v[136:137], v[136:137], 2, s[90:91]
	global_store_dwordx4 v[136:137], v[132:135], off
	s_nop 1
	v_sub_f32_e32 v133, v217, v242
	v_sub_f32_e32 v132, v216, v242
	v_sub_f32_e32 v135, v219, v242
	v_sub_f32_e32 v134, v218, v242
	v_pk_mul_f32 v[132:133], v[242:243], v[132:133] op_sel:[1,0]
	v_pk_mul_f32 v[134:135], v[242:243], v[134:135] op_sel:[1,0]
	v_pk_fma_f32 v[132:133], v[150:151], v[132:133], v[64:65]
	v_pk_fma_f32 v[134:135], v[148:149], v[134:135], v[66:67]
	v_pk_fma_f32 v[128:129], v[128:129], s[78:79], v[132:133] op_sel_hi:[1,0,1]
	v_add_u32_e32 v132, 0x58010, v194
	v_mov_b32_e32 v133, v159
	v_pk_fma_f32 v[130:131], v[130:131], s[78:79], v[134:135] op_sel_hi:[1,0,1]
	v_lshl_add_u64 v[132:133], v[132:133], 2, s[90:91]
	global_store_dwordx4 v[132:133], v[128:131], off
	global_load_dwordx4 v[128:131], v[140:141], off offset:512
	v_add_u32_e32 v136, v232, v230
	v_mov_b32_e32 v137, v159
	v_lshl_add_u64 v[136:137], v[136:137], 2, s[88:89]
	s_waitcnt vmcnt(0)
;     template <bool LN, int BJ, int LO, int HI> DI void batch(const f32x4 (&acc)[2][2][4][2], unsigned row0, unsigned col0, const f32x4 (&gv)[2], const f32x4 (&bv)[2]) const {
;         f32x4 r[HI - LO]; float mean[(HI - LO) / 2], rstd[(HI - LO) / 2];
; #pragma unroll
;         for (int i = LO; i < HI; ++i) { const int ai = i >> 3, m = (i >> 1) & 3, n = i & 1; const unsigned row = row0 + ai * HALF + m * 16;
;             if (n == 0) { mean[(i - LO) >> 1] = 0.f; rstd[(i - LO) >> 1] = 1.f;
;                 if (LN) { const float2 st = *(const float2*)(stats + row * 2u); mean[(i - LO) >> 1] = st.x; rstd[(i - LO) >> 1] = st.y; } }
;             r[i - LO] = *(const f32x4*)(src + (row * (unsigned)DM + col0 + BJ * HALF + n * 16)); }
; #pragma unroll
;         for (int i = LO; i < HI; ++i) { const int ai = i >> 3, m = (i >> 1) & 3, n = i & 1; const unsigned row = row0 + ai * HALF + m * 16;
;             *(f32x4*)(Y + (row * (unsigned)DM + col0 + BJ * HALF + n * 16)) = acc[ai][BJ][m][n] + ((r[i - LO] - mean[(i - LO) >> 1]) * rstd[(i - LO) >> 1]) * gv[n] + bv[n]; }
;         __builtin_amdgcn_sched_barrier(0);
;     }
;     template <bool LN, int BJ> DI void load_gb(unsigned col0, f32x4 (&gv)[2], f32x4 (&bv)[2]) const {
; #pragma unroll
;         for (int n = 0; n < 2; ++n) {
;             if (LN) { gv[n] = *(const f32x4*)(gam + col0 + BJ * HALF + n * 16) * ALPHA; bv[n] = *(const f32x4*)(bet + col0 + BJ * HALF + n * 16) * ALPHA; }
;             else { gv[n] = (f32x4){ALPHA, ALPHA, ALPHA, ALPHA}; bv[n] = (f32x4){0.f, 0.f, 0.f, 0.f}; }
;         }
;     }
;     template <bool LN> DI void run(const f32x4 (&acc)[2][2][4][2], const Unit& u, int wr, int wc, int fr, int fq) const {
;         const unsigned row0 = u.pm * BM + wr * 64 + fr, col0 = u.pn * BM + wc * 32 + 4 * fq;
;         f32x4 gv[2], bv[2];
;         load_gb<LN, 0>(col0, gv, bv);
;         batch<LN, 0, 0, 4>(acc, row0, col0, gv, bv);
;         batch<LN, 0, 4, 8>(acc, row0, col0, gv, bv);
;         batch<LN, 0, 8, 12>(acc, row0, col0, gv, bv);
;         batch<LN, 0, 12, 16>(acc, row0, col0, gv, bv);
;         load_gb<LN, 1>(col0, gv, bv);
;         batch<LN, 1, 0, 8>(acc, row0, col0, gv, bv);
	v_pk_mul_f32 v[212:213], v[130:131], s[78:79] op_sel_hi:[1,0]
	v_pk_mul_f32 v[214:215], v[128:129], s[78:79] op_sel_hi:[1,0]
	global_load_dwordx4 v[132:135], v[142:143], off offset:512
	global_load_dwordx4 v[128:131], v[140:141], off offset:576
	s_waitcnt vmcnt(0)
	v_pk_mul_f32 v[206:207], v[130:131], s[78:79] op_sel_hi:[1,0]
	v_pk_mul_f32 v[208:209], v[128:129], s[78:79] op_sel_hi:[1,0]
	global_load_dwordx4 v[128:131], v[142:143], off offset:576
	global_load_dwordx2 v[220:221], v[144:145], off
	global_load_dwordx4 v[240:243], v[136:137], off
	v_add_u32_e32 v136, v232, v229
	v_mov_b32_e32 v137, v159
	v_lshl_add_u64 v[136:137], v[136:137], 2, s[88:89]
	global_load_dwordx4 v[244:247], v[136:137], off
	global_load_dwordx2 v[218:219], v[146:147], off
	v_add_u32_e32 v136, v195, v230
	v_mov_b32_e32 v137, v159
	v_lshl_add_u64 v[136:137], v[136:137], 2, s[88:89]
	global_load_dwordx4 v[248:251], v[136:137], off
	v_add_u32_e32 v136, v195, v229
	v_mov_b32_e32 v137, v159
	v_lshl_add_u64 v[136:137], v[136:137], 2, s[88:89]
	global_load_dwordx4 v[152:155], v[136:137], off
	global_load_dwordx2 v[216:217], v[200:201], off
	v_add_u32_e32 v136, v236, v230
	v_mov_b32_e32 v137, v159
	v_lshl_add_u64 v[136:137], v[136:137], 2, s[88:89]
	global_load_dwordx4 v[148:151], v[136:137], off
	v_add_u32_e32 v136, v236, v229
	v_mov_b32_e32 v137, v159
	v_lshl_add_u64 v[136:137], v[136:137], 2, s[88:89]
	global_load_dwordx4 v[144:147], v[136:137], off
	global_load_dwordx2 v[200:201], v[202:203], off
	v_add_u32_e32 v136, v235, v230
	v_mov_b32_e32 v137, v159
	v_lshl_add_u64 v[136:137], v[136:137], 2, s[88:89]
	global_load_dwordx4 v[140:143], v[136:137], off
	v_add_u32_e32 v136, v235, v229
	v_mov_b32_e32 v137, v159
	v_lshl_add_u64 v[136:137], v[136:137], 2, s[88:89]
	global_load_dwordx4 v[136:139], v[136:137], off
	v_add_u32_e32 v202, 0x80, v194
	v_mov_b32_e32 v203, v159
	v_lshl_add_u64 v[202:203], v[202:203], 2, s[90:91]
	s_waitcnt vmcnt(0)
	v_sub_f32_e32 v241, v241, v220
	v_sub_f32_e32 v240, v240, v220
	v_sub_f32_e32 v243, v243, v220
	v_sub_f32_e32 v242, v242, v220
	v_pk_mul_f32 v[242:243], v[220:221], v[242:243] op_sel:[1,0]
	v_pk_mul_f32 v[240:241], v[220:221], v[240:241] op_sel:[1,0]
	v_pk_fma_f32 v[242:243], v[212:213], v[242:243], v[62:63]
	v_pk_fma_f32 v[240:241], v[214:215], v[240:241], v[60:61]
	v_pk_fma_f32 v[242:243], v[134:135], s[78:79], v[242:243] op_sel_hi:[1,0,1]
	v_pk_fma_f32 v[240:241], v[132:133], s[78:79], v[240:241] op_sel_hi:[1,0,1]
	global_store_dwordx4 v[202:203], v[240:243], off
	v_sub_f32_e32 v203, v245, v220
	v_sub_f32_e32 v202, v244, v220
	v_sub_f32_e32 v241, v247, v220
	v_sub_f32_e32 v240, v246, v220
	v_pk_mul_f32 v[202:203], v[220:221], v[202:203] op_sel:[1,0]
	v_pk_mul_f32 v[240:241], v[220:221], v[240:241] op_sel:[1,0]
	v_pk_fma_f32 v[202:203], v[208:209], v[202:203], v[56:57]
	v_pk_fma_f32 v[220:221], v[206:207], v[240:241], v[58:59]
	v_pk_fma_f32 v[240:241], v[128:129], s[78:79], v[202:203] op_sel_hi:[1,0,1]
	v_add_u32_e32 v202, 0x90, v194
	v_mov_b32_e32 v203, v159
	v_pk_fma_f32 v[242:243], v[130:131], s[78:79], v[220:221] op_sel_hi:[1,0,1]
	v_lshl_add_u64 v[202:203], v[202:203], 2, s[90:91]
	global_store_dwordx4 v[202:203], v[240:243], off
	v_sub_f32_e32 v203, v249, v218
	v_sub_f32_e32 v202, v248, v218
	v_sub_f32_e32 v221, v251, v218
	v_sub_f32_e32 v220, v250, v218
	v_pk_mul_f32 v[202:203], v[218:219], v[202:203] op_sel:[1,0]
	v_pk_mul_f32 v[220:221], v[218:219], v[220:221] op_sel:[1,0]
	v_pk_fma_f32 v[202:203], v[214:215], v[202:203], v[52:53]
	v_pk_fma_f32 v[220:221], v[212:213], v[220:221], v[54:55]
	v_pk_fma_f32 v[240:241], v[132:133], s[78:79], v[202:203] op_sel_hi:[1,0,1]
	v_add_u32_e32 v202, 0x8080, v194
	v_mov_b32_e32 v203, v159
	v_sub_f32_e32 v153, v153, v218
	v_sub_f32_e32 v152, v152, v218
	v_sub_f32_e32 v155, v155, v218
	v_sub_f32_e32 v154, v154, v218
	v_pk_fma_f32 v[242:243], v[134:135], s[78:79], v[220:221] op_sel_hi:[1,0,1]
	v_lshl_add_u64 v[202:203], v[202:203], 2, s[90:91]
	v_pk_mul_f32 v[154:155], v[218:219], v[154:155] op_sel:[1,0]
	v_pk_mul_f32 v[152:153], v[218:219], v[152:153] op_sel:[1,0]
	global_store_dwordx4 v[202:203], v[240:243], off
	v_pk_fma_f32 v[152:153], v[208:209], v[152:153], v[48:49]
	v_pk_fma_f32 v[154:155], v[206:207], v[154:155], v[50:51]
	v_add_u32_e32 v202, 0x8090, v194
	v_mov_b32_e32 v203, v159
	v_sub_f32_e32 v149, v149, v216
	v_sub_f32_e32 v148, v148, v216
	v_sub_f32_e32 v151, v151, v216
	v_sub_f32_e32 v150, v150, v216
	v_pk_fma_f32 v[154:155], v[130:131], s[78:79], v[154:155] op_sel_hi:[1,0,1]
	v_pk_fma_f32 v[152:153], v[128:129], s[78:79], v[152:153] op_sel_hi:[1,0,1]
	v_lshl_add_u64 v[202:203], v[202:203], 2, s[90:91]
	v_pk_mul_f32 v[150:151], v[216:217], v[150:151] op_sel:[1,0]
	v_pk_mul_f32 v[148:149], v[216:217], v[148:149] op_sel:[1,0]
	global_store_dwordx4 v[202:203], v[152:155], off
	v_pk_fma_f32 v[148:149], v[214:215], v[148:149], v[44:45]
	v_pk_fma_f32 v[150:151], v[212:213], v[150:151], v[46:47]
	v_add_u32_e32 v152, 0x10080, v194
	v_mov_b32_e32 v153, v159
	v_sub_f32_e32 v145, v145, v216
	v_sub_f32_e32 v144, v144, v216
	v_sub_f32_e32 v147, v147, v216
	v_sub_f32_e32 v146, v146, v216
	v_pk_fma_f32 v[150:151], v[134:135], s[78:79], v[150:151] op_sel_hi:[1,0,1]
	v_pk_fma_f32 v[148:149], v[132:133], s[78:79], v[148:149] op_sel_hi:[1,0,1]
	v_lshl_add_u64 v[152:153], v[152:153], 2, s[90:91]
	v_pk_mul_f32 v[146:147], v[216:217], v[146:147] op_sel:[1,0]
	v_pk_mul_f32 v[144:145], v[216:217], v[144:145] op_sel:[1,0]
	global_store_dwordx4 v[152:153], v[148:151], off
	v_pk_fma_f32 v[144:145], v[208:209], v[144:145], v[40:41]
	v_pk_fma_f32 v[146:147], v[206:207], v[146:147], v[42:43]
;     template <bool LN, int BJ, int LO, int HI> DI void batch(const f32x4 (&acc)[2][2][4][2], unsigned row0, unsigned col0, const f32x4 (&gv)[2], const f32x4 (&bv)[2]) const {
;         f32x4 r[HI - LO]; float mean[(HI - LO) / 2], rstd[(HI - LO) / 2];
; #pragma unroll
;         for (int i = LO; i < HI; ++i) { const int ai = i >> 3, m = (i >> 1) & 3, n = i & 1; const unsigned row = row0 + ai * HALF + m * 16;
;             if (n == 0) { mean[(i - LO) >> 1] = 0.f; rstd[(i - LO) >> 1] = 1.f;
;                 if (LN) { const float2 st = *(const float2*)(stats + row * 2u); mean[(i - LO) >> 1] = st.x; rstd[(i - LO) >> 1] = st.y; } }
;             r[i - LO] = *(const f32x4*)(src + (row * (unsigned)DM + col0 + BJ * HALF + n * 16)); }
; #pragma unroll
;         for (int i = LO; i < HI; ++i) { const int ai = i >> 3, m = (i >> 1) & 3, n = i & 1; const unsigned row = row0 + ai * HALF + m * 16;
;             *(f32x4*)(Y + (row * (unsigned)DM + col0 + BJ * HALF + n * 16)) = acc[ai][BJ][m][n] + ((r[i - LO] - mean[(i - LO) >> 1]) * rstd[(i - LO) >> 1]) * gv[n] + bv[n]; }
	v_add_u32_e32 v148, 0x10090, v194
	v_mov_b32_e32 v149, v159
	v_sub_f32_e32 v141, v141, v200
	v_sub_f32_e32 v140, v140, v200
	v_sub_f32_e32 v143, v143, v200
	v_sub_f32_e32 v142, v142, v200
	v_pk_fma_f32 v[146:147], v[130:131], s[78:79], v[146:147] op_sel_hi:[1,0,1]
	v_pk_fma_f32 v[144:145], v[128:129], s[78:79], v[144:145] op_sel_hi:[1,0,1]
	v_lshl_add_u64 v[148:149], v[148:149], 2, s[90:91]
	v_pk_mul_f32 v[142:143], v[200:201], v[142:143] op_sel:[1,0]
	v_pk_mul_f32 v[140:141], v[200:201], v[140:141] op_sel:[1,0]
	global_store_dwordx4 v[148:149], v[144:147], off
	v_pk_fma_f32 v[140:141], v[214:215], v[140:141], v[36:37]
	v_pk_fma_f32 v[142:143], v[212:213], v[142:143], v[38:39]
	v_add_u32_e32 v144, 0x18080, v194
	v_mov_b32_e32 v145, v159
	v_sub_f32_e32 v137, v137, v200
	v_sub_f32_e32 v136, v136, v200
	v_sub_f32_e32 v139, v139, v200
	v_sub_f32_e32 v138, v138, v200
	v_pk_fma_f32 v[142:143], v[134:135], s[78:79], v[142:143] op_sel_hi:[1,0,1]
	v_pk_fma_f32 v[140:141], v[132:133], s[78:79], v[140:141] op_sel_hi:[1,0,1]
	v_lshl_add_u64 v[144:145], v[144:145], 2, s[90:91]
	v_pk_mul_f32 v[138:139], v[200:201], v[138:139] op_sel:[1,0]
	v_pk_mul_f32 v[136:137], v[200:201], v[136:137] op_sel:[1,0]
	global_store_dwordx4 v[144:145], v[140:143], off
	v_pk_fma_f32 v[136:137], v[208:209], v[136:137], v[32:33]
	v_pk_fma_f32 v[138:139], v[206:207], v[138:139], v[34:35]
	v_add_u32_e32 v140, 0x18090, v194
	v_mov_b32_e32 v141, v159
	v_pk_fma_f32 v[138:139], v[130:131], s[78:79], v[138:139] op_sel_hi:[1,0,1]
	v_pk_fma_f32 v[136:137], v[128:129], s[78:79], v[136:137] op_sel_hi:[1,0,1]
	v_lshl_add_u64 v[140:141], v[140:141], 2, s[90:91]
	global_store_dwordx4 v[140:141], v[136:139], off
	s_nop 1
	v_add_u32_e32 v136, v233, v230
	v_mov_b32_e32 v137, v159
	v_lshl_add_u64 v[136:137], v[136:137], 2, s[88:89]
	global_load_dwordx2 v[220:221], v[196:197], off
	global_load_dwordx4 v[216:219], v[136:137], off
	v_add_u32_e32 v136, v233, v229
	v_mov_b32_e32 v137, v159
	v_lshl_add_u64 v[136:137], v[136:137], 2, s[88:89]
	global_load_dwordx4 v[240:243], v[136:137], off
	global_load_dwordx2 v[200:201], v[198:199], off
	v_add_u32_e32 v136, v234, v230
	v_mov_b32_e32 v137, v159
	v_lshl_add_u64 v[136:137], v[136:137], 2, s[88:89]
	global_load_dwordx4 v[244:247], v[136:137], off
	v_add_u32_e32 v136, v234, v229
	v_mov_b32_e32 v137, v159
	v_lshl_add_u64 v[136:137], v[136:137], 2, s[88:89]
	global_load_dwordx4 v[152:155], v[136:137], off
	global_load_dwordx2 v[198:199], v[204:205], off
	v_add_u32_e32 v136, v237, v230
	v_mov_b32_e32 v137, v159
	v_lshl_add_u64 v[136:137], v[136:137], 2, s[88:89]
	global_load_dwordx4 v[148:151], v[136:137], off
	v_add_u32_e32 v136, v237, v229
	v_mov_b32_e32 v137, v159
	v_lshl_add_u64 v[136:137], v[136:137], 2, s[88:89]
	global_load_dwordx4 v[144:147], v[136:137], off
	global_load_dwordx2 v[196:197], v[210:211], off
	v_add_u32_e32 v136, v238, v230
	v_mov_b32_e32 v137, v159
	v_lshl_add_u64 v[136:137], v[136:137], 2, s[88:89]
	global_load_dwordx4 v[140:143], v[136:137], off
	v_add_u32_e32 v136, v238, v229
	v_mov_b32_e32 v137, v159
	v_lshl_add_u64 v[136:137], v[136:137], 2, s[88:89]
	global_load_dwordx4 v[136:139], v[136:137], off
	v_add_u32_e32 v210, 0x40080, v194
	v_mov_b32_e32 v211, v159
	v_lshl_add_u64 v[210:211], v[210:211], 2, s[90:91]
	s_waitcnt vmcnt(0)
;     template <bool LN, int BJ, int LO, int HI> DI void batch(const f32x4 (&acc)[2][2][4][2], unsigned row0, unsigned col0, const f32x4 (&gv)[2], const f32x4 (&bv)[2]) const {
;         f32x4 r[HI - LO]; float mean[(HI - LO) / 2], rstd[(HI - LO) / 2];
; #pragma unroll
;         for (int i = LO; i < HI; ++i) { const int ai = i >> 3, m = (i >> 1) & 3, n = i & 1; const unsigned row = row0 + ai * HALF + m * 16;
;             if (n == 0) { mean[(i - LO) >> 1] = 0.f; rstd[(i - LO) >> 1] = 1.f;
;                 if (LN) { const float2 st = *(const float2*)(stats + row * 2u); mean[(i - LO) >> 1] = st.x; rstd[(i - LO) >> 1] = st.y; } }
;             r[i - LO] = *(const f32x4*)(src + (row * (unsigned)DM + col0 + BJ * HALF + n * 16)); }
; #pragma unroll
;         for (int i = LO; i < HI; ++i) { const int ai = i >> 3, m = (i >> 1) & 3, n = i & 1; const unsigned row = row0 + ai * HALF + m * 16;
;             *(f32x4*)(Y + (row * (unsigned)DM + col0 + BJ * HALF + n * 16)) = acc[ai][BJ][m][n] + ((r[i - LO] - mean[(i - LO) >> 1]) * rstd[(i - LO) >> 1]) * gv[n] + bv[n]; }
	v_sub_f32_e32 v203, v217, v220
	v_sub_f32_e32 v202, v216, v220
	v_sub_f32_e32 v205, v219, v220
	v_sub_f32_e32 v204, v218, v220
	v_pk_mul_f32 v[204:205], v[220:221], v[204:205] op_sel:[1,0]
	v_pk_mul_f32 v[202:203], v[220:221], v[202:203] op_sel:[1,0]
	v_pk_fma_f32 v[204:205], v[212:213], v[204:205], v[30:31]
	v_pk_fma_f32 v[202:203], v[214:215], v[202:203], v[28:29]
	v_pk_fma_f32 v[204:205], v[134:135], s[78:79], v[204:205] op_sel_hi:[1,0,1]
	v_pk_fma_f32 v[202:203], v[132:133], s[78:79], v[202:203] op_sel_hi:[1,0,1]
	global_store_dwordx4 v[210:211], v[202:205], off
	v_add_u32_e32 v210, 0x40090, v194
	v_mov_b32_e32 v211, v159
	v_sub_f32_e32 v203, v241, v220
	v_sub_f32_e32 v202, v240, v220
	v_sub_f32_e32 v205, v243, v220
	v_sub_f32_e32 v204, v242, v220
	v_pk_mul_f32 v[204:205], v[220:221], v[204:205] op_sel:[1,0]
	v_pk_mul_f32 v[202:203], v[220:221], v[202:203] op_sel:[1,0]
	v_pk_fma_f32 v[204:205], v[206:207], v[204:205], v[26:27]
	v_pk_fma_f32 v[202:203], v[208:209], v[202:203], v[24:25]
	v_pk_fma_f32 v[204:205], v[130:131], s[78:79], v[204:205] op_sel_hi:[1,0,1]
	v_pk_fma_f32 v[202:203], v[128:129], s[78:79], v[202:203] op_sel_hi:[1,0,1]
	v_lshl_add_u64 v[210:211], v[210:211], 2, s[90:91]
	global_store_dwordx4 v[210:211], v[202:205], off
	v_sub_f32_e32 v149, v149, v198
	v_sub_f32_e32 v148, v148, v198
	v_sub_f32_e32 v203, v245, v200
	v_sub_f32_e32 v202, v244, v200
	v_sub_f32_e32 v141, v141, v196
	v_sub_f32_e32 v140, v140, v196
	v_sub_f32_e32 v205, v247, v200
	v_sub_f32_e32 v204, v246, v200
	v_pk_mul_f32 v[202:203], v[200:201], v[202:203] op_sel:[1,0]
	v_sub_f32_e32 v151, v151, v198
	v_sub_f32_e32 v150, v150, v198
	v_pk_mul_f32 v[148:149], v[198:199], v[148:149] op_sel:[1,0]
	v_sub_f32_e32 v143, v143, v196
	v_sub_f32_e32 v142, v142, v196
	v_pk_mul_f32 v[140:141], v[196:197], v[140:141] op_sel:[1,0]
	v_pk_mul_f32 v[204:205], v[200:201], v[204:205] op_sel:[1,0]
	v_pk_fma_f32 v[202:203], v[214:215], v[202:203], v[20:21]
	v_sub_f32_e32 v153, v153, v200
	v_sub_f32_e32 v152, v152, v200
	v_sub_f32_e32 v155, v155, v200
	v_sub_f32_e32 v154, v154, v200
	v_pk_mul_f32 v[150:151], v[198:199], v[150:151] op_sel:[1,0]
	v_pk_fma_f32 v[148:149], v[214:215], v[148:149], v[12:13]
	v_pk_mul_f32 v[142:143], v[196:197], v[142:143] op_sel:[1,0]
	v_pk_fma_f32 v[140:141], v[214:215], v[140:141], v[4:5]
	v_pk_fma_f32 v[204:205], v[212:213], v[204:205], v[22:23]
	v_pk_fma_f32 v[202:203], v[132:133], s[78:79], v[202:203] op_sel_hi:[1,0,1]
	v_pk_mul_f32 v[154:155], v[200:201], v[154:155] op_sel:[1,0]
	v_pk_mul_f32 v[152:153], v[200:201], v[152:153] op_sel:[1,0]
	v_pk_fma_f32 v[150:151], v[212:213], v[150:151], v[14:15]
	v_pk_fma_f32 v[148:149], v[132:133], s[78:79], v[148:149] op_sel_hi:[1,0,1]
	v_pk_fma_f32 v[142:143], v[212:213], v[142:143], v[6:7]
	v_pk_fma_f32 v[132:133], v[132:133], s[78:79], v[140:141] op_sel_hi:[1,0,1]
	v_add_u32_e32 v140, 0x58080, v194
	v_mov_b32_e32 v141, v159
	v_pk_fma_f32 v[204:205], v[134:135], s[78:79], v[204:205] op_sel_hi:[1,0,1]
	v_pk_fma_f32 v[152:153], v[208:209], v[152:153], v[16:17]
	v_pk_fma_f32 v[154:155], v[206:207], v[154:155], v[18:19]
	v_add_u32_e32 v200, 0x48090, v194
	v_mov_b32_e32 v201, v159
	v_pk_fma_f32 v[150:151], v[134:135], s[78:79], v[150:151] op_sel_hi:[1,0,1]
	v_pk_fma_f32 v[134:135], v[134:135], s[78:79], v[142:143] op_sel_hi:[1,0,1]
	v_lshl_add_u64 v[140:141], v[140:141], 2, s[90:91]
	v_pk_fma_f32 v[154:155], v[130:131], s[78:79], v[154:155] op_sel_hi:[1,0,1]
	v_pk_fma_f32 v[152:153], v[128:129], s[78:79], v[152:153] op_sel_hi:[1,0,1]
	v_lshl_add_u64 v[200:201], v[200:201], 2, s[90:91]
	v_sub_f32_e32 v145, v145, v198
	v_sub_f32_e32 v144, v144, v198
	global_store_dwordx4 v[140:141], v[132:135], off
	global_store_dwordx4 v[200:201], v[152:155], off
	v_sub_f32_e32 v147, v147, v198
	v_sub_f32_e32 v133, v137, v196
	v_sub_f32_e32 v132, v136, v196
	v_add_u32_e32 v152, 0x50080, v194
	v_mov_b32_e32 v153, v159
	v_sub_f32_e32 v146, v146, v198
	v_pk_mul_f32 v[144:145], v[198:199], v[144:145] op_sel:[1,0]
	v_sub_f32_e32 v135, v139, v196
	v_sub_f32_e32 v134, v138, v196
	v_pk_mul_f32 v[132:133], v[196:197], v[132:133] op_sel:[1,0]
	v_lshl_add_u64 v[152:153], v[152:153], 2, s[90:91]
	v_pk_mul_f32 v[146:147], v[198:199], v[146:147] op_sel:[1,0]
	v_pk_fma_f32 v[144:145], v[208:209], v[144:145], v[8:9]
	v_pk_mul_f32 v[134:135], v[196:197], v[134:135] op_sel:[1,0]
	v_pk_fma_f32 v[132:133], v[208:209], v[132:133], v[0:1]
	v_add_u32_e32 v210, 0x48080, v194
	v_mov_b32_e32 v211, v159
	global_store_dwordx4 v[152:153], v[148:151], off
	v_pk_fma_f32 v[146:147], v[206:207], v[146:147], v[10:11]
	v_pk_fma_f32 v[144:145], v[128:129], s[78:79], v[144:145] op_sel_hi:[1,0,1]
	v_add_u32_e32 v148, 0x50090, v194
	v_mov_b32_e32 v149, v159
	v_pk_fma_f32 v[134:135], v[206:207], v[134:135], v[2:3]
	v_pk_fma_f32 v[128:129], v[128:129], s[78:79], v[132:133] op_sel_hi:[1,0,1]
	v_add_u32_e32 v132, 0x58090, v194
	v_mov_b32_e32 v133, v159
	v_lshl_add_u64 v[210:211], v[210:211], 2, s[90:91]
	v_pk_fma_f32 v[146:147], v[130:131], s[78:79], v[146:147] op_sel_hi:[1,0,1]
	v_lshl_add_u64 v[148:149], v[148:149], 2, s[90:91]
	v_pk_fma_f32 v[130:131], v[130:131], s[78:79], v[134:135] op_sel_hi:[1,0,1]
	v_lshl_add_u64 v[132:133], v[132:133], 2, s[90:91]
	global_store_dwordx4 v[210:211], v[202:205], off
	global_store_dwordx4 v[148:149], v[144:147], off
	global_store_dwordx4 v[132:133], v[128:131], off
	s_mov_b64 s[24:25], 0
	s_branch .LBB0_324
